# fp6 encode source loads system-scope nontemporal, one 8KB group in flight per wave; PEER gather alternates sweep direction per token
# speedup vs baseline: 1.1298x; 1.0160x over previous
; __global__ void __launch_bounds__(256, 2) fwd_megakernel(Params p) {
;     ...
;   if (bid < (nb >> 1)) {
;   for (size_t blk = (size_t)bid * 256 + tid; blk < (size_t)16384 * 64; blk += (size_t)nb * 256) {
; #pragma unroll
;     for (int tb = 0; tb < 2; ++tb) {
;       const float* src = (tb ? p.peer_up : p.peer_down) + blk * 32;
;       const float sc = tb ? UP_SCALE : DOWN_SCALE;
;       v16f va, vb;
; #pragma unroll
;       for (int q = 0; q < 4; ++q) {
;         const float4 x = *(const float4*)(src + q * 8), y = *(const float4*)(src + q * 8 + 4);
;         va[q * 4] = x.x * sc; vb[q * 4] = x.y * sc; va[q * 4 + 1] = x.z * sc; vb[q * 4 + 1] = x.w * sc;
;         va[q * 4 + 2] = y.x * sc; vb[q * 4 + 2] = y.y * sc; va[q * 4 + 3] = y.z * sc; vb[q * 4 + 3] = y.w * sc;
;       }
;       const v6u o = __builtin_amdgcn_cvt_scalef32_2xpk16_fp6_f32(va, vb, 1.0f);
;       unsigned char* dst = (tb ? p.up8 : p.down8) + blk * 24;
;       *(u32x2*)dst = u32x2{o[0], o[1]}; *(u32x2*)(dst + 8) = u32x2{o[2], o[3]}; *(u32x2*)(dst + 16) = u32x2{o[4], o[5]};
;     }
;   }
.LBB0_1436:
	s_or_b64 exec, exec, s[0:1]
	s_ashr_i32 s0, s92, 1
	v_mov_b32_e32 v34, v0
	s_cmp_ge_i32 s94, s0
	s_waitcnt lgkmcnt(0)
	s_barrier
	s_cselect_b64 s[72:73], -1, 0
	s_cmp_lt_i32 s94, s0
	v_ashrrev_i32_e32 v35, 31, v34
	s_cbranch_scc0 .LBB0_1441
	s_mov_b64 exec, -1
	v_lshrrev_b32_e32 v54, 6, v0
	v_and_b32_e32 v55, 63, v0
	v_lshlrev_b32_e32 v52, 13, v54
	v_lshl_or_b32 v52, v55, 4, v52
	v_mul_u32_u24_e32 v53, 0xc00, v54
	v_lshl_or_b32 v53, v55, 4, v53
	v_add_u32_e32 v54, 0x1000, v52
	s_lshl_b32 s10, s94, 8
	s_lshl_b32 s11, s92, 8
	s_lshl_b32 s12, s92, 15
	s_mul_i32 s13, s92, 0x3000
	s_mov_b32 s16, 0x42800000
	s_lshl_b32 s0, s94, 15
	s_add_u32 s2, s40, s0
	s_addc_u32 s3, s41, 0
	s_add_u32 s4, s42, s0
	s_addc_u32 s5, s43, 0
	s_mul_i32 s0, s94, 0x3000
	s_add_u32 s6, s62, s0
	s_addc_u32 s7, s63, 0
	s_cmp_lt_u32 s10, 0x100000
	s_cbranch_scc0 .Lenc_end_a
	s_cmpk_lg_u32 s92, 0x200
	s_cbranch_scc1 .Lenc_generic_a
	global_load_dwordx4 v[56:59], v52, s[2:3] sc0 sc1 nt
	global_load_dwordx4 v[60:63], v52, s[2:3] offset:1024 sc0 sc1 nt
	global_load_dwordx4 v[64:67], v52, s[2:3] offset:2048 sc0 sc1 nt
	global_load_dwordx4 v[68:71], v52, s[2:3] offset:3072 sc0 sc1 nt
	global_load_dwordx4 v[72:75], v54, s[2:3] sc0 sc1 nt
	global_load_dwordx4 v[76:79], v54, s[2:3] offset:1024 sc0 sc1 nt
	global_load_dwordx4 v[80:83], v54, s[2:3] offset:2048 sc0 sc1 nt
	global_load_dwordx4 v[84:87], v54, s[2:3] offset:3072 sc0 sc1 nt
	s_waitcnt vmcnt(0)
	v_mul_f32_e32 v2, s16, v56
	v_mul_f32_e32 v3, s16, v58
	v_mul_f32_e32 v4, s16, v60
	v_mul_f32_e32 v5, s16, v62
	v_mul_f32_e32 v6, s16, v64
	v_mul_f32_e32 v7, s16, v66
	v_mul_f32_e32 v8, s16, v68
	v_mul_f32_e32 v9, s16, v70
	v_mul_f32_e32 v10, s16, v72
	v_mul_f32_e32 v11, s16, v74
	v_mul_f32_e32 v12, s16, v76
	v_mul_f32_e32 v13, s16, v78
	v_mul_f32_e32 v14, s16, v80
	v_mul_f32_e32 v15, s16, v82
	v_mul_f32_e32 v16, s16, v84
	v_mul_f32_e32 v17, s16, v86
	v_mul_f32_e32 v18, s16, v57
	v_mul_f32_e32 v19, s16, v59
	v_mul_f32_e32 v20, s16, v61
	v_mul_f32_e32 v21, s16, v63
	v_mul_f32_e32 v22, s16, v65
	v_mul_f32_e32 v23, s16, v67
	v_mul_f32_e32 v24, s16, v69
	v_mul_f32_e32 v25, s16, v71
	v_mul_f32_e32 v26, s16, v73
	v_mul_f32_e32 v27, s16, v75
	v_mul_f32_e32 v28, s16, v77
	v_mul_f32_e32 v29, s16, v79
	v_mul_f32_e32 v30, s16, v81
	v_mul_f32_e32 v31, s16, v83
	v_mul_f32_e32 v32, s16, v85
	v_mul_f32_e32 v33, s16, v87
	s_nop 0
	v_cvt_scalef32_2xpk16_fp6_f32 v[40:45], v[2:17], v[18:33], 1.0
	global_load_dwordx4 v[56:59], v52, s[4:5] sc0 sc1 nt
	global_load_dwordx4 v[60:63], v52, s[4:5] offset:1024 sc0 sc1 nt
	global_load_dwordx4 v[64:67], v52, s[4:5] offset:2048 sc0 sc1 nt
	global_load_dwordx4 v[68:71], v52, s[4:5] offset:3072 sc0 sc1 nt
	global_load_dwordx4 v[72:75], v54, s[4:5] sc0 sc1 nt
	global_load_dwordx4 v[76:79], v54, s[4:5] offset:1024 sc0 sc1 nt
	global_load_dwordx4 v[80:83], v54, s[4:5] offset:2048 sc0 sc1 nt
	global_load_dwordx4 v[84:87], v54, s[4:5] offset:3072 sc0 sc1 nt
	s_add_u32 s2, s2, s12
	s_addc_u32 s3, s3, 0
	s_add_u32 s4, s4, s12
	s_addc_u32 s5, s5, 0
	s_waitcnt vmcnt(0)
	v_mul_f32_e32 v2, 4.0, v56
	v_mul_f32_e32 v3, 4.0, v58
	v_mul_f32_e32 v4, 4.0, v60
	v_mul_f32_e32 v5, 4.0, v62
	v_mul_f32_e32 v6, 4.0, v64
	v_mul_f32_e32 v7, 4.0, v66
	v_mul_f32_e32 v8, 4.0, v68
	v_mul_f32_e32 v9, 4.0, v70
	v_mul_f32_e32 v10, 4.0, v72
	v_mul_f32_e32 v11, 4.0, v74
	v_mul_f32_e32 v12, 4.0, v76
	v_mul_f32_e32 v13, 4.0, v78
	v_mul_f32_e32 v14, 4.0, v80
	v_mul_f32_e32 v15, 4.0, v82
	v_mul_f32_e32 v16, 4.0, v84
	v_mul_f32_e32 v17, 4.0, v86
	v_mul_f32_e32 v18, 4.0, v57
	v_mul_f32_e32 v19, 4.0, v59
	v_mul_f32_e32 v20, 4.0, v61
	v_mul_f32_e32 v21, 4.0, v63
	v_mul_f32_e32 v22, 4.0, v65
	v_mul_f32_e32 v23, 4.0, v67
	v_mul_f32_e32 v24, 4.0, v69
	v_mul_f32_e32 v25, 4.0, v71
	v_mul_f32_e32 v26, 4.0, v73
	v_mul_f32_e32 v27, 4.0, v75
	v_mul_f32_e32 v28, 4.0, v77
	v_mul_f32_e32 v29, 4.0, v79
	v_mul_f32_e32 v30, 4.0, v81
	v_mul_f32_e32 v31, 4.0, v83
	v_mul_f32_e32 v32, 4.0, v85
	v_mul_f32_e32 v33, 4.0, v87
	s_nop 0
	v_cvt_scalef32_2xpk16_fp6_f32 v[46:51], v[2:17], v[18:33], 1.0
	global_store_dwordx4 v53, v[40:43], s[6:7]
	global_store_dwordx4 v53, v[48:51], s[6:7] offset:1024
	global_store_dwordx4 v53, v[44:47], s[6:7] offset:2048
	s_add_u32 s6, s6, s13
	s_addc_u32 s7, s7, 0
	global_load_dwordx4 v[56:59], v52, s[2:3] sc0 sc1 nt
	global_load_dwordx4 v[60:63], v52, s[2:3] offset:1024 sc0 sc1 nt
	global_load_dwordx4 v[64:67], v52, s[2:3] offset:2048 sc0 sc1 nt
	global_load_dwordx4 v[68:71], v52, s[2:3] offset:3072 sc0 sc1 nt
	global_load_dwordx4 v[72:75], v54, s[2:3] sc0 sc1 nt
	global_load_dwordx4 v[76:79], v54, s[2:3] offset:1024 sc0 sc1 nt
	global_load_dwordx4 v[80:83], v54, s[2:3] offset:2048 sc0 sc1 nt
	global_load_dwordx4 v[84:87], v54, s[2:3] offset:3072 sc0 sc1 nt
	s_waitcnt vmcnt(0)
	v_mul_f32_e32 v2, s16, v56
	v_mul_f32_e32 v3, s16, v58
	v_mul_f32_e32 v4, s16, v60
	v_mul_f32_e32 v5, s16, v62
	v_mul_f32_e32 v6, s16, v64
	v_mul_f32_e32 v7, s16, v66
	v_mul_f32_e32 v8, s16, v68
	v_mul_f32_e32 v9, s16, v70
	v_mul_f32_e32 v10, s16, v72
	v_mul_f32_e32 v11, s16, v74
	v_mul_f32_e32 v12, s16, v76
	v_mul_f32_e32 v13, s16, v78
	v_mul_f32_e32 v14, s16, v80
	v_mul_f32_e32 v15, s16, v82
	v_mul_f32_e32 v16, s16, v84
	v_mul_f32_e32 v17, s16, v86
	v_mul_f32_e32 v18, s16, v57
	v_mul_f32_e32 v19, s16, v59
	v_mul_f32_e32 v20, s16, v61
	v_mul_f32_e32 v21, s16, v63
	v_mul_f32_e32 v22, s16, v65
	v_mul_f32_e32 v23, s16, v67
	v_mul_f32_e32 v24, s16, v69
	v_mul_f32_e32 v25, s16, v71
	v_mul_f32_e32 v26, s16, v73
	v_mul_f32_e32 v27, s16, v75
	v_mul_f32_e32 v28, s16, v77
	v_mul_f32_e32 v29, s16, v79
	v_mul_f32_e32 v30, s16, v81
	v_mul_f32_e32 v31, s16, v83
	v_mul_f32_e32 v32, s16, v85
	v_mul_f32_e32 v33, s16, v87
	s_nop 0
	v_cvt_scalef32_2xpk16_fp6_f32 v[40:45], v[2:17], v[18:33], 1.0
	global_load_dwordx4 v[56:59], v52, s[4:5] sc0 sc1 nt
	global_load_dwordx4 v[60:63], v52, s[4:5] offset:1024 sc0 sc1 nt
	global_load_dwordx4 v[64:67], v52, s[4:5] offset:2048 sc0 sc1 nt
	global_load_dwordx4 v[68:71], v52, s[4:5] offset:3072 sc0 sc1 nt
	global_load_dwordx4 v[72:75], v54, s[4:5] sc0 sc1 nt
	global_load_dwordx4 v[76:79], v54, s[4:5] offset:1024 sc0 sc1 nt
	global_load_dwordx4 v[80:83], v54, s[4:5] offset:2048 sc0 sc1 nt
	global_load_dwordx4 v[84:87], v54, s[4:5] offset:3072 sc0 sc1 nt
	s_add_u32 s2, s2, s12
	s_addc_u32 s3, s3, 0
	s_add_u32 s4, s4, s12
	s_addc_u32 s5, s5, 0
	s_waitcnt vmcnt(0)
; __global__ void __launch_bounds__(256, 2) fwd_megakernel(Params p) {
;     ...
;   for (size_t blk = (size_t)bid * 256 + tid; blk < (size_t)16384 * 64; blk += (size_t)nb * 256) {
; #pragma unroll
;     for (int tb = 0; tb < 2; ++tb) {
;       const float* src = (tb ? p.peer_up : p.peer_down) + blk * 32;
;       const float sc = tb ? UP_SCALE : DOWN_SCALE;
;       v16f va, vb;
; #pragma unroll
;       for (int q = 0; q < 4; ++q) {
;         const float4 x = *(const float4*)(src + q * 8), y = *(const float4*)(src + q * 8 + 4);
;         va[q * 4] = x.x * sc; vb[q * 4] = x.y * sc; va[q * 4 + 1] = x.z * sc; vb[q * 4 + 1] = x.w * sc;
;         va[q * 4 + 2] = y.x * sc; vb[q * 4 + 2] = y.y * sc; va[q * 4 + 3] = y.z * sc; vb[q * 4 + 3] = y.w * sc;
;       }
;       const v6u o = __builtin_amdgcn_cvt_scalef32_2xpk16_fp6_f32(va, vb, 1.0f);
;       unsigned char* dst = (tb ? p.up8 : p.down8) + blk * 24;
;       *(u32x2*)dst = u32x2{o[0], o[1]}; *(u32x2*)(dst + 8) = u32x2{o[2], o[3]}; *(u32x2*)(dst + 16) = u32x2{o[4], o[5]};
;     }
	v_mul_f32_e32 v2, 4.0, v56
	v_mul_f32_e32 v3, 4.0, v58
	v_mul_f32_e32 v4, 4.0, v60
	v_mul_f32_e32 v5, 4.0, v62
	v_mul_f32_e32 v6, 4.0, v64
	v_mul_f32_e32 v7, 4.0, v66
	v_mul_f32_e32 v8, 4.0, v68
	v_mul_f32_e32 v9, 4.0, v70
	v_mul_f32_e32 v10, 4.0, v72
	v_mul_f32_e32 v11, 4.0, v74
	v_mul_f32_e32 v12, 4.0, v76
	v_mul_f32_e32 v13, 4.0, v78
	v_mul_f32_e32 v14, 4.0, v80
	v_mul_f32_e32 v15, 4.0, v82
	v_mul_f32_e32 v16, 4.0, v84
	v_mul_f32_e32 v17, 4.0, v86
	v_mul_f32_e32 v18, 4.0, v57
	v_mul_f32_e32 v19, 4.0, v59
	v_mul_f32_e32 v20, 4.0, v61
	v_mul_f32_e32 v21, 4.0, v63
	v_mul_f32_e32 v22, 4.0, v65
	v_mul_f32_e32 v23, 4.0, v67
	v_mul_f32_e32 v24, 4.0, v69
	v_mul_f32_e32 v25, 4.0, v71
	v_mul_f32_e32 v26, 4.0, v73
	v_mul_f32_e32 v27, 4.0, v75
	v_mul_f32_e32 v28, 4.0, v77
	v_mul_f32_e32 v29, 4.0, v79
	v_mul_f32_e32 v30, 4.0, v81
	v_mul_f32_e32 v31, 4.0, v83
	v_mul_f32_e32 v32, 4.0, v85
	v_mul_f32_e32 v33, 4.0, v87
	s_nop 0
	v_cvt_scalef32_2xpk16_fp6_f32 v[46:51], v[2:17], v[18:33], 1.0
	global_store_dwordx4 v53, v[40:43], s[6:7]
	global_store_dwordx4 v53, v[48:51], s[6:7] offset:1024
	global_store_dwordx4 v53, v[44:47], s[6:7] offset:2048
	s_add_u32 s6, s6, s13
	s_addc_u32 s7, s7, 0
	global_load_dwordx4 v[56:59], v52, s[2:3] sc0 sc1 nt
	global_load_dwordx4 v[60:63], v52, s[2:3] offset:1024 sc0 sc1 nt
	global_load_dwordx4 v[64:67], v52, s[2:3] offset:2048 sc0 sc1 nt
	global_load_dwordx4 v[68:71], v52, s[2:3] offset:3072 sc0 sc1 nt
	global_load_dwordx4 v[72:75], v54, s[2:3] sc0 sc1 nt
	global_load_dwordx4 v[76:79], v54, s[2:3] offset:1024 sc0 sc1 nt
	global_load_dwordx4 v[80:83], v54, s[2:3] offset:2048 sc0 sc1 nt
	global_load_dwordx4 v[84:87], v54, s[2:3] offset:3072 sc0 sc1 nt
	s_waitcnt vmcnt(0)
	v_mul_f32_e32 v2, s16, v56
	v_mul_f32_e32 v3, s16, v58
	v_mul_f32_e32 v4, s16, v60
	v_mul_f32_e32 v5, s16, v62
	v_mul_f32_e32 v6, s16, v64
	v_mul_f32_e32 v7, s16, v66
	v_mul_f32_e32 v8, s16, v68
	v_mul_f32_e32 v9, s16, v70
	v_mul_f32_e32 v10, s16, v72
	v_mul_f32_e32 v11, s16, v74
	v_mul_f32_e32 v12, s16, v76
	v_mul_f32_e32 v13, s16, v78
	v_mul_f32_e32 v14, s16, v80
	v_mul_f32_e32 v15, s16, v82
	v_mul_f32_e32 v16, s16, v84
	v_mul_f32_e32 v17, s16, v86
	v_mul_f32_e32 v18, s16, v57
	v_mul_f32_e32 v19, s16, v59
	v_mul_f32_e32 v20, s16, v61
	v_mul_f32_e32 v21, s16, v63
	v_mul_f32_e32 v22, s16, v65
	v_mul_f32_e32 v23, s16, v67
	v_mul_f32_e32 v24, s16, v69
	v_mul_f32_e32 v25, s16, v71
	v_mul_f32_e32 v26, s16, v73
	v_mul_f32_e32 v27, s16, v75
	v_mul_f32_e32 v28, s16, v77
	v_mul_f32_e32 v29, s16, v79
	v_mul_f32_e32 v30, s16, v81
	v_mul_f32_e32 v31, s16, v83
	v_mul_f32_e32 v32, s16, v85
	v_mul_f32_e32 v33, s16, v87
	s_nop 0
	v_cvt_scalef32_2xpk16_fp6_f32 v[40:45], v[2:17], v[18:33], 1.0
	global_load_dwordx4 v[56:59], v52, s[4:5] sc0 sc1 nt
	global_load_dwordx4 v[60:63], v52, s[4:5] offset:1024 sc0 sc1 nt
	global_load_dwordx4 v[64:67], v52, s[4:5] offset:2048 sc0 sc1 nt
	global_load_dwordx4 v[68:71], v52, s[4:5] offset:3072 sc0 sc1 nt
	global_load_dwordx4 v[72:75], v54, s[4:5] sc0 sc1 nt
	global_load_dwordx4 v[76:79], v54, s[4:5] offset:1024 sc0 sc1 nt
	global_load_dwordx4 v[80:83], v54, s[4:5] offset:2048 sc0 sc1 nt
	global_load_dwordx4 v[84:87], v54, s[4:5] offset:3072 sc0 sc1 nt
	s_add_u32 s2, s2, s12
	s_addc_u32 s3, s3, 0
	s_add_u32 s4, s4, s12
	s_addc_u32 s5, s5, 0
	s_waitcnt vmcnt(0)
	v_mul_f32_e32 v2, 4.0, v56
	v_mul_f32_e32 v3, 4.0, v58
	v_mul_f32_e32 v4, 4.0, v60
	v_mul_f32_e32 v5, 4.0, v62
	v_mul_f32_e32 v6, 4.0, v64
	v_mul_f32_e32 v7, 4.0, v66
	v_mul_f32_e32 v8, 4.0, v68
	v_mul_f32_e32 v9, 4.0, v70
	v_mul_f32_e32 v10, 4.0, v72
	v_mul_f32_e32 v11, 4.0, v74
	v_mul_f32_e32 v12, 4.0, v76
	v_mul_f32_e32 v13, 4.0, v78
	v_mul_f32_e32 v14, 4.0, v80
	v_mul_f32_e32 v15, 4.0, v82
	v_mul_f32_e32 v16, 4.0, v84
	v_mul_f32_e32 v17, 4.0, v86
	v_mul_f32_e32 v18, 4.0, v57
	v_mul_f32_e32 v19, 4.0, v59
	v_mul_f32_e32 v20, 4.0, v61
	v_mul_f32_e32 v21, 4.0, v63
	v_mul_f32_e32 v22, 4.0, v65
	v_mul_f32_e32 v23, 4.0, v67
	v_mul_f32_e32 v24, 4.0, v69
	v_mul_f32_e32 v25, 4.0, v71
	v_mul_f32_e32 v26, 4.0, v73
	v_mul_f32_e32 v27, 4.0, v75
	v_mul_f32_e32 v28, 4.0, v77
	v_mul_f32_e32 v29, 4.0, v79
	v_mul_f32_e32 v30, 4.0, v81
	v_mul_f32_e32 v31, 4.0, v83
	v_mul_f32_e32 v32, 4.0, v85
	v_mul_f32_e32 v33, 4.0, v87
	s_nop 0
	v_cvt_scalef32_2xpk16_fp6_f32 v[46:51], v[2:17], v[18:33], 1.0
	global_store_dwordx4 v53, v[40:43], s[6:7]
	global_store_dwordx4 v53, v[48:51], s[6:7] offset:1024
	global_store_dwordx4 v53, v[44:47], s[6:7] offset:2048
	s_add_u32 s6, s6, s13
	s_addc_u32 s7, s7, 0
	global_load_dwordx4 v[56:59], v52, s[2:3] sc0 sc1 nt
	global_load_dwordx4 v[60:63], v52, s[2:3] offset:1024 sc0 sc1 nt
	global_load_dwordx4 v[64:67], v52, s[2:3] offset:2048 sc0 sc1 nt
	global_load_dwordx4 v[68:71], v52, s[2:3] offset:3072 sc0 sc1 nt
	global_load_dwordx4 v[72:75], v54, s[2:3] sc0 sc1 nt
	global_load_dwordx4 v[76:79], v54, s[2:3] offset:1024 sc0 sc1 nt
	global_load_dwordx4 v[80:83], v54, s[2:3] offset:2048 sc0 sc1 nt
	global_load_dwordx4 v[84:87], v54, s[2:3] offset:3072 sc0 sc1 nt
	s_waitcnt vmcnt(0)
; __global__ void __launch_bounds__(256, 2) fwd_megakernel(Params p) {
;     ...
;   for (size_t blk = (size_t)bid * 256 + tid; blk < (size_t)16384 * 64; blk += (size_t)nb * 256) {
; #pragma unroll
;     for (int tb = 0; tb < 2; ++tb) {
;       const float* src = (tb ? p.peer_up : p.peer_down) + blk * 32;
;       const float sc = tb ? UP_SCALE : DOWN_SCALE;
;       v16f va, vb;
; #pragma unroll
;       for (int q = 0; q < 4; ++q) {
;         const float4 x = *(const float4*)(src + q * 8), y = *(const float4*)(src + q * 8 + 4);
;         va[q * 4] = x.x * sc; vb[q * 4] = x.y * sc; va[q * 4 + 1] = x.z * sc; vb[q * 4 + 1] = x.w * sc;
;         va[q * 4 + 2] = y.x * sc; vb[q * 4 + 2] = y.y * sc; va[q * 4 + 3] = y.z * sc; vb[q * 4 + 3] = y.w * sc;
;       }
;       const v6u o = __builtin_amdgcn_cvt_scalef32_2xpk16_fp6_f32(va, vb, 1.0f);
;       unsigned char* dst = (tb ? p.up8 : p.down8) + blk * 24;
;       *(u32x2*)dst = u32x2{o[0], o[1]}; *(u32x2*)(dst + 8) = u32x2{o[2], o[3]}; *(u32x2*)(dst + 16) = u32x2{o[4], o[5]};
;     }
	v_mul_f32_e32 v2, s16, v56
	v_mul_f32_e32 v3, s16, v58
	v_mul_f32_e32 v4, s16, v60
	v_mul_f32_e32 v5, s16, v62
	v_mul_f32_e32 v6, s16, v64
	v_mul_f32_e32 v7, s16, v66
	v_mul_f32_e32 v8, s16, v68
	v_mul_f32_e32 v9, s16, v70
	v_mul_f32_e32 v10, s16, v72
	v_mul_f32_e32 v11, s16, v74
	v_mul_f32_e32 v12, s16, v76
	v_mul_f32_e32 v13, s16, v78
	v_mul_f32_e32 v14, s16, v80
	v_mul_f32_e32 v15, s16, v82
	v_mul_f32_e32 v16, s16, v84
	v_mul_f32_e32 v17, s16, v86
	v_mul_f32_e32 v18, s16, v57
	v_mul_f32_e32 v19, s16, v59
	v_mul_f32_e32 v20, s16, v61
	v_mul_f32_e32 v21, s16, v63
	v_mul_f32_e32 v22, s16, v65
	v_mul_f32_e32 v23, s16, v67
	v_mul_f32_e32 v24, s16, v69
	v_mul_f32_e32 v25, s16, v71
	v_mul_f32_e32 v26, s16, v73
	v_mul_f32_e32 v27, s16, v75
	v_mul_f32_e32 v28, s16, v77
	v_mul_f32_e32 v29, s16, v79
	v_mul_f32_e32 v30, s16, v81
	v_mul_f32_e32 v31, s16, v83
	v_mul_f32_e32 v32, s16, v85
	v_mul_f32_e32 v33, s16, v87
	s_nop 0
	v_cvt_scalef32_2xpk16_fp6_f32 v[40:45], v[2:17], v[18:33], 1.0
	global_load_dwordx4 v[56:59], v52, s[4:5] sc0 sc1 nt
	global_load_dwordx4 v[60:63], v52, s[4:5] offset:1024 sc0 sc1 nt
	global_load_dwordx4 v[64:67], v52, s[4:5] offset:2048 sc0 sc1 nt
	global_load_dwordx4 v[68:71], v52, s[4:5] offset:3072 sc0 sc1 nt
	global_load_dwordx4 v[72:75], v54, s[4:5] sc0 sc1 nt
	global_load_dwordx4 v[76:79], v54, s[4:5] offset:1024 sc0 sc1 nt
	global_load_dwordx4 v[80:83], v54, s[4:5] offset:2048 sc0 sc1 nt
	global_load_dwordx4 v[84:87], v54, s[4:5] offset:3072 sc0 sc1 nt
	s_add_u32 s2, s2, s12
	s_addc_u32 s3, s3, 0
	s_add_u32 s4, s4, s12
	s_addc_u32 s5, s5, 0
	s_waitcnt vmcnt(0)
	v_mul_f32_e32 v2, 4.0, v56
	v_mul_f32_e32 v3, 4.0, v58
	v_mul_f32_e32 v4, 4.0, v60
	v_mul_f32_e32 v5, 4.0, v62
	v_mul_f32_e32 v6, 4.0, v64
	v_mul_f32_e32 v7, 4.0, v66
	v_mul_f32_e32 v8, 4.0, v68
	v_mul_f32_e32 v9, 4.0, v70
	v_mul_f32_e32 v10, 4.0, v72
	v_mul_f32_e32 v11, 4.0, v74
	v_mul_f32_e32 v12, 4.0, v76
	v_mul_f32_e32 v13, 4.0, v78
	v_mul_f32_e32 v14, 4.0, v80
	v_mul_f32_e32 v15, 4.0, v82
	v_mul_f32_e32 v16, 4.0, v84
	v_mul_f32_e32 v17, 4.0, v86
	v_mul_f32_e32 v18, 4.0, v57
	v_mul_f32_e32 v19, 4.0, v59
	v_mul_f32_e32 v20, 4.0, v61
	v_mul_f32_e32 v21, 4.0, v63
	v_mul_f32_e32 v22, 4.0, v65
	v_mul_f32_e32 v23, 4.0, v67
	v_mul_f32_e32 v24, 4.0, v69
	v_mul_f32_e32 v25, 4.0, v71
	v_mul_f32_e32 v26, 4.0, v73
	v_mul_f32_e32 v27, 4.0, v75
	v_mul_f32_e32 v28, 4.0, v77
	v_mul_f32_e32 v29, 4.0, v79
	v_mul_f32_e32 v30, 4.0, v81
	v_mul_f32_e32 v31, 4.0, v83
	v_mul_f32_e32 v32, 4.0, v85
	v_mul_f32_e32 v33, 4.0, v87
	s_nop 0
	v_cvt_scalef32_2xpk16_fp6_f32 v[46:51], v[2:17], v[18:33], 1.0
	global_store_dwordx4 v53, v[40:43], s[6:7]
	global_store_dwordx4 v53, v[48:51], s[6:7] offset:1024
	global_store_dwordx4 v53, v[44:47], s[6:7] offset:2048
	s_add_u32 s6, s6, s13
	s_addc_u32 s7, s7, 0
	global_load_dwordx4 v[56:59], v52, s[2:3] sc0 sc1 nt
	global_load_dwordx4 v[60:63], v52, s[2:3] offset:1024 sc0 sc1 nt
	global_load_dwordx4 v[64:67], v52, s[2:3] offset:2048 sc0 sc1 nt
	global_load_dwordx4 v[68:71], v52, s[2:3] offset:3072 sc0 sc1 nt
	global_load_dwordx4 v[72:75], v54, s[2:3] sc0 sc1 nt
	global_load_dwordx4 v[76:79], v54, s[2:3] offset:1024 sc0 sc1 nt
	global_load_dwordx4 v[80:83], v54, s[2:3] offset:2048 sc0 sc1 nt
	global_load_dwordx4 v[84:87], v54, s[2:3] offset:3072 sc0 sc1 nt
	s_waitcnt vmcnt(0)
	v_mul_f32_e32 v2, s16, v56
	v_mul_f32_e32 v3, s16, v58
	v_mul_f32_e32 v4, s16, v60
	v_mul_f32_e32 v5, s16, v62
	v_mul_f32_e32 v6, s16, v64
	v_mul_f32_e32 v7, s16, v66
	v_mul_f32_e32 v8, s16, v68
	v_mul_f32_e32 v9, s16, v70
	v_mul_f32_e32 v10, s16, v72
	v_mul_f32_e32 v11, s16, v74
	v_mul_f32_e32 v12, s16, v76
	v_mul_f32_e32 v13, s16, v78
	v_mul_f32_e32 v14, s16, v80
	v_mul_f32_e32 v15, s16, v82
	v_mul_f32_e32 v16, s16, v84
	v_mul_f32_e32 v17, s16, v86
	v_mul_f32_e32 v18, s16, v57
	v_mul_f32_e32 v19, s16, v59
	v_mul_f32_e32 v20, s16, v61
	v_mul_f32_e32 v21, s16, v63
	v_mul_f32_e32 v22, s16, v65
	v_mul_f32_e32 v23, s16, v67
	v_mul_f32_e32 v24, s16, v69
	v_mul_f32_e32 v25, s16, v71
	v_mul_f32_e32 v26, s16, v73
	v_mul_f32_e32 v27, s16, v75
	v_mul_f32_e32 v28, s16, v77
	v_mul_f32_e32 v29, s16, v79
	v_mul_f32_e32 v30, s16, v81
	v_mul_f32_e32 v31, s16, v83
	v_mul_f32_e32 v32, s16, v85
	v_mul_f32_e32 v33, s16, v87
	s_nop 0
	v_cvt_scalef32_2xpk16_fp6_f32 v[40:45], v[2:17], v[18:33], 1.0
	global_load_dwordx4 v[56:59], v52, s[4:5] sc0 sc1 nt
	global_load_dwordx4 v[60:63], v52, s[4:5] offset:1024 sc0 sc1 nt
	global_load_dwordx4 v[64:67], v52, s[4:5] offset:2048 sc0 sc1 nt
	global_load_dwordx4 v[68:71], v52, s[4:5] offset:3072 sc0 sc1 nt
	global_load_dwordx4 v[72:75], v54, s[4:5] sc0 sc1 nt
	global_load_dwordx4 v[76:79], v54, s[4:5] offset:1024 sc0 sc1 nt
	global_load_dwordx4 v[80:83], v54, s[4:5] offset:2048 sc0 sc1 nt
	global_load_dwordx4 v[84:87], v54, s[4:5] offset:3072 sc0 sc1 nt
	s_add_u32 s2, s2, s12
	s_addc_u32 s3, s3, 0
	s_add_u32 s4, s4, s12
	s_addc_u32 s5, s5, 0
	s_waitcnt vmcnt(0)
; __global__ void __launch_bounds__(256, 2) fwd_megakernel(Params p) {
;     ...
;   for (size_t blk = (size_t)bid * 256 + tid; blk < (size_t)16384 * 64; blk += (size_t)nb * 256) {
; #pragma unroll
;     for (int tb = 0; tb < 2; ++tb) {
;       const float* src = (tb ? p.peer_up : p.peer_down) + blk * 32;
;       const float sc = tb ? UP_SCALE : DOWN_SCALE;
;       v16f va, vb;
; #pragma unroll
;       for (int q = 0; q < 4; ++q) {
;         const float4 x = *(const float4*)(src + q * 8), y = *(const float4*)(src + q * 8 + 4);
;         va[q * 4] = x.x * sc; vb[q * 4] = x.y * sc; va[q * 4 + 1] = x.z * sc; vb[q * 4 + 1] = x.w * sc;
;         va[q * 4 + 2] = y.x * sc; vb[q * 4 + 2] = y.y * sc; va[q * 4 + 3] = y.z * sc; vb[q * 4 + 3] = y.w * sc;
;       }
;       const v6u o = __builtin_amdgcn_cvt_scalef32_2xpk16_fp6_f32(va, vb, 1.0f);
;       unsigned char* dst = (tb ? p.up8 : p.down8) + blk * 24;
;       *(u32x2*)dst = u32x2{o[0], o[1]}; *(u32x2*)(dst + 8) = u32x2{o[2], o[3]}; *(u32x2*)(dst + 16) = u32x2{o[4], o[5]};
;     }
	v_mul_f32_e32 v2, 4.0, v56
	v_mul_f32_e32 v3, 4.0, v58
	v_mul_f32_e32 v4, 4.0, v60
	v_mul_f32_e32 v5, 4.0, v62
	v_mul_f32_e32 v6, 4.0, v64
	v_mul_f32_e32 v7, 4.0, v66
	v_mul_f32_e32 v8, 4.0, v68
	v_mul_f32_e32 v9, 4.0, v70
	v_mul_f32_e32 v10, 4.0, v72
	v_mul_f32_e32 v11, 4.0, v74
	v_mul_f32_e32 v12, 4.0, v76
	v_mul_f32_e32 v13, 4.0, v78
	v_mul_f32_e32 v14, 4.0, v80
	v_mul_f32_e32 v15, 4.0, v82
	v_mul_f32_e32 v16, 4.0, v84
	v_mul_f32_e32 v17, 4.0, v86
	v_mul_f32_e32 v18, 4.0, v57
	v_mul_f32_e32 v19, 4.0, v59
	v_mul_f32_e32 v20, 4.0, v61
	v_mul_f32_e32 v21, 4.0, v63
	v_mul_f32_e32 v22, 4.0, v65
	v_mul_f32_e32 v23, 4.0, v67
	v_mul_f32_e32 v24, 4.0, v69
	v_mul_f32_e32 v25, 4.0, v71
	v_mul_f32_e32 v26, 4.0, v73
	v_mul_f32_e32 v27, 4.0, v75
	v_mul_f32_e32 v28, 4.0, v77
	v_mul_f32_e32 v29, 4.0, v79
	v_mul_f32_e32 v30, 4.0, v81
	v_mul_f32_e32 v31, 4.0, v83
	v_mul_f32_e32 v32, 4.0, v85
	v_mul_f32_e32 v33, 4.0, v87
	s_nop 0
	v_cvt_scalef32_2xpk16_fp6_f32 v[46:51], v[2:17], v[18:33], 1.0
	global_store_dwordx4 v53, v[40:43], s[6:7]
	global_store_dwordx4 v53, v[48:51], s[6:7] offset:1024
	global_store_dwordx4 v53, v[44:47], s[6:7] offset:2048
	s_add_u32 s6, s6, s13
	s_addc_u32 s7, s7, 0
	global_load_dwordx4 v[56:59], v52, s[2:3] sc0 sc1 nt
	global_load_dwordx4 v[60:63], v52, s[2:3] offset:1024 sc0 sc1 nt
	global_load_dwordx4 v[64:67], v52, s[2:3] offset:2048 sc0 sc1 nt
	global_load_dwordx4 v[68:71], v52, s[2:3] offset:3072 sc0 sc1 nt
	global_load_dwordx4 v[72:75], v54, s[2:3] sc0 sc1 nt
	global_load_dwordx4 v[76:79], v54, s[2:3] offset:1024 sc0 sc1 nt
	global_load_dwordx4 v[80:83], v54, s[2:3] offset:2048 sc0 sc1 nt
	global_load_dwordx4 v[84:87], v54, s[2:3] offset:3072 sc0 sc1 nt
	s_waitcnt vmcnt(0)
	v_mul_f32_e32 v2, s16, v56
	v_mul_f32_e32 v3, s16, v58
	v_mul_f32_e32 v4, s16, v60
	v_mul_f32_e32 v5, s16, v62
	v_mul_f32_e32 v6, s16, v64
	v_mul_f32_e32 v7, s16, v66
	v_mul_f32_e32 v8, s16, v68
	v_mul_f32_e32 v9, s16, v70
	v_mul_f32_e32 v10, s16, v72
	v_mul_f32_e32 v11, s16, v74
	v_mul_f32_e32 v12, s16, v76
	v_mul_f32_e32 v13, s16, v78
	v_mul_f32_e32 v14, s16, v80
	v_mul_f32_e32 v15, s16, v82
	v_mul_f32_e32 v16, s16, v84
	v_mul_f32_e32 v17, s16, v86
	v_mul_f32_e32 v18, s16, v57
	v_mul_f32_e32 v19, s16, v59
	v_mul_f32_e32 v20, s16, v61
	v_mul_f32_e32 v21, s16, v63
	v_mul_f32_e32 v22, s16, v65
	v_mul_f32_e32 v23, s16, v67
	v_mul_f32_e32 v24, s16, v69
	v_mul_f32_e32 v25, s16, v71
	v_mul_f32_e32 v26, s16, v73
	v_mul_f32_e32 v27, s16, v75
	v_mul_f32_e32 v28, s16, v77
	v_mul_f32_e32 v29, s16, v79
	v_mul_f32_e32 v30, s16, v81
	v_mul_f32_e32 v31, s16, v83
	v_mul_f32_e32 v32, s16, v85
	v_mul_f32_e32 v33, s16, v87
	s_nop 0
	v_cvt_scalef32_2xpk16_fp6_f32 v[40:45], v[2:17], v[18:33], 1.0
	global_load_dwordx4 v[56:59], v52, s[4:5] sc0 sc1 nt
	global_load_dwordx4 v[60:63], v52, s[4:5] offset:1024 sc0 sc1 nt
	global_load_dwordx4 v[64:67], v52, s[4:5] offset:2048 sc0 sc1 nt
	global_load_dwordx4 v[68:71], v52, s[4:5] offset:3072 sc0 sc1 nt
	global_load_dwordx4 v[72:75], v54, s[4:5] sc0 sc1 nt
	global_load_dwordx4 v[76:79], v54, s[4:5] offset:1024 sc0 sc1 nt
	global_load_dwordx4 v[80:83], v54, s[4:5] offset:2048 sc0 sc1 nt
	global_load_dwordx4 v[84:87], v54, s[4:5] offset:3072 sc0 sc1 nt
	s_add_u32 s2, s2, s12
	s_addc_u32 s3, s3, 0
	s_add_u32 s4, s4, s12
	s_addc_u32 s5, s5, 0
	s_waitcnt vmcnt(0)
	v_mul_f32_e32 v2, 4.0, v56
	v_mul_f32_e32 v3, 4.0, v58
	v_mul_f32_e32 v4, 4.0, v60
	v_mul_f32_e32 v5, 4.0, v62
	v_mul_f32_e32 v6, 4.0, v64
	v_mul_f32_e32 v7, 4.0, v66
	v_mul_f32_e32 v8, 4.0, v68
	v_mul_f32_e32 v9, 4.0, v70
	v_mul_f32_e32 v10, 4.0, v72
	v_mul_f32_e32 v11, 4.0, v74
	v_mul_f32_e32 v12, 4.0, v76
	v_mul_f32_e32 v13, 4.0, v78
	v_mul_f32_e32 v14, 4.0, v80
	v_mul_f32_e32 v15, 4.0, v82
	v_mul_f32_e32 v16, 4.0, v84
	v_mul_f32_e32 v17, 4.0, v86
	v_mul_f32_e32 v18, 4.0, v57
	v_mul_f32_e32 v19, 4.0, v59
	v_mul_f32_e32 v20, 4.0, v61
	v_mul_f32_e32 v21, 4.0, v63
	v_mul_f32_e32 v22, 4.0, v65
	v_mul_f32_e32 v23, 4.0, v67
	v_mul_f32_e32 v24, 4.0, v69
	v_mul_f32_e32 v25, 4.0, v71
	v_mul_f32_e32 v26, 4.0, v73
	v_mul_f32_e32 v27, 4.0, v75
	v_mul_f32_e32 v28, 4.0, v77
	v_mul_f32_e32 v29, 4.0, v79
	v_mul_f32_e32 v30, 4.0, v81
	v_mul_f32_e32 v31, 4.0, v83
	v_mul_f32_e32 v32, 4.0, v85
	v_mul_f32_e32 v33, 4.0, v87
	s_nop 0
	v_cvt_scalef32_2xpk16_fp6_f32 v[46:51], v[2:17], v[18:33], 1.0
	global_store_dwordx4 v53, v[40:43], s[6:7]
	global_store_dwordx4 v53, v[48:51], s[6:7] offset:1024
	global_store_dwordx4 v53, v[44:47], s[6:7] offset:2048
	s_add_u32 s6, s6, s13
	s_addc_u32 s7, s7, 0
	global_load_dwordx4 v[56:59], v52, s[2:3] sc0 sc1 nt
	global_load_dwordx4 v[60:63], v52, s[2:3] offset:1024 sc0 sc1 nt
	global_load_dwordx4 v[64:67], v52, s[2:3] offset:2048 sc0 sc1 nt
	global_load_dwordx4 v[68:71], v52, s[2:3] offset:3072 sc0 sc1 nt
	global_load_dwordx4 v[72:75], v54, s[2:3] sc0 sc1 nt
	global_load_dwordx4 v[76:79], v54, s[2:3] offset:1024 sc0 sc1 nt
	global_load_dwordx4 v[80:83], v54, s[2:3] offset:2048 sc0 sc1 nt
	global_load_dwordx4 v[84:87], v54, s[2:3] offset:3072 sc0 sc1 nt
	s_waitcnt vmcnt(0)
; __global__ void __launch_bounds__(256, 2) fwd_megakernel(Params p) {
;     ...
;   for (size_t blk = (size_t)bid * 256 + tid; blk < (size_t)16384 * 64; blk += (size_t)nb * 256) {
; #pragma unroll
;     for (int tb = 0; tb < 2; ++tb) {
;       const float* src = (tb ? p.peer_up : p.peer_down) + blk * 32;
;       const float sc = tb ? UP_SCALE : DOWN_SCALE;
;       v16f va, vb;
; #pragma unroll
;       for (int q = 0; q < 4; ++q) {
;         const float4 x = *(const float4*)(src + q * 8), y = *(const float4*)(src + q * 8 + 4);
;         va[q * 4] = x.x * sc; vb[q * 4] = x.y * sc; va[q * 4 + 1] = x.z * sc; vb[q * 4 + 1] = x.w * sc;
;         va[q * 4 + 2] = y.x * sc; vb[q * 4 + 2] = y.y * sc; va[q * 4 + 3] = y.z * sc; vb[q * 4 + 3] = y.w * sc;
;       }
;       const v6u o = __builtin_amdgcn_cvt_scalef32_2xpk16_fp6_f32(va, vb, 1.0f);
;       unsigned char* dst = (tb ? p.up8 : p.down8) + blk * 24;
;       *(u32x2*)dst = u32x2{o[0], o[1]}; *(u32x2*)(dst + 8) = u32x2{o[2], o[3]}; *(u32x2*)(dst + 16) = u32x2{o[4], o[5]};
;     }
	v_mul_f32_e32 v2, s16, v56
	v_mul_f32_e32 v3, s16, v58
	v_mul_f32_e32 v4, s16, v60
	v_mul_f32_e32 v5, s16, v62
	v_mul_f32_e32 v6, s16, v64
	v_mul_f32_e32 v7, s16, v66
	v_mul_f32_e32 v8, s16, v68
	v_mul_f32_e32 v9, s16, v70
	v_mul_f32_e32 v10, s16, v72
	v_mul_f32_e32 v11, s16, v74
	v_mul_f32_e32 v12, s16, v76
	v_mul_f32_e32 v13, s16, v78
	v_mul_f32_e32 v14, s16, v80
	v_mul_f32_e32 v15, s16, v82
	v_mul_f32_e32 v16, s16, v84
	v_mul_f32_e32 v17, s16, v86
	v_mul_f32_e32 v18, s16, v57
	v_mul_f32_e32 v19, s16, v59
	v_mul_f32_e32 v20, s16, v61
	v_mul_f32_e32 v21, s16, v63
	v_mul_f32_e32 v22, s16, v65
	v_mul_f32_e32 v23, s16, v67
	v_mul_f32_e32 v24, s16, v69
	v_mul_f32_e32 v25, s16, v71
	v_mul_f32_e32 v26, s16, v73
	v_mul_f32_e32 v27, s16, v75
	v_mul_f32_e32 v28, s16, v77
	v_mul_f32_e32 v29, s16, v79
	v_mul_f32_e32 v30, s16, v81
	v_mul_f32_e32 v31, s16, v83
	v_mul_f32_e32 v32, s16, v85
	v_mul_f32_e32 v33, s16, v87
	s_nop 0
	v_cvt_scalef32_2xpk16_fp6_f32 v[40:45], v[2:17], v[18:33], 1.0
	global_load_dwordx4 v[56:59], v52, s[4:5] sc0 sc1 nt
	global_load_dwordx4 v[60:63], v52, s[4:5] offset:1024 sc0 sc1 nt
	global_load_dwordx4 v[64:67], v52, s[4:5] offset:2048 sc0 sc1 nt
	global_load_dwordx4 v[68:71], v52, s[4:5] offset:3072 sc0 sc1 nt
	global_load_dwordx4 v[72:75], v54, s[4:5] sc0 sc1 nt
	global_load_dwordx4 v[76:79], v54, s[4:5] offset:1024 sc0 sc1 nt
	global_load_dwordx4 v[80:83], v54, s[4:5] offset:2048 sc0 sc1 nt
	global_load_dwordx4 v[84:87], v54, s[4:5] offset:3072 sc0 sc1 nt
	s_add_u32 s2, s2, s12
	s_addc_u32 s3, s3, 0
	s_add_u32 s4, s4, s12
	s_addc_u32 s5, s5, 0
	s_waitcnt vmcnt(0)
	v_mul_f32_e32 v2, 4.0, v56
	v_mul_f32_e32 v3, 4.0, v58
	v_mul_f32_e32 v4, 4.0, v60
	v_mul_f32_e32 v5, 4.0, v62
	v_mul_f32_e32 v6, 4.0, v64
	v_mul_f32_e32 v7, 4.0, v66
	v_mul_f32_e32 v8, 4.0, v68
	v_mul_f32_e32 v9, 4.0, v70
	v_mul_f32_e32 v10, 4.0, v72
	v_mul_f32_e32 v11, 4.0, v74
	v_mul_f32_e32 v12, 4.0, v76
	v_mul_f32_e32 v13, 4.0, v78
	v_mul_f32_e32 v14, 4.0, v80
	v_mul_f32_e32 v15, 4.0, v82
	v_mul_f32_e32 v16, 4.0, v84
	v_mul_f32_e32 v17, 4.0, v86
	v_mul_f32_e32 v18, 4.0, v57
	v_mul_f32_e32 v19, 4.0, v59
	v_mul_f32_e32 v20, 4.0, v61
	v_mul_f32_e32 v21, 4.0, v63
	v_mul_f32_e32 v22, 4.0, v65
	v_mul_f32_e32 v23, 4.0, v67
	v_mul_f32_e32 v24, 4.0, v69
	v_mul_f32_e32 v25, 4.0, v71
	v_mul_f32_e32 v26, 4.0, v73
	v_mul_f32_e32 v27, 4.0, v75
	v_mul_f32_e32 v28, 4.0, v77
	v_mul_f32_e32 v29, 4.0, v79
	v_mul_f32_e32 v30, 4.0, v81
	v_mul_f32_e32 v31, 4.0, v83
	v_mul_f32_e32 v32, 4.0, v85
	v_mul_f32_e32 v33, 4.0, v87
	s_nop 0
	v_cvt_scalef32_2xpk16_fp6_f32 v[46:51], v[2:17], v[18:33], 1.0
	global_store_dwordx4 v53, v[40:43], s[6:7]
	global_store_dwordx4 v53, v[48:51], s[6:7] offset:1024
	global_store_dwordx4 v53, v[44:47], s[6:7] offset:2048
	s_add_u32 s6, s6, s13
	s_addc_u32 s7, s7, 0
	global_load_dwordx4 v[56:59], v52, s[2:3] sc0 sc1 nt
	global_load_dwordx4 v[60:63], v52, s[2:3] offset:1024 sc0 sc1 nt
	global_load_dwordx4 v[64:67], v52, s[2:3] offset:2048 sc0 sc1 nt
	global_load_dwordx4 v[68:71], v52, s[2:3] offset:3072 sc0 sc1 nt
	global_load_dwordx4 v[72:75], v54, s[2:3] sc0 sc1 nt
	global_load_dwordx4 v[76:79], v54, s[2:3] offset:1024 sc0 sc1 nt
	global_load_dwordx4 v[80:83], v54, s[2:3] offset:2048 sc0 sc1 nt
	global_load_dwordx4 v[84:87], v54, s[2:3] offset:3072 sc0 sc1 nt
	s_waitcnt vmcnt(0)
	v_mul_f32_e32 v2, s16, v56
	v_mul_f32_e32 v3, s16, v58
	v_mul_f32_e32 v4, s16, v60
	v_mul_f32_e32 v5, s16, v62
	v_mul_f32_e32 v6, s16, v64
	v_mul_f32_e32 v7, s16, v66
	v_mul_f32_e32 v8, s16, v68
	v_mul_f32_e32 v9, s16, v70
	v_mul_f32_e32 v10, s16, v72
	v_mul_f32_e32 v11, s16, v74
	v_mul_f32_e32 v12, s16, v76
	v_mul_f32_e32 v13, s16, v78
	v_mul_f32_e32 v14, s16, v80
	v_mul_f32_e32 v15, s16, v82
	v_mul_f32_e32 v16, s16, v84
	v_mul_f32_e32 v17, s16, v86
	v_mul_f32_e32 v18, s16, v57
	v_mul_f32_e32 v19, s16, v59
	v_mul_f32_e32 v20, s16, v61
	v_mul_f32_e32 v21, s16, v63
	v_mul_f32_e32 v22, s16, v65
	v_mul_f32_e32 v23, s16, v67
	v_mul_f32_e32 v24, s16, v69
	v_mul_f32_e32 v25, s16, v71
	v_mul_f32_e32 v26, s16, v73
	v_mul_f32_e32 v27, s16, v75
	v_mul_f32_e32 v28, s16, v77
	v_mul_f32_e32 v29, s16, v79
	v_mul_f32_e32 v30, s16, v81
	v_mul_f32_e32 v31, s16, v83
	v_mul_f32_e32 v32, s16, v85
	v_mul_f32_e32 v33, s16, v87
	s_nop 0
	v_cvt_scalef32_2xpk16_fp6_f32 v[40:45], v[2:17], v[18:33], 1.0
	global_load_dwordx4 v[56:59], v52, s[4:5] sc0 sc1 nt
	global_load_dwordx4 v[60:63], v52, s[4:5] offset:1024 sc0 sc1 nt
	global_load_dwordx4 v[64:67], v52, s[4:5] offset:2048 sc0 sc1 nt
	global_load_dwordx4 v[68:71], v52, s[4:5] offset:3072 sc0 sc1 nt
	global_load_dwordx4 v[72:75], v54, s[4:5] sc0 sc1 nt
	global_load_dwordx4 v[76:79], v54, s[4:5] offset:1024 sc0 sc1 nt
	global_load_dwordx4 v[80:83], v54, s[4:5] offset:2048 sc0 sc1 nt
	global_load_dwordx4 v[84:87], v54, s[4:5] offset:3072 sc0 sc1 nt
	s_waitcnt vmcnt(0)
	v_mul_f32_e32 v2, 4.0, v56
	v_mul_f32_e32 v3, 4.0, v58
	v_mul_f32_e32 v4, 4.0, v60
	v_mul_f32_e32 v5, 4.0, v62
	v_mul_f32_e32 v6, 4.0, v64
	v_mul_f32_e32 v7, 4.0, v66
	v_mul_f32_e32 v8, 4.0, v68
	v_mul_f32_e32 v9, 4.0, v70
	v_mul_f32_e32 v10, 4.0, v72
	v_mul_f32_e32 v11, 4.0, v74
	v_mul_f32_e32 v12, 4.0, v76
	v_mul_f32_e32 v13, 4.0, v78
	v_mul_f32_e32 v14, 4.0, v80
	v_mul_f32_e32 v15, 4.0, v82
	v_mul_f32_e32 v16, 4.0, v84
	v_mul_f32_e32 v17, 4.0, v86
	v_mul_f32_e32 v18, 4.0, v57
	v_mul_f32_e32 v19, 4.0, v59
	v_mul_f32_e32 v20, 4.0, v61
	v_mul_f32_e32 v21, 4.0, v63
	v_mul_f32_e32 v22, 4.0, v65
	v_mul_f32_e32 v23, 4.0, v67
	v_mul_f32_e32 v24, 4.0, v69
	v_mul_f32_e32 v25, 4.0, v71
	v_mul_f32_e32 v26, 4.0, v73
	v_mul_f32_e32 v27, 4.0, v75
	v_mul_f32_e32 v28, 4.0, v77
	v_mul_f32_e32 v29, 4.0, v79
	v_mul_f32_e32 v30, 4.0, v81
	v_mul_f32_e32 v31, 4.0, v83
	v_mul_f32_e32 v32, 4.0, v85
	v_mul_f32_e32 v33, 4.0, v87
	s_nop 0
	v_cvt_scalef32_2xpk16_fp6_f32 v[46:51], v[2:17], v[18:33], 1.0
	global_store_dwordx4 v53, v[40:43], s[6:7]
	global_store_dwordx4 v53, v[48:51], s[6:7] offset:1024
	global_store_dwordx4 v53, v[44:47], s[6:7] offset:2048
	s_add_u32 s6, s6, s13
	s_addc_u32 s7, s7, 0
	s_branch .Lenc_end_a
; __global__ void __launch_bounds__(256, 2) fwd_megakernel(Params p) {
;     ...
;   for (size_t blk = (size_t)bid * 256 + tid; blk < (size_t)16384 * 64; blk += (size_t)nb * 256) {
; #pragma unroll
;     for (int tb = 0; tb < 2; ++tb) {
;       const float* src = (tb ? p.peer_up : p.peer_down) + blk * 32;
;       const float sc = tb ? UP_SCALE : DOWN_SCALE;
;       v16f va, vb;
; #pragma unroll
;       for (int q = 0; q < 4; ++q) {
;         const float4 x = *(const float4*)(src + q * 8), y = *(const float4*)(src + q * 8 + 4);
;         va[q * 4] = x.x * sc; vb[q * 4] = x.y * sc; va[q * 4 + 1] = x.z * sc; vb[q * 4 + 1] = x.w * sc;
;         va[q * 4 + 2] = y.x * sc; vb[q * 4 + 2] = y.y * sc; va[q * 4 + 3] = y.z * sc; vb[q * 4 + 3] = y.w * sc;
.Lenc_generic_a:
	global_load_dwordx4 v[64:67], v52, s[2:3] sc0 sc1 nt
	global_load_dwordx4 v[68:71], v52, s[2:3] offset:1024 sc0 sc1 nt
	global_load_dwordx4 v[72:75], v52, s[2:3] offset:2048 sc0 sc1 nt
	global_load_dwordx4 v[76:79], v52, s[2:3] offset:3072 sc0 sc1 nt
	global_load_dwordx4 v[80:83], v54, s[2:3] sc0 sc1 nt
	global_load_dwordx4 v[84:87], v54, s[2:3] offset:1024 sc0 sc1 nt
	global_load_dwordx4 v[88:91], v54, s[2:3] offset:2048 sc0 sc1 nt
	global_load_dwordx4 v[92:95], v54, s[2:3] offset:3072 sc0 sc1 nt
	global_load_dwordx4 v[96:99], v52, s[4:5] sc0 sc1 nt
	global_load_dwordx4 v[100:103], v52, s[4:5] offset:1024 sc0 sc1 nt
	global_load_dwordx4 v[104:107], v52, s[4:5] offset:2048 sc0 sc1 nt
	global_load_dwordx4 v[108:111], v52, s[4:5] offset:3072 sc0 sc1 nt
	global_load_dwordx4 v[112:115], v54, s[4:5] sc0 sc1 nt
	global_load_dwordx4 v[116:119], v54, s[4:5] offset:1024 sc0 sc1 nt
	global_load_dwordx4 v[120:123], v54, s[4:5] offset:2048 sc0 sc1 nt
	global_load_dwordx4 v[124:127], v54, s[4:5] offset:3072 sc0 sc1 nt
; __global__ void __launch_bounds__(256, 2) fwd_megakernel(Params p) {
;     ...
;   for (size_t blk = (size_t)bid * 256 + tid; blk < (size_t)16384 * 64; blk += (size_t)nb * 256) {
; #pragma unroll
;     for (int tb = 0; tb < 2; ++tb) {
;       const float* src = (tb ? p.peer_up : p.peer_down) + blk * 32;
;       const float sc = tb ? UP_SCALE : DOWN_SCALE;
;       v16f va, vb;
; #pragma unroll
;       for (int q = 0; q < 4; ++q) {
;         const float4 x = *(const float4*)(src + q * 8), y = *(const float4*)(src + q * 8 + 4);
;         va[q * 4] = x.x * sc; vb[q * 4] = x.y * sc; va[q * 4 + 1] = x.z * sc; vb[q * 4 + 1] = x.w * sc;
;         va[q * 4 + 2] = y.x * sc; vb[q * 4 + 2] = y.y * sc; va[q * 4 + 3] = y.z * sc; vb[q * 4 + 3] = y.w * sc;
;       }
;       const v6u o = __builtin_amdgcn_cvt_scalef32_2xpk16_fp6_f32(va, vb, 1.0f);
;       unsigned char* dst = (tb ? p.up8 : p.down8) + blk * 24;
;       *(u32x2*)dst = u32x2{o[0], o[1]}; *(u32x2*)(dst + 8) = u32x2{o[2], o[3]}; *(u32x2*)(dst + 16) = u32x2{o[4], o[5]};
;     }
.Lenc_loop_a:
	s_add_u32 s10, s10, s11
	s_cmp_lt_u32 s10, 0x100000
	s_cbranch_scc0 .Lenc_last_a_0
	s_add_u32 s2, s2, s12
	s_addc_u32 s3, s3, 0
	s_add_u32 s4, s4, s12
	s_addc_u32 s5, s5, 0
	global_load_dwordx4 v[128:131], v52, s[2:3] sc0 sc1 nt
	global_load_dwordx4 v[132:135], v52, s[2:3] offset:1024 sc0 sc1 nt
	global_load_dwordx4 v[136:139], v52, s[2:3] offset:2048 sc0 sc1 nt
	global_load_dwordx4 v[140:143], v52, s[2:3] offset:3072 sc0 sc1 nt
	global_load_dwordx4 v[144:147], v54, s[2:3] sc0 sc1 nt
	global_load_dwordx4 v[148:151], v54, s[2:3] offset:1024 sc0 sc1 nt
	global_load_dwordx4 v[152:155], v54, s[2:3] offset:2048 sc0 sc1 nt
	global_load_dwordx4 v[156:159], v54, s[2:3] offset:3072 sc0 sc1 nt
	global_load_dwordx4 v[160:163], v52, s[4:5] sc0 sc1 nt
	global_load_dwordx4 v[164:167], v52, s[4:5] offset:1024 sc0 sc1 nt
	global_load_dwordx4 v[168:171], v52, s[4:5] offset:2048 sc0 sc1 nt
	global_load_dwordx4 v[172:175], v52, s[4:5] offset:3072 sc0 sc1 nt
	global_load_dwordx4 v[176:179], v54, s[4:5] sc0 sc1 nt
	global_load_dwordx4 v[180:183], v54, s[4:5] offset:1024 sc0 sc1 nt
	global_load_dwordx4 v[184:187], v54, s[4:5] offset:2048 sc0 sc1 nt
	global_load_dwordx4 v[188:191], v54, s[4:5] offset:3072 sc0 sc1 nt
	s_waitcnt vmcnt(16)
	v_mul_f32_e32 v2, s16, v64
	v_mul_f32_e32 v3, s16, v66
	v_mul_f32_e32 v4, s16, v68
	v_mul_f32_e32 v5, s16, v70
	v_mul_f32_e32 v6, s16, v72
	v_mul_f32_e32 v7, s16, v74
	v_mul_f32_e32 v8, s16, v76
	v_mul_f32_e32 v9, s16, v78
	v_mul_f32_e32 v10, s16, v80
	v_mul_f32_e32 v11, s16, v82
	v_mul_f32_e32 v12, s16, v84
	v_mul_f32_e32 v13, s16, v86
	v_mul_f32_e32 v14, s16, v88
	v_mul_f32_e32 v15, s16, v90
	v_mul_f32_e32 v16, s16, v92
	v_mul_f32_e32 v17, s16, v94
	v_mul_f32_e32 v18, s16, v65
	v_mul_f32_e32 v19, s16, v67
	v_mul_f32_e32 v20, s16, v69
	v_mul_f32_e32 v21, s16, v71
	v_mul_f32_e32 v22, s16, v73
	v_mul_f32_e32 v23, s16, v75
	v_mul_f32_e32 v24, s16, v77
	v_mul_f32_e32 v25, s16, v79
	v_mul_f32_e32 v26, s16, v81
	v_mul_f32_e32 v27, s16, v83
	v_mul_f32_e32 v28, s16, v85
	v_mul_f32_e32 v29, s16, v87
	v_mul_f32_e32 v30, s16, v89
	v_mul_f32_e32 v31, s16, v91
	v_mul_f32_e32 v32, s16, v93
	v_mul_f32_e32 v33, s16, v95
	s_nop 0
	v_cvt_scalef32_2xpk16_fp6_f32 v[40:45], v[2:17], v[18:33], 1.0
	v_mul_f32_e32 v2, 4.0, v96
	v_mul_f32_e32 v3, 4.0, v98
	v_mul_f32_e32 v4, 4.0, v100
	v_mul_f32_e32 v5, 4.0, v102
	v_mul_f32_e32 v6, 4.0, v104
	v_mul_f32_e32 v7, 4.0, v106
	v_mul_f32_e32 v8, 4.0, v108
	v_mul_f32_e32 v9, 4.0, v110
	v_mul_f32_e32 v10, 4.0, v112
	v_mul_f32_e32 v11, 4.0, v114
	v_mul_f32_e32 v12, 4.0, v116
	v_mul_f32_e32 v13, 4.0, v118
	v_mul_f32_e32 v14, 4.0, v120
	v_mul_f32_e32 v15, 4.0, v122
	v_mul_f32_e32 v16, 4.0, v124
	v_mul_f32_e32 v17, 4.0, v126
	v_mul_f32_e32 v18, 4.0, v97
	v_mul_f32_e32 v19, 4.0, v99
	v_mul_f32_e32 v20, 4.0, v101
	v_mul_f32_e32 v21, 4.0, v103
	v_mul_f32_e32 v22, 4.0, v105
	v_mul_f32_e32 v23, 4.0, v107
	v_mul_f32_e32 v24, 4.0, v109
	v_mul_f32_e32 v25, 4.0, v111
	v_mul_f32_e32 v26, 4.0, v113
	v_mul_f32_e32 v27, 4.0, v115
	v_mul_f32_e32 v28, 4.0, v117
	v_mul_f32_e32 v29, 4.0, v119
	v_mul_f32_e32 v30, 4.0, v121
	v_mul_f32_e32 v31, 4.0, v123
	v_mul_f32_e32 v32, 4.0, v125
	v_mul_f32_e32 v33, 4.0, v127
	s_nop 0
	v_cvt_scalef32_2xpk16_fp6_f32 v[46:51], v[2:17], v[18:33], 1.0
	global_store_dwordx4 v53, v[40:43], s[6:7]
	global_store_dwordx4 v53, v[48:51], s[6:7] offset:1024
	global_store_dwordx4 v53, v[44:47], s[6:7] offset:2048
	s_add_u32 s6, s6, s13
	s_addc_u32 s7, s7, 0
	s_add_u32 s10, s10, s11
	s_cmp_lt_u32 s10, 0x100000
	s_cbranch_scc0 .Lenc_last_a_1
	s_add_u32 s2, s2, s12
	s_addc_u32 s3, s3, 0
	s_add_u32 s4, s4, s12
	s_addc_u32 s5, s5, 0
	global_load_dwordx4 v[64:67], v52, s[2:3] sc0 sc1 nt
	global_load_dwordx4 v[68:71], v52, s[2:3] offset:1024 sc0 sc1 nt
	global_load_dwordx4 v[72:75], v52, s[2:3] offset:2048 sc0 sc1 nt
	global_load_dwordx4 v[76:79], v52, s[2:3] offset:3072 sc0 sc1 nt
	global_load_dwordx4 v[80:83], v54, s[2:3] sc0 sc1 nt
	global_load_dwordx4 v[84:87], v54, s[2:3] offset:1024 sc0 sc1 nt
	global_load_dwordx4 v[88:91], v54, s[2:3] offset:2048 sc0 sc1 nt
	global_load_dwordx4 v[92:95], v54, s[2:3] offset:3072 sc0 sc1 nt
	global_load_dwordx4 v[96:99], v52, s[4:5] sc0 sc1 nt
	global_load_dwordx4 v[100:103], v52, s[4:5] offset:1024 sc0 sc1 nt
	global_load_dwordx4 v[104:107], v52, s[4:5] offset:2048 sc0 sc1 nt
	global_load_dwordx4 v[108:111], v52, s[4:5] offset:3072 sc0 sc1 nt
	global_load_dwordx4 v[112:115], v54, s[4:5] sc0 sc1 nt
	global_load_dwordx4 v[116:119], v54, s[4:5] offset:1024 sc0 sc1 nt
	global_load_dwordx4 v[120:123], v54, s[4:5] offset:2048 sc0 sc1 nt
	global_load_dwordx4 v[124:127], v54, s[4:5] offset:3072 sc0 sc1 nt
	s_waitcnt vmcnt(16)
	v_mul_f32_e32 v2, s16, v128
	v_mul_f32_e32 v3, s16, v130
	v_mul_f32_e32 v4, s16, v132
	v_mul_f32_e32 v5, s16, v134
	v_mul_f32_e32 v6, s16, v136
	v_mul_f32_e32 v7, s16, v138
	v_mul_f32_e32 v8, s16, v140
	v_mul_f32_e32 v9, s16, v142
	v_mul_f32_e32 v10, s16, v144
	v_mul_f32_e32 v11, s16, v146
	v_mul_f32_e32 v12, s16, v148
	v_mul_f32_e32 v13, s16, v150
	v_mul_f32_e32 v14, s16, v152
	v_mul_f32_e32 v15, s16, v154
	v_mul_f32_e32 v16, s16, v156
	v_mul_f32_e32 v17, s16, v158
	v_mul_f32_e32 v18, s16, v129
	v_mul_f32_e32 v19, s16, v131
	v_mul_f32_e32 v20, s16, v133
	v_mul_f32_e32 v21, s16, v135
	v_mul_f32_e32 v22, s16, v137
	v_mul_f32_e32 v23, s16, v139
	v_mul_f32_e32 v24, s16, v141
	v_mul_f32_e32 v25, s16, v143
	v_mul_f32_e32 v26, s16, v145
	v_mul_f32_e32 v27, s16, v147
	v_mul_f32_e32 v28, s16, v149
	v_mul_f32_e32 v29, s16, v151
	v_mul_f32_e32 v30, s16, v153
	v_mul_f32_e32 v31, s16, v155
	v_mul_f32_e32 v32, s16, v157
	v_mul_f32_e32 v33, s16, v159
	s_nop 0
	v_cvt_scalef32_2xpk16_fp6_f32 v[40:45], v[2:17], v[18:33], 1.0
	v_mul_f32_e32 v2, 4.0, v160
	v_mul_f32_e32 v3, 4.0, v162
	v_mul_f32_e32 v4, 4.0, v164
	v_mul_f32_e32 v5, 4.0, v166
	v_mul_f32_e32 v6, 4.0, v168
	v_mul_f32_e32 v7, 4.0, v170
	v_mul_f32_e32 v8, 4.0, v172
	v_mul_f32_e32 v9, 4.0, v174
	v_mul_f32_e32 v10, 4.0, v176
	v_mul_f32_e32 v11, 4.0, v178
	v_mul_f32_e32 v12, 4.0, v180
	v_mul_f32_e32 v13, 4.0, v182
	v_mul_f32_e32 v14, 4.0, v184
	v_mul_f32_e32 v15, 4.0, v186
	v_mul_f32_e32 v16, 4.0, v188
	v_mul_f32_e32 v17, 4.0, v190
	v_mul_f32_e32 v18, 4.0, v161
	v_mul_f32_e32 v19, 4.0, v163
	v_mul_f32_e32 v20, 4.0, v165
	v_mul_f32_e32 v21, 4.0, v167
	v_mul_f32_e32 v22, 4.0, v169
	v_mul_f32_e32 v23, 4.0, v171
	v_mul_f32_e32 v24, 4.0, v173
	v_mul_f32_e32 v25, 4.0, v175
	v_mul_f32_e32 v26, 4.0, v177
	v_mul_f32_e32 v27, 4.0, v179
	v_mul_f32_e32 v28, 4.0, v181
	v_mul_f32_e32 v29, 4.0, v183
	v_mul_f32_e32 v30, 4.0, v185
	v_mul_f32_e32 v31, 4.0, v187
	v_mul_f32_e32 v32, 4.0, v189
	v_mul_f32_e32 v33, 4.0, v191
	s_nop 0
	v_cvt_scalef32_2xpk16_fp6_f32 v[46:51], v[2:17], v[18:33], 1.0
	global_store_dwordx4 v53, v[40:43], s[6:7]
	global_store_dwordx4 v53, v[48:51], s[6:7] offset:1024
	global_store_dwordx4 v53, v[44:47], s[6:7] offset:2048
	s_add_u32 s6, s6, s13
	s_addc_u32 s7, s7, 0
	s_branch .Lenc_loop_a

; __global__ void __launch_bounds__(256, 2) fwd_megakernel(Params p) {
;     ...
;   if (bid >= (nb >> 1)) {
;   for (size_t blk = (size_t)bid * 256 + tid; blk < (size_t)16384 * 64; blk += (size_t)nb * 256) {
; #pragma unroll
;     for (int tb = 0; tb < 2; ++tb) {
;       const float* src = (tb ? p.peer_up : p.peer_down) + blk * 32;
;       const float sc = tb ? UP_SCALE : DOWN_SCALE;
;       v16f va, vb;
; #pragma unroll
;       for (int q = 0; q < 4; ++q) {
;         const float4 x = *(const float4*)(src + q * 8), y = *(const float4*)(src + q * 8 + 4);
;         va[q * 4] = x.x * sc; vb[q * 4] = x.y * sc; va[q * 4 + 1] = x.z * sc; vb[q * 4 + 1] = x.w * sc;
;         va[q * 4 + 2] = y.x * sc; vb[q * 4 + 2] = y.y * sc; va[q * 4 + 3] = y.z * sc; vb[q * 4 + 3] = y.w * sc;
;       }
;       const v6u o = __builtin_amdgcn_cvt_scalef32_2xpk16_fp6_f32(va, vb, 1.0f);
;       unsigned char* dst = (tb ? p.up8 : p.down8) + blk * 24;
;       *(u32x2*)dst = u32x2{o[0], o[1]}; *(u32x2*)(dst + 8) = u32x2{o[2], o[3]}; *(u32x2*)(dst + 16) = u32x2{o[4], o[5]};
;     }
.LBB0_1510:
	s_and_b64 vcc, exec, s[72:73]
	s_cbranch_vccz .LBB0_1515
	s_mov_b64 exec, -1
	v_lshrrev_b32_e32 v54, 6, v0
	v_and_b32_e32 v55, 63, v0
	v_lshlrev_b32_e32 v52, 13, v54
	v_lshl_or_b32 v52, v55, 4, v52
	v_mul_u32_u24_e32 v53, 0xc00, v54
	v_lshl_or_b32 v53, v55, 4, v53
	v_add_u32_e32 v54, 0x1000, v52
	s_lshl_b32 s10, s94, 8
	s_lshl_b32 s11, s92, 8
	s_lshl_b32 s12, s92, 15
	s_mul_i32 s13, s92, 0x3000
	s_mov_b32 s16, 0x42800000
	s_lshl_b32 s0, s94, 15
	s_add_u32 s2, s40, s0
	s_addc_u32 s3, s41, 0
	s_add_u32 s4, s42, s0
	s_addc_u32 s5, s43, 0
	s_mul_i32 s0, s94, 0x3000
	s_add_u32 s6, s62, s0
	s_addc_u32 s7, s63, 0
	s_cmp_lt_u32 s10, 0x100000
	s_cbranch_scc0 .Lenc_end_b
	s_cmpk_lg_u32 s92, 0x200
	s_cbranch_scc1 .Lenc_generic_b
	global_load_dwordx4 v[56:59], v52, s[2:3] sc0 sc1 nt
	global_load_dwordx4 v[60:63], v52, s[2:3] offset:1024 sc0 sc1 nt
	global_load_dwordx4 v[64:67], v52, s[2:3] offset:2048 sc0 sc1 nt
	global_load_dwordx4 v[68:71], v52, s[2:3] offset:3072 sc0 sc1 nt
	global_load_dwordx4 v[72:75], v54, s[2:3] sc0 sc1 nt
	global_load_dwordx4 v[76:79], v54, s[2:3] offset:1024 sc0 sc1 nt
	global_load_dwordx4 v[80:83], v54, s[2:3] offset:2048 sc0 sc1 nt
	global_load_dwordx4 v[84:87], v54, s[2:3] offset:3072 sc0 sc1 nt
	s_waitcnt vmcnt(0)
	v_mul_f32_e32 v2, s16, v56
	v_mul_f32_e32 v3, s16, v58
	v_mul_f32_e32 v4, s16, v60
	v_mul_f32_e32 v5, s16, v62
	v_mul_f32_e32 v6, s16, v64
	v_mul_f32_e32 v7, s16, v66
	v_mul_f32_e32 v8, s16, v68
	v_mul_f32_e32 v9, s16, v70
	v_mul_f32_e32 v10, s16, v72
	v_mul_f32_e32 v11, s16, v74
	v_mul_f32_e32 v12, s16, v76
	v_mul_f32_e32 v13, s16, v78
	v_mul_f32_e32 v14, s16, v80
	v_mul_f32_e32 v15, s16, v82
	v_mul_f32_e32 v16, s16, v84
	v_mul_f32_e32 v17, s16, v86
	v_mul_f32_e32 v18, s16, v57
	v_mul_f32_e32 v19, s16, v59
	v_mul_f32_e32 v20, s16, v61
	v_mul_f32_e32 v21, s16, v63
	v_mul_f32_e32 v22, s16, v65
	v_mul_f32_e32 v23, s16, v67
	v_mul_f32_e32 v24, s16, v69
	v_mul_f32_e32 v25, s16, v71
	v_mul_f32_e32 v26, s16, v73
	v_mul_f32_e32 v27, s16, v75
	v_mul_f32_e32 v28, s16, v77
	v_mul_f32_e32 v29, s16, v79
	v_mul_f32_e32 v30, s16, v81
	v_mul_f32_e32 v31, s16, v83
	v_mul_f32_e32 v32, s16, v85
	v_mul_f32_e32 v33, s16, v87
	s_nop 0
	v_cvt_scalef32_2xpk16_fp6_f32 v[40:45], v[2:17], v[18:33], 1.0
	global_load_dwordx4 v[56:59], v52, s[4:5] sc0 sc1 nt
	global_load_dwordx4 v[60:63], v52, s[4:5] offset:1024 sc0 sc1 nt
	global_load_dwordx4 v[64:67], v52, s[4:5] offset:2048 sc0 sc1 nt
	global_load_dwordx4 v[68:71], v52, s[4:5] offset:3072 sc0 sc1 nt
	global_load_dwordx4 v[72:75], v54, s[4:5] sc0 sc1 nt
	global_load_dwordx4 v[76:79], v54, s[4:5] offset:1024 sc0 sc1 nt
	global_load_dwordx4 v[80:83], v54, s[4:5] offset:2048 sc0 sc1 nt
	global_load_dwordx4 v[84:87], v54, s[4:5] offset:3072 sc0 sc1 nt
	s_add_u32 s2, s2, s12
	s_addc_u32 s3, s3, 0
	s_add_u32 s4, s4, s12
	s_addc_u32 s5, s5, 0
	s_waitcnt vmcnt(0)
	v_mul_f32_e32 v2, 4.0, v56
	v_mul_f32_e32 v3, 4.0, v58
	v_mul_f32_e32 v4, 4.0, v60
	v_mul_f32_e32 v5, 4.0, v62
	v_mul_f32_e32 v6, 4.0, v64
	v_mul_f32_e32 v7, 4.0, v66
	v_mul_f32_e32 v8, 4.0, v68
	v_mul_f32_e32 v9, 4.0, v70
	v_mul_f32_e32 v10, 4.0, v72
	v_mul_f32_e32 v11, 4.0, v74
	v_mul_f32_e32 v12, 4.0, v76
	v_mul_f32_e32 v13, 4.0, v78
	v_mul_f32_e32 v14, 4.0, v80
	v_mul_f32_e32 v15, 4.0, v82
	v_mul_f32_e32 v16, 4.0, v84
	v_mul_f32_e32 v17, 4.0, v86
	v_mul_f32_e32 v18, 4.0, v57
	v_mul_f32_e32 v19, 4.0, v59
	v_mul_f32_e32 v20, 4.0, v61
	v_mul_f32_e32 v21, 4.0, v63
	v_mul_f32_e32 v22, 4.0, v65
	v_mul_f32_e32 v23, 4.0, v67
	v_mul_f32_e32 v24, 4.0, v69
	v_mul_f32_e32 v25, 4.0, v71
	v_mul_f32_e32 v26, 4.0, v73
	v_mul_f32_e32 v27, 4.0, v75
	v_mul_f32_e32 v28, 4.0, v77
	v_mul_f32_e32 v29, 4.0, v79
	v_mul_f32_e32 v30, 4.0, v81
	v_mul_f32_e32 v31, 4.0, v83
	v_mul_f32_e32 v32, 4.0, v85
	v_mul_f32_e32 v33, 4.0, v87
	s_nop 0
	v_cvt_scalef32_2xpk16_fp6_f32 v[46:51], v[2:17], v[18:33], 1.0
	global_store_dwordx4 v53, v[40:43], s[6:7]
	global_store_dwordx4 v53, v[48:51], s[6:7] offset:1024
	global_store_dwordx4 v53, v[44:47], s[6:7] offset:2048
	s_add_u32 s6, s6, s13
	s_addc_u32 s7, s7, 0
	global_load_dwordx4 v[56:59], v52, s[2:3] sc0 sc1 nt
	global_load_dwordx4 v[60:63], v52, s[2:3] offset:1024 sc0 sc1 nt
	global_load_dwordx4 v[64:67], v52, s[2:3] offset:2048 sc0 sc1 nt
	global_load_dwordx4 v[68:71], v52, s[2:3] offset:3072 sc0 sc1 nt
	global_load_dwordx4 v[72:75], v54, s[2:3] sc0 sc1 nt
	global_load_dwordx4 v[76:79], v54, s[2:3] offset:1024 sc0 sc1 nt
	global_load_dwordx4 v[80:83], v54, s[2:3] offset:2048 sc0 sc1 nt
	global_load_dwordx4 v[84:87], v54, s[2:3] offset:3072 sc0 sc1 nt
	s_waitcnt vmcnt(0)
	v_mul_f32_e32 v2, s16, v56
	v_mul_f32_e32 v3, s16, v58
	v_mul_f32_e32 v4, s16, v60
	v_mul_f32_e32 v5, s16, v62
	v_mul_f32_e32 v6, s16, v64
	v_mul_f32_e32 v7, s16, v66
	v_mul_f32_e32 v8, s16, v68
	v_mul_f32_e32 v9, s16, v70
	v_mul_f32_e32 v10, s16, v72
	v_mul_f32_e32 v11, s16, v74
	v_mul_f32_e32 v12, s16, v76
	v_mul_f32_e32 v13, s16, v78
	v_mul_f32_e32 v14, s16, v80
	v_mul_f32_e32 v15, s16, v82
	v_mul_f32_e32 v16, s16, v84
	v_mul_f32_e32 v17, s16, v86
	v_mul_f32_e32 v18, s16, v57
	v_mul_f32_e32 v19, s16, v59
	v_mul_f32_e32 v20, s16, v61
	v_mul_f32_e32 v21, s16, v63
	v_mul_f32_e32 v22, s16, v65
	v_mul_f32_e32 v23, s16, v67
	v_mul_f32_e32 v24, s16, v69
	v_mul_f32_e32 v25, s16, v71
	v_mul_f32_e32 v26, s16, v73
	v_mul_f32_e32 v27, s16, v75
	v_mul_f32_e32 v28, s16, v77
	v_mul_f32_e32 v29, s16, v79
	v_mul_f32_e32 v30, s16, v81
	v_mul_f32_e32 v31, s16, v83
	v_mul_f32_e32 v32, s16, v85
	v_mul_f32_e32 v33, s16, v87
	s_nop 0
	v_cvt_scalef32_2xpk16_fp6_f32 v[40:45], v[2:17], v[18:33], 1.0
	global_load_dwordx4 v[56:59], v52, s[4:5] sc0 sc1 nt
	global_load_dwordx4 v[60:63], v52, s[4:5] offset:1024 sc0 sc1 nt
	global_load_dwordx4 v[64:67], v52, s[4:5] offset:2048 sc0 sc1 nt
	global_load_dwordx4 v[68:71], v52, s[4:5] offset:3072 sc0 sc1 nt
	global_load_dwordx4 v[72:75], v54, s[4:5] sc0 sc1 nt
	global_load_dwordx4 v[76:79], v54, s[4:5] offset:1024 sc0 sc1 nt
	global_load_dwordx4 v[80:83], v54, s[4:5] offset:2048 sc0 sc1 nt
	global_load_dwordx4 v[84:87], v54, s[4:5] offset:3072 sc0 sc1 nt
	s_add_u32 s2, s2, s12
	s_addc_u32 s3, s3, 0
	s_add_u32 s4, s4, s12
	s_addc_u32 s5, s5, 0
	s_waitcnt vmcnt(0)
; __global__ void __launch_bounds__(256, 2) fwd_megakernel(Params p) {
;     ...
;   for (size_t blk = (size_t)bid * 256 + tid; blk < (size_t)16384 * 64; blk += (size_t)nb * 256) {
; #pragma unroll
;     for (int tb = 0; tb < 2; ++tb) {
;       const float* src = (tb ? p.peer_up : p.peer_down) + blk * 32;
;       const float sc = tb ? UP_SCALE : DOWN_SCALE;
;       v16f va, vb;
; #pragma unroll
;       for (int q = 0; q < 4; ++q) {
;         const float4 x = *(const float4*)(src + q * 8), y = *(const float4*)(src + q * 8 + 4);
;         va[q * 4] = x.x * sc; vb[q * 4] = x.y * sc; va[q * 4 + 1] = x.z * sc; vb[q * 4 + 1] = x.w * sc;
;         va[q * 4 + 2] = y.x * sc; vb[q * 4 + 2] = y.y * sc; va[q * 4 + 3] = y.z * sc; vb[q * 4 + 3] = y.w * sc;
;       }
;       const v6u o = __builtin_amdgcn_cvt_scalef32_2xpk16_fp6_f32(va, vb, 1.0f);
;       unsigned char* dst = (tb ? p.up8 : p.down8) + blk * 24;
;       *(u32x2*)dst = u32x2{o[0], o[1]}; *(u32x2*)(dst + 8) = u32x2{o[2], o[3]}; *(u32x2*)(dst + 16) = u32x2{o[4], o[5]};
;     }
	v_mul_f32_e32 v2, 4.0, v56
	v_mul_f32_e32 v3, 4.0, v58
	v_mul_f32_e32 v4, 4.0, v60
	v_mul_f32_e32 v5, 4.0, v62
	v_mul_f32_e32 v6, 4.0, v64
	v_mul_f32_e32 v7, 4.0, v66
	v_mul_f32_e32 v8, 4.0, v68
	v_mul_f32_e32 v9, 4.0, v70
	v_mul_f32_e32 v10, 4.0, v72
	v_mul_f32_e32 v11, 4.0, v74
	v_mul_f32_e32 v12, 4.0, v76
	v_mul_f32_e32 v13, 4.0, v78
	v_mul_f32_e32 v14, 4.0, v80
	v_mul_f32_e32 v15, 4.0, v82
	v_mul_f32_e32 v16, 4.0, v84
	v_mul_f32_e32 v17, 4.0, v86
	v_mul_f32_e32 v18, 4.0, v57
	v_mul_f32_e32 v19, 4.0, v59
	v_mul_f32_e32 v20, 4.0, v61
	v_mul_f32_e32 v21, 4.0, v63
	v_mul_f32_e32 v22, 4.0, v65
	v_mul_f32_e32 v23, 4.0, v67
	v_mul_f32_e32 v24, 4.0, v69
	v_mul_f32_e32 v25, 4.0, v71
	v_mul_f32_e32 v26, 4.0, v73
	v_mul_f32_e32 v27, 4.0, v75
	v_mul_f32_e32 v28, 4.0, v77
	v_mul_f32_e32 v29, 4.0, v79
	v_mul_f32_e32 v30, 4.0, v81
	v_mul_f32_e32 v31, 4.0, v83
	v_mul_f32_e32 v32, 4.0, v85
	v_mul_f32_e32 v33, 4.0, v87
	s_nop 0
	v_cvt_scalef32_2xpk16_fp6_f32 v[46:51], v[2:17], v[18:33], 1.0
	global_store_dwordx4 v53, v[40:43], s[6:7]
	global_store_dwordx4 v53, v[48:51], s[6:7] offset:1024
	global_store_dwordx4 v53, v[44:47], s[6:7] offset:2048
	s_add_u32 s6, s6, s13
	s_addc_u32 s7, s7, 0
	global_load_dwordx4 v[56:59], v52, s[2:3] sc0 sc1 nt
	global_load_dwordx4 v[60:63], v52, s[2:3] offset:1024 sc0 sc1 nt
	global_load_dwordx4 v[64:67], v52, s[2:3] offset:2048 sc0 sc1 nt
	global_load_dwordx4 v[68:71], v52, s[2:3] offset:3072 sc0 sc1 nt
	global_load_dwordx4 v[72:75], v54, s[2:3] sc0 sc1 nt
	global_load_dwordx4 v[76:79], v54, s[2:3] offset:1024 sc0 sc1 nt
	global_load_dwordx4 v[80:83], v54, s[2:3] offset:2048 sc0 sc1 nt
	global_load_dwordx4 v[84:87], v54, s[2:3] offset:3072 sc0 sc1 nt
	s_waitcnt vmcnt(0)
	v_mul_f32_e32 v2, s16, v56
	v_mul_f32_e32 v3, s16, v58
	v_mul_f32_e32 v4, s16, v60
	v_mul_f32_e32 v5, s16, v62
	v_mul_f32_e32 v6, s16, v64
	v_mul_f32_e32 v7, s16, v66
	v_mul_f32_e32 v8, s16, v68
	v_mul_f32_e32 v9, s16, v70
	v_mul_f32_e32 v10, s16, v72
	v_mul_f32_e32 v11, s16, v74
	v_mul_f32_e32 v12, s16, v76
	v_mul_f32_e32 v13, s16, v78
	v_mul_f32_e32 v14, s16, v80
	v_mul_f32_e32 v15, s16, v82
	v_mul_f32_e32 v16, s16, v84
	v_mul_f32_e32 v17, s16, v86
	v_mul_f32_e32 v18, s16, v57
	v_mul_f32_e32 v19, s16, v59
	v_mul_f32_e32 v20, s16, v61
	v_mul_f32_e32 v21, s16, v63
	v_mul_f32_e32 v22, s16, v65
	v_mul_f32_e32 v23, s16, v67
	v_mul_f32_e32 v24, s16, v69
	v_mul_f32_e32 v25, s16, v71
	v_mul_f32_e32 v26, s16, v73
	v_mul_f32_e32 v27, s16, v75
	v_mul_f32_e32 v28, s16, v77
	v_mul_f32_e32 v29, s16, v79
	v_mul_f32_e32 v30, s16, v81
	v_mul_f32_e32 v31, s16, v83
	v_mul_f32_e32 v32, s16, v85
	v_mul_f32_e32 v33, s16, v87
	s_nop 0
	v_cvt_scalef32_2xpk16_fp6_f32 v[40:45], v[2:17], v[18:33], 1.0
	global_load_dwordx4 v[56:59], v52, s[4:5] sc0 sc1 nt
	global_load_dwordx4 v[60:63], v52, s[4:5] offset:1024 sc0 sc1 nt
	global_load_dwordx4 v[64:67], v52, s[4:5] offset:2048 sc0 sc1 nt
	global_load_dwordx4 v[68:71], v52, s[4:5] offset:3072 sc0 sc1 nt
	global_load_dwordx4 v[72:75], v54, s[4:5] sc0 sc1 nt
	global_load_dwordx4 v[76:79], v54, s[4:5] offset:1024 sc0 sc1 nt
	global_load_dwordx4 v[80:83], v54, s[4:5] offset:2048 sc0 sc1 nt
	global_load_dwordx4 v[84:87], v54, s[4:5] offset:3072 sc0 sc1 nt
	s_add_u32 s2, s2, s12
	s_addc_u32 s3, s3, 0
	s_add_u32 s4, s4, s12
	s_addc_u32 s5, s5, 0
	s_waitcnt vmcnt(0)
	v_mul_f32_e32 v2, 4.0, v56
	v_mul_f32_e32 v3, 4.0, v58
	v_mul_f32_e32 v4, 4.0, v60
	v_mul_f32_e32 v5, 4.0, v62
	v_mul_f32_e32 v6, 4.0, v64
	v_mul_f32_e32 v7, 4.0, v66
	v_mul_f32_e32 v8, 4.0, v68
	v_mul_f32_e32 v9, 4.0, v70
	v_mul_f32_e32 v10, 4.0, v72
	v_mul_f32_e32 v11, 4.0, v74
	v_mul_f32_e32 v12, 4.0, v76
	v_mul_f32_e32 v13, 4.0, v78
	v_mul_f32_e32 v14, 4.0, v80
	v_mul_f32_e32 v15, 4.0, v82
	v_mul_f32_e32 v16, 4.0, v84
	v_mul_f32_e32 v17, 4.0, v86
	v_mul_f32_e32 v18, 4.0, v57
	v_mul_f32_e32 v19, 4.0, v59
	v_mul_f32_e32 v20, 4.0, v61
	v_mul_f32_e32 v21, 4.0, v63
	v_mul_f32_e32 v22, 4.0, v65
	v_mul_f32_e32 v23, 4.0, v67
	v_mul_f32_e32 v24, 4.0, v69
	v_mul_f32_e32 v25, 4.0, v71
	v_mul_f32_e32 v26, 4.0, v73
	v_mul_f32_e32 v27, 4.0, v75
	v_mul_f32_e32 v28, 4.0, v77
	v_mul_f32_e32 v29, 4.0, v79
	v_mul_f32_e32 v30, 4.0, v81
	v_mul_f32_e32 v31, 4.0, v83
	v_mul_f32_e32 v32, 4.0, v85
	v_mul_f32_e32 v33, 4.0, v87
	s_nop 0
	v_cvt_scalef32_2xpk16_fp6_f32 v[46:51], v[2:17], v[18:33], 1.0
	global_store_dwordx4 v53, v[40:43], s[6:7]
	global_store_dwordx4 v53, v[48:51], s[6:7] offset:1024
	global_store_dwordx4 v53, v[44:47], s[6:7] offset:2048
	s_add_u32 s6, s6, s13
	s_addc_u32 s7, s7, 0
	global_load_dwordx4 v[56:59], v52, s[2:3] sc0 sc1 nt
	global_load_dwordx4 v[60:63], v52, s[2:3] offset:1024 sc0 sc1 nt
	global_load_dwordx4 v[64:67], v52, s[2:3] offset:2048 sc0 sc1 nt
	global_load_dwordx4 v[68:71], v52, s[2:3] offset:3072 sc0 sc1 nt
	global_load_dwordx4 v[72:75], v54, s[2:3] sc0 sc1 nt
	global_load_dwordx4 v[76:79], v54, s[2:3] offset:1024 sc0 sc1 nt
	global_load_dwordx4 v[80:83], v54, s[2:3] offset:2048 sc0 sc1 nt
	global_load_dwordx4 v[84:87], v54, s[2:3] offset:3072 sc0 sc1 nt
	s_waitcnt vmcnt(0)
; __global__ void __launch_bounds__(256, 2) fwd_megakernel(Params p) {
;     ...
;   for (size_t blk = (size_t)bid * 256 + tid; blk < (size_t)16384 * 64; blk += (size_t)nb * 256) {
; #pragma unroll
;     for (int tb = 0; tb < 2; ++tb) {
;       const float* src = (tb ? p.peer_up : p.peer_down) + blk * 32;
;       const float sc = tb ? UP_SCALE : DOWN_SCALE;
;       v16f va, vb;
; #pragma unroll
;       for (int q = 0; q < 4; ++q) {
;         const float4 x = *(const float4*)(src + q * 8), y = *(const float4*)(src + q * 8 + 4);
;         va[q * 4] = x.x * sc; vb[q * 4] = x.y * sc; va[q * 4 + 1] = x.z * sc; vb[q * 4 + 1] = x.w * sc;
;         va[q * 4 + 2] = y.x * sc; vb[q * 4 + 2] = y.y * sc; va[q * 4 + 3] = y.z * sc; vb[q * 4 + 3] = y.w * sc;
;       }
;       const v6u o = __builtin_amdgcn_cvt_scalef32_2xpk16_fp6_f32(va, vb, 1.0f);
;       unsigned char* dst = (tb ? p.up8 : p.down8) + blk * 24;
;       *(u32x2*)dst = u32x2{o[0], o[1]}; *(u32x2*)(dst + 8) = u32x2{o[2], o[3]}; *(u32x2*)(dst + 16) = u32x2{o[4], o[5]};
;     }
	v_mul_f32_e32 v2, s16, v56
	v_mul_f32_e32 v3, s16, v58
	v_mul_f32_e32 v4, s16, v60
	v_mul_f32_e32 v5, s16, v62
	v_mul_f32_e32 v6, s16, v64
	v_mul_f32_e32 v7, s16, v66
	v_mul_f32_e32 v8, s16, v68
	v_mul_f32_e32 v9, s16, v70
	v_mul_f32_e32 v10, s16, v72
	v_mul_f32_e32 v11, s16, v74
	v_mul_f32_e32 v12, s16, v76
	v_mul_f32_e32 v13, s16, v78
	v_mul_f32_e32 v14, s16, v80
	v_mul_f32_e32 v15, s16, v82
	v_mul_f32_e32 v16, s16, v84
	v_mul_f32_e32 v17, s16, v86
	v_mul_f32_e32 v18, s16, v57
	v_mul_f32_e32 v19, s16, v59
	v_mul_f32_e32 v20, s16, v61
	v_mul_f32_e32 v21, s16, v63
	v_mul_f32_e32 v22, s16, v65
	v_mul_f32_e32 v23, s16, v67
	v_mul_f32_e32 v24, s16, v69
	v_mul_f32_e32 v25, s16, v71
	v_mul_f32_e32 v26, s16, v73
	v_mul_f32_e32 v27, s16, v75
	v_mul_f32_e32 v28, s16, v77
	v_mul_f32_e32 v29, s16, v79
	v_mul_f32_e32 v30, s16, v81
	v_mul_f32_e32 v31, s16, v83
	v_mul_f32_e32 v32, s16, v85
	v_mul_f32_e32 v33, s16, v87
	s_nop 0
	v_cvt_scalef32_2xpk16_fp6_f32 v[40:45], v[2:17], v[18:33], 1.0
	global_load_dwordx4 v[56:59], v52, s[4:5] sc0 sc1 nt
	global_load_dwordx4 v[60:63], v52, s[4:5] offset:1024 sc0 sc1 nt
	global_load_dwordx4 v[64:67], v52, s[4:5] offset:2048 sc0 sc1 nt
	global_load_dwordx4 v[68:71], v52, s[4:5] offset:3072 sc0 sc1 nt
	global_load_dwordx4 v[72:75], v54, s[4:5] sc0 sc1 nt
	global_load_dwordx4 v[76:79], v54, s[4:5] offset:1024 sc0 sc1 nt
	global_load_dwordx4 v[80:83], v54, s[4:5] offset:2048 sc0 sc1 nt
	global_load_dwordx4 v[84:87], v54, s[4:5] offset:3072 sc0 sc1 nt
	s_add_u32 s2, s2, s12
	s_addc_u32 s3, s3, 0
	s_add_u32 s4, s4, s12
	s_addc_u32 s5, s5, 0
	s_waitcnt vmcnt(0)
	v_mul_f32_e32 v2, 4.0, v56
	v_mul_f32_e32 v3, 4.0, v58
	v_mul_f32_e32 v4, 4.0, v60
	v_mul_f32_e32 v5, 4.0, v62
	v_mul_f32_e32 v6, 4.0, v64
	v_mul_f32_e32 v7, 4.0, v66
	v_mul_f32_e32 v8, 4.0, v68
	v_mul_f32_e32 v9, 4.0, v70
	v_mul_f32_e32 v10, 4.0, v72
	v_mul_f32_e32 v11, 4.0, v74
	v_mul_f32_e32 v12, 4.0, v76
	v_mul_f32_e32 v13, 4.0, v78
	v_mul_f32_e32 v14, 4.0, v80
	v_mul_f32_e32 v15, 4.0, v82
	v_mul_f32_e32 v16, 4.0, v84
	v_mul_f32_e32 v17, 4.0, v86
	v_mul_f32_e32 v18, 4.0, v57
	v_mul_f32_e32 v19, 4.0, v59
	v_mul_f32_e32 v20, 4.0, v61
	v_mul_f32_e32 v21, 4.0, v63
	v_mul_f32_e32 v22, 4.0, v65
	v_mul_f32_e32 v23, 4.0, v67
	v_mul_f32_e32 v24, 4.0, v69
	v_mul_f32_e32 v25, 4.0, v71
	v_mul_f32_e32 v26, 4.0, v73
	v_mul_f32_e32 v27, 4.0, v75
	v_mul_f32_e32 v28, 4.0, v77
	v_mul_f32_e32 v29, 4.0, v79
	v_mul_f32_e32 v30, 4.0, v81
	v_mul_f32_e32 v31, 4.0, v83
	v_mul_f32_e32 v32, 4.0, v85
	v_mul_f32_e32 v33, 4.0, v87
	s_nop 0
	v_cvt_scalef32_2xpk16_fp6_f32 v[46:51], v[2:17], v[18:33], 1.0
	global_store_dwordx4 v53, v[40:43], s[6:7]
	global_store_dwordx4 v53, v[48:51], s[6:7] offset:1024
	global_store_dwordx4 v53, v[44:47], s[6:7] offset:2048
	s_add_u32 s6, s6, s13
	s_addc_u32 s7, s7, 0
	global_load_dwordx4 v[56:59], v52, s[2:3] sc0 sc1 nt
	global_load_dwordx4 v[60:63], v52, s[2:3] offset:1024 sc0 sc1 nt
	global_load_dwordx4 v[64:67], v52, s[2:3] offset:2048 sc0 sc1 nt
	global_load_dwordx4 v[68:71], v52, s[2:3] offset:3072 sc0 sc1 nt
	global_load_dwordx4 v[72:75], v54, s[2:3] sc0 sc1 nt
	global_load_dwordx4 v[76:79], v54, s[2:3] offset:1024 sc0 sc1 nt
	global_load_dwordx4 v[80:83], v54, s[2:3] offset:2048 sc0 sc1 nt
	global_load_dwordx4 v[84:87], v54, s[2:3] offset:3072 sc0 sc1 nt
	s_waitcnt vmcnt(0)
	v_mul_f32_e32 v2, s16, v56
	v_mul_f32_e32 v3, s16, v58
	v_mul_f32_e32 v4, s16, v60
	v_mul_f32_e32 v5, s16, v62
	v_mul_f32_e32 v6, s16, v64
	v_mul_f32_e32 v7, s16, v66
	v_mul_f32_e32 v8, s16, v68
	v_mul_f32_e32 v9, s16, v70
	v_mul_f32_e32 v10, s16, v72
	v_mul_f32_e32 v11, s16, v74
	v_mul_f32_e32 v12, s16, v76
	v_mul_f32_e32 v13, s16, v78
	v_mul_f32_e32 v14, s16, v80
	v_mul_f32_e32 v15, s16, v82
	v_mul_f32_e32 v16, s16, v84
	v_mul_f32_e32 v17, s16, v86
	v_mul_f32_e32 v18, s16, v57
	v_mul_f32_e32 v19, s16, v59
	v_mul_f32_e32 v20, s16, v61
	v_mul_f32_e32 v21, s16, v63
	v_mul_f32_e32 v22, s16, v65
	v_mul_f32_e32 v23, s16, v67
	v_mul_f32_e32 v24, s16, v69
	v_mul_f32_e32 v25, s16, v71
	v_mul_f32_e32 v26, s16, v73
	v_mul_f32_e32 v27, s16, v75
	v_mul_f32_e32 v28, s16, v77
	v_mul_f32_e32 v29, s16, v79
	v_mul_f32_e32 v30, s16, v81
	v_mul_f32_e32 v31, s16, v83
	v_mul_f32_e32 v32, s16, v85
	v_mul_f32_e32 v33, s16, v87
	s_nop 0
	v_cvt_scalef32_2xpk16_fp6_f32 v[40:45], v[2:17], v[18:33], 1.0
	global_load_dwordx4 v[56:59], v52, s[4:5] sc0 sc1 nt
	global_load_dwordx4 v[60:63], v52, s[4:5] offset:1024 sc0 sc1 nt
	global_load_dwordx4 v[64:67], v52, s[4:5] offset:2048 sc0 sc1 nt
	global_load_dwordx4 v[68:71], v52, s[4:5] offset:3072 sc0 sc1 nt
	global_load_dwordx4 v[72:75], v54, s[4:5] sc0 sc1 nt
	global_load_dwordx4 v[76:79], v54, s[4:5] offset:1024 sc0 sc1 nt
	global_load_dwordx4 v[80:83], v54, s[4:5] offset:2048 sc0 sc1 nt
	global_load_dwordx4 v[84:87], v54, s[4:5] offset:3072 sc0 sc1 nt
	s_add_u32 s2, s2, s12
	s_addc_u32 s3, s3, 0
	s_add_u32 s4, s4, s12
	s_addc_u32 s5, s5, 0
	s_waitcnt vmcnt(0)
; __global__ void __launch_bounds__(256, 2) fwd_megakernel(Params p) {
;     ...
;   for (size_t blk = (size_t)bid * 256 + tid; blk < (size_t)16384 * 64; blk += (size_t)nb * 256) {
; #pragma unroll
;     for (int tb = 0; tb < 2; ++tb) {
;       const float* src = (tb ? p.peer_up : p.peer_down) + blk * 32;
;       const float sc = tb ? UP_SCALE : DOWN_SCALE;
;       v16f va, vb;
; #pragma unroll
;       for (int q = 0; q < 4; ++q) {
;         const float4 x = *(const float4*)(src + q * 8), y = *(const float4*)(src + q * 8 + 4);
;         va[q * 4] = x.x * sc; vb[q * 4] = x.y * sc; va[q * 4 + 1] = x.z * sc; vb[q * 4 + 1] = x.w * sc;
;         va[q * 4 + 2] = y.x * sc; vb[q * 4 + 2] = y.y * sc; va[q * 4 + 3] = y.z * sc; vb[q * 4 + 3] = y.w * sc;
;       }
;       const v6u o = __builtin_amdgcn_cvt_scalef32_2xpk16_fp6_f32(va, vb, 1.0f);
;       unsigned char* dst = (tb ? p.up8 : p.down8) + blk * 24;
;       *(u32x2*)dst = u32x2{o[0], o[1]}; *(u32x2*)(dst + 8) = u32x2{o[2], o[3]}; *(u32x2*)(dst + 16) = u32x2{o[4], o[5]};
;     }
	v_mul_f32_e32 v2, 4.0, v56
	v_mul_f32_e32 v3, 4.0, v58
	v_mul_f32_e32 v4, 4.0, v60
	v_mul_f32_e32 v5, 4.0, v62
	v_mul_f32_e32 v6, 4.0, v64
	v_mul_f32_e32 v7, 4.0, v66
	v_mul_f32_e32 v8, 4.0, v68
	v_mul_f32_e32 v9, 4.0, v70
	v_mul_f32_e32 v10, 4.0, v72
	v_mul_f32_e32 v11, 4.0, v74
	v_mul_f32_e32 v12, 4.0, v76
	v_mul_f32_e32 v13, 4.0, v78
	v_mul_f32_e32 v14, 4.0, v80
	v_mul_f32_e32 v15, 4.0, v82
	v_mul_f32_e32 v16, 4.0, v84
	v_mul_f32_e32 v17, 4.0, v86
	v_mul_f32_e32 v18, 4.0, v57
	v_mul_f32_e32 v19, 4.0, v59
	v_mul_f32_e32 v20, 4.0, v61
	v_mul_f32_e32 v21, 4.0, v63
	v_mul_f32_e32 v22, 4.0, v65
	v_mul_f32_e32 v23, 4.0, v67
	v_mul_f32_e32 v24, 4.0, v69
	v_mul_f32_e32 v25, 4.0, v71
	v_mul_f32_e32 v26, 4.0, v73
	v_mul_f32_e32 v27, 4.0, v75
	v_mul_f32_e32 v28, 4.0, v77
	v_mul_f32_e32 v29, 4.0, v79
	v_mul_f32_e32 v30, 4.0, v81
	v_mul_f32_e32 v31, 4.0, v83
	v_mul_f32_e32 v32, 4.0, v85
	v_mul_f32_e32 v33, 4.0, v87
	s_nop 0
	v_cvt_scalef32_2xpk16_fp6_f32 v[46:51], v[2:17], v[18:33], 1.0
	global_store_dwordx4 v53, v[40:43], s[6:7]
	global_store_dwordx4 v53, v[48:51], s[6:7] offset:1024
	global_store_dwordx4 v53, v[44:47], s[6:7] offset:2048
	s_add_u32 s6, s6, s13
	s_addc_u32 s7, s7, 0
	global_load_dwordx4 v[56:59], v52, s[2:3] sc0 sc1 nt
	global_load_dwordx4 v[60:63], v52, s[2:3] offset:1024 sc0 sc1 nt
	global_load_dwordx4 v[64:67], v52, s[2:3] offset:2048 sc0 sc1 nt
	global_load_dwordx4 v[68:71], v52, s[2:3] offset:3072 sc0 sc1 nt
	global_load_dwordx4 v[72:75], v54, s[2:3] sc0 sc1 nt
	global_load_dwordx4 v[76:79], v54, s[2:3] offset:1024 sc0 sc1 nt
	global_load_dwordx4 v[80:83], v54, s[2:3] offset:2048 sc0 sc1 nt
	global_load_dwordx4 v[84:87], v54, s[2:3] offset:3072 sc0 sc1 nt
	s_waitcnt vmcnt(0)
	v_mul_f32_e32 v2, s16, v56
	v_mul_f32_e32 v3, s16, v58
	v_mul_f32_e32 v4, s16, v60
	v_mul_f32_e32 v5, s16, v62
	v_mul_f32_e32 v6, s16, v64
	v_mul_f32_e32 v7, s16, v66
	v_mul_f32_e32 v8, s16, v68
	v_mul_f32_e32 v9, s16, v70
	v_mul_f32_e32 v10, s16, v72
	v_mul_f32_e32 v11, s16, v74
	v_mul_f32_e32 v12, s16, v76
	v_mul_f32_e32 v13, s16, v78
	v_mul_f32_e32 v14, s16, v80
	v_mul_f32_e32 v15, s16, v82
	v_mul_f32_e32 v16, s16, v84
	v_mul_f32_e32 v17, s16, v86
	v_mul_f32_e32 v18, s16, v57
	v_mul_f32_e32 v19, s16, v59
	v_mul_f32_e32 v20, s16, v61
	v_mul_f32_e32 v21, s16, v63
	v_mul_f32_e32 v22, s16, v65
	v_mul_f32_e32 v23, s16, v67
	v_mul_f32_e32 v24, s16, v69
	v_mul_f32_e32 v25, s16, v71
	v_mul_f32_e32 v26, s16, v73
	v_mul_f32_e32 v27, s16, v75
	v_mul_f32_e32 v28, s16, v77
	v_mul_f32_e32 v29, s16, v79
	v_mul_f32_e32 v30, s16, v81
	v_mul_f32_e32 v31, s16, v83
	v_mul_f32_e32 v32, s16, v85
	v_mul_f32_e32 v33, s16, v87
	s_nop 0
	v_cvt_scalef32_2xpk16_fp6_f32 v[40:45], v[2:17], v[18:33], 1.0
	global_load_dwordx4 v[56:59], v52, s[4:5] sc0 sc1 nt
	global_load_dwordx4 v[60:63], v52, s[4:5] offset:1024 sc0 sc1 nt
	global_load_dwordx4 v[64:67], v52, s[4:5] offset:2048 sc0 sc1 nt
	global_load_dwordx4 v[68:71], v52, s[4:5] offset:3072 sc0 sc1 nt
	global_load_dwordx4 v[72:75], v54, s[4:5] sc0 sc1 nt
	global_load_dwordx4 v[76:79], v54, s[4:5] offset:1024 sc0 sc1 nt
	global_load_dwordx4 v[80:83], v54, s[4:5] offset:2048 sc0 sc1 nt
	global_load_dwordx4 v[84:87], v54, s[4:5] offset:3072 sc0 sc1 nt
	s_add_u32 s2, s2, s12
	s_addc_u32 s3, s3, 0
	s_add_u32 s4, s4, s12
	s_addc_u32 s5, s5, 0
	s_waitcnt vmcnt(0)
	v_mul_f32_e32 v2, 4.0, v56
	v_mul_f32_e32 v3, 4.0, v58
	v_mul_f32_e32 v4, 4.0, v60
	v_mul_f32_e32 v5, 4.0, v62
	v_mul_f32_e32 v6, 4.0, v64
	v_mul_f32_e32 v7, 4.0, v66
	v_mul_f32_e32 v8, 4.0, v68
	v_mul_f32_e32 v9, 4.0, v70
	v_mul_f32_e32 v10, 4.0, v72
	v_mul_f32_e32 v11, 4.0, v74
	v_mul_f32_e32 v12, 4.0, v76
	v_mul_f32_e32 v13, 4.0, v78
	v_mul_f32_e32 v14, 4.0, v80
	v_mul_f32_e32 v15, 4.0, v82
	v_mul_f32_e32 v16, 4.0, v84
	v_mul_f32_e32 v17, 4.0, v86
	v_mul_f32_e32 v18, 4.0, v57
	v_mul_f32_e32 v19, 4.0, v59
	v_mul_f32_e32 v20, 4.0, v61
	v_mul_f32_e32 v21, 4.0, v63
	v_mul_f32_e32 v22, 4.0, v65
	v_mul_f32_e32 v23, 4.0, v67
	v_mul_f32_e32 v24, 4.0, v69
	v_mul_f32_e32 v25, 4.0, v71
	v_mul_f32_e32 v26, 4.0, v73
	v_mul_f32_e32 v27, 4.0, v75
	v_mul_f32_e32 v28, 4.0, v77
	v_mul_f32_e32 v29, 4.0, v79
	v_mul_f32_e32 v30, 4.0, v81
	v_mul_f32_e32 v31, 4.0, v83
	v_mul_f32_e32 v32, 4.0, v85
	v_mul_f32_e32 v33, 4.0, v87
	s_nop 0
	v_cvt_scalef32_2xpk16_fp6_f32 v[46:51], v[2:17], v[18:33], 1.0
	global_store_dwordx4 v53, v[40:43], s[6:7]
	global_store_dwordx4 v53, v[48:51], s[6:7] offset:1024
	global_store_dwordx4 v53, v[44:47], s[6:7] offset:2048
	s_add_u32 s6, s6, s13
	s_addc_u32 s7, s7, 0
	global_load_dwordx4 v[56:59], v52, s[2:3] sc0 sc1 nt
	global_load_dwordx4 v[60:63], v52, s[2:3] offset:1024 sc0 sc1 nt
	global_load_dwordx4 v[64:67], v52, s[2:3] offset:2048 sc0 sc1 nt
	global_load_dwordx4 v[68:71], v52, s[2:3] offset:3072 sc0 sc1 nt
	global_load_dwordx4 v[72:75], v54, s[2:3] sc0 sc1 nt
	global_load_dwordx4 v[76:79], v54, s[2:3] offset:1024 sc0 sc1 nt
	global_load_dwordx4 v[80:83], v54, s[2:3] offset:2048 sc0 sc1 nt
	global_load_dwordx4 v[84:87], v54, s[2:3] offset:3072 sc0 sc1 nt
	s_waitcnt vmcnt(0)
; __global__ void __launch_bounds__(256, 2) fwd_megakernel(Params p) {
;     ...
;   for (size_t blk = (size_t)bid * 256 + tid; blk < (size_t)16384 * 64; blk += (size_t)nb * 256) {
; #pragma unroll
;     for (int tb = 0; tb < 2; ++tb) {
;       const float* src = (tb ? p.peer_up : p.peer_down) + blk * 32;
;       const float sc = tb ? UP_SCALE : DOWN_SCALE;
;       v16f va, vb;
; #pragma unroll
;       for (int q = 0; q < 4; ++q) {
;         const float4 x = *(const float4*)(src + q * 8), y = *(const float4*)(src + q * 8 + 4);
;         va[q * 4] = x.x * sc; vb[q * 4] = x.y * sc; va[q * 4 + 1] = x.z * sc; vb[q * 4 + 1] = x.w * sc;
;         va[q * 4 + 2] = y.x * sc; vb[q * 4 + 2] = y.y * sc; va[q * 4 + 3] = y.z * sc; vb[q * 4 + 3] = y.w * sc;
;       }
;       const v6u o = __builtin_amdgcn_cvt_scalef32_2xpk16_fp6_f32(va, vb, 1.0f);
;       unsigned char* dst = (tb ? p.up8 : p.down8) + blk * 24;
;       *(u32x2*)dst = u32x2{o[0], o[1]}; *(u32x2*)(dst + 8) = u32x2{o[2], o[3]}; *(u32x2*)(dst + 16) = u32x2{o[4], o[5]};
;     }
	v_mul_f32_e32 v2, s16, v56
	v_mul_f32_e32 v3, s16, v58
	v_mul_f32_e32 v4, s16, v60
	v_mul_f32_e32 v5, s16, v62
	v_mul_f32_e32 v6, s16, v64
	v_mul_f32_e32 v7, s16, v66
	v_mul_f32_e32 v8, s16, v68
	v_mul_f32_e32 v9, s16, v70
	v_mul_f32_e32 v10, s16, v72
	v_mul_f32_e32 v11, s16, v74
	v_mul_f32_e32 v12, s16, v76
	v_mul_f32_e32 v13, s16, v78
	v_mul_f32_e32 v14, s16, v80
	v_mul_f32_e32 v15, s16, v82
	v_mul_f32_e32 v16, s16, v84
	v_mul_f32_e32 v17, s16, v86
	v_mul_f32_e32 v18, s16, v57
	v_mul_f32_e32 v19, s16, v59
	v_mul_f32_e32 v20, s16, v61
	v_mul_f32_e32 v21, s16, v63
	v_mul_f32_e32 v22, s16, v65
	v_mul_f32_e32 v23, s16, v67
	v_mul_f32_e32 v24, s16, v69
	v_mul_f32_e32 v25, s16, v71
	v_mul_f32_e32 v26, s16, v73
	v_mul_f32_e32 v27, s16, v75
	v_mul_f32_e32 v28, s16, v77
	v_mul_f32_e32 v29, s16, v79
	v_mul_f32_e32 v30, s16, v81
	v_mul_f32_e32 v31, s16, v83
	v_mul_f32_e32 v32, s16, v85
	v_mul_f32_e32 v33, s16, v87
	s_nop 0
	v_cvt_scalef32_2xpk16_fp6_f32 v[40:45], v[2:17], v[18:33], 1.0
	global_load_dwordx4 v[56:59], v52, s[4:5] sc0 sc1 nt
	global_load_dwordx4 v[60:63], v52, s[4:5] offset:1024 sc0 sc1 nt
	global_load_dwordx4 v[64:67], v52, s[4:5] offset:2048 sc0 sc1 nt
	global_load_dwordx4 v[68:71], v52, s[4:5] offset:3072 sc0 sc1 nt
	global_load_dwordx4 v[72:75], v54, s[4:5] sc0 sc1 nt
	global_load_dwordx4 v[76:79], v54, s[4:5] offset:1024 sc0 sc1 nt
	global_load_dwordx4 v[80:83], v54, s[4:5] offset:2048 sc0 sc1 nt
	global_load_dwordx4 v[84:87], v54, s[4:5] offset:3072 sc0 sc1 nt
	s_add_u32 s2, s2, s12
	s_addc_u32 s3, s3, 0
	s_add_u32 s4, s4, s12
	s_addc_u32 s5, s5, 0
	s_waitcnt vmcnt(0)
	v_mul_f32_e32 v2, 4.0, v56
	v_mul_f32_e32 v3, 4.0, v58
	v_mul_f32_e32 v4, 4.0, v60
	v_mul_f32_e32 v5, 4.0, v62
	v_mul_f32_e32 v6, 4.0, v64
	v_mul_f32_e32 v7, 4.0, v66
	v_mul_f32_e32 v8, 4.0, v68
	v_mul_f32_e32 v9, 4.0, v70
	v_mul_f32_e32 v10, 4.0, v72
	v_mul_f32_e32 v11, 4.0, v74
	v_mul_f32_e32 v12, 4.0, v76
	v_mul_f32_e32 v13, 4.0, v78
	v_mul_f32_e32 v14, 4.0, v80
	v_mul_f32_e32 v15, 4.0, v82
	v_mul_f32_e32 v16, 4.0, v84
	v_mul_f32_e32 v17, 4.0, v86
	v_mul_f32_e32 v18, 4.0, v57
	v_mul_f32_e32 v19, 4.0, v59
	v_mul_f32_e32 v20, 4.0, v61
	v_mul_f32_e32 v21, 4.0, v63
	v_mul_f32_e32 v22, 4.0, v65
	v_mul_f32_e32 v23, 4.0, v67
	v_mul_f32_e32 v24, 4.0, v69
	v_mul_f32_e32 v25, 4.0, v71
	v_mul_f32_e32 v26, 4.0, v73
	v_mul_f32_e32 v27, 4.0, v75
	v_mul_f32_e32 v28, 4.0, v77
	v_mul_f32_e32 v29, 4.0, v79
	v_mul_f32_e32 v30, 4.0, v81
	v_mul_f32_e32 v31, 4.0, v83
	v_mul_f32_e32 v32, 4.0, v85
	v_mul_f32_e32 v33, 4.0, v87
	s_nop 0
	v_cvt_scalef32_2xpk16_fp6_f32 v[46:51], v[2:17], v[18:33], 1.0
	global_store_dwordx4 v53, v[40:43], s[6:7]
	global_store_dwordx4 v53, v[48:51], s[6:7] offset:1024
	global_store_dwordx4 v53, v[44:47], s[6:7] offset:2048
	s_add_u32 s6, s6, s13
	s_addc_u32 s7, s7, 0
	global_load_dwordx4 v[56:59], v52, s[2:3] sc0 sc1 nt
	global_load_dwordx4 v[60:63], v52, s[2:3] offset:1024 sc0 sc1 nt
	global_load_dwordx4 v[64:67], v52, s[2:3] offset:2048 sc0 sc1 nt
	global_load_dwordx4 v[68:71], v52, s[2:3] offset:3072 sc0 sc1 nt
	global_load_dwordx4 v[72:75], v54, s[2:3] sc0 sc1 nt
	global_load_dwordx4 v[76:79], v54, s[2:3] offset:1024 sc0 sc1 nt
	global_load_dwordx4 v[80:83], v54, s[2:3] offset:2048 sc0 sc1 nt
	global_load_dwordx4 v[84:87], v54, s[2:3] offset:3072 sc0 sc1 nt
	s_waitcnt vmcnt(0)
	v_mul_f32_e32 v2, s16, v56
	v_mul_f32_e32 v3, s16, v58
	v_mul_f32_e32 v4, s16, v60
	v_mul_f32_e32 v5, s16, v62
	v_mul_f32_e32 v6, s16, v64
	v_mul_f32_e32 v7, s16, v66
	v_mul_f32_e32 v8, s16, v68
	v_mul_f32_e32 v9, s16, v70
	v_mul_f32_e32 v10, s16, v72
	v_mul_f32_e32 v11, s16, v74
	v_mul_f32_e32 v12, s16, v76
	v_mul_f32_e32 v13, s16, v78
	v_mul_f32_e32 v14, s16, v80
	v_mul_f32_e32 v15, s16, v82
	v_mul_f32_e32 v16, s16, v84
	v_mul_f32_e32 v17, s16, v86
	v_mul_f32_e32 v18, s16, v57
	v_mul_f32_e32 v19, s16, v59
	v_mul_f32_e32 v20, s16, v61
	v_mul_f32_e32 v21, s16, v63
	v_mul_f32_e32 v22, s16, v65
	v_mul_f32_e32 v23, s16, v67
	v_mul_f32_e32 v24, s16, v69
	v_mul_f32_e32 v25, s16, v71
	v_mul_f32_e32 v26, s16, v73
	v_mul_f32_e32 v27, s16, v75
	v_mul_f32_e32 v28, s16, v77
	v_mul_f32_e32 v29, s16, v79
	v_mul_f32_e32 v30, s16, v81
	v_mul_f32_e32 v31, s16, v83
	v_mul_f32_e32 v32, s16, v85
	v_mul_f32_e32 v33, s16, v87
	s_nop 0
	v_cvt_scalef32_2xpk16_fp6_f32 v[40:45], v[2:17], v[18:33], 1.0
	global_load_dwordx4 v[56:59], v52, s[4:5] sc0 sc1 nt
	global_load_dwordx4 v[60:63], v52, s[4:5] offset:1024 sc0 sc1 nt
	global_load_dwordx4 v[64:67], v52, s[4:5] offset:2048 sc0 sc1 nt
	global_load_dwordx4 v[68:71], v52, s[4:5] offset:3072 sc0 sc1 nt
	global_load_dwordx4 v[72:75], v54, s[4:5] sc0 sc1 nt
	global_load_dwordx4 v[76:79], v54, s[4:5] offset:1024 sc0 sc1 nt
	global_load_dwordx4 v[80:83], v54, s[4:5] offset:2048 sc0 sc1 nt
	global_load_dwordx4 v[84:87], v54, s[4:5] offset:3072 sc0 sc1 nt
	s_waitcnt vmcnt(0)
	v_mul_f32_e32 v2, 4.0, v56
	v_mul_f32_e32 v3, 4.0, v58
	v_mul_f32_e32 v4, 4.0, v60
	v_mul_f32_e32 v5, 4.0, v62
	v_mul_f32_e32 v6, 4.0, v64
	v_mul_f32_e32 v7, 4.0, v66
	v_mul_f32_e32 v8, 4.0, v68
	v_mul_f32_e32 v9, 4.0, v70
	v_mul_f32_e32 v10, 4.0, v72
	v_mul_f32_e32 v11, 4.0, v74
	v_mul_f32_e32 v12, 4.0, v76
	v_mul_f32_e32 v13, 4.0, v78
	v_mul_f32_e32 v14, 4.0, v80
	v_mul_f32_e32 v15, 4.0, v82
	v_mul_f32_e32 v16, 4.0, v84
	v_mul_f32_e32 v17, 4.0, v86
	v_mul_f32_e32 v18, 4.0, v57
	v_mul_f32_e32 v19, 4.0, v59
	v_mul_f32_e32 v20, 4.0, v61
	v_mul_f32_e32 v21, 4.0, v63
	v_mul_f32_e32 v22, 4.0, v65
	v_mul_f32_e32 v23, 4.0, v67
	v_mul_f32_e32 v24, 4.0, v69
	v_mul_f32_e32 v25, 4.0, v71
	v_mul_f32_e32 v26, 4.0, v73
	v_mul_f32_e32 v27, 4.0, v75
	v_mul_f32_e32 v28, 4.0, v77
	v_mul_f32_e32 v29, 4.0, v79
	v_mul_f32_e32 v30, 4.0, v81
	v_mul_f32_e32 v31, 4.0, v83
	v_mul_f32_e32 v32, 4.0, v85
	v_mul_f32_e32 v33, 4.0, v87
	s_nop 0
	v_cvt_scalef32_2xpk16_fp6_f32 v[46:51], v[2:17], v[18:33], 1.0
	global_store_dwordx4 v53, v[40:43], s[6:7]
	global_store_dwordx4 v53, v[48:51], s[6:7] offset:1024
	global_store_dwordx4 v53, v[44:47], s[6:7] offset:2048
	s_add_u32 s6, s6, s13
	s_addc_u32 s7, s7, 0
	s_branch .Lenc_end_b

; DEV int ltid() { int t = threadIdx.x; asm volatile("" : "+v"(t)); return t; }
; DEV float bflo(unsigned u) { return __uint_as_float(u << 16); }
; DEV float bfhi(unsigned u) { return __uint_as_float(u & 0xffff0000u); }
; DEV void peer_gather_token(const Params& p, int tok) {
;   const int lane = ltid() & 63, b = tok >> 11;
;   float hx[32], acc[32];
;   {
;     const u16* hr = p.h + (size_t)tok * 2048 + lane * 32;
; #pragma unroll
;     for (int q = 0; q < 4; ++q) {
;       u32x4 v = *(const u32x4*)(hr + q * 8);
; #pragma unroll
;       for (int e = 0; e < 4; ++e) { hx[q * 8 + 2 * e] = bflo(v[e]); hx[q * 8 + 2 * e + 1] = bfhi(v[e]); }
;     }
;   }
; #pragma unroll
;   for (int e = 0; e < 32; ++e) acc[e] = 0.f;
;   const int e0 = p.eidx[(size_t)tok * 128 + lane], e1 = p.eidx[(size_t)tok * 128 + 64 + lane];
;   const int g0 = __builtin_bit_cast(int, p.gw[(size_t)tok * 128 + lane]), g1 = __builtin_bit_cast(int, p.gw[(size_t)tok * 128 + 64 + lane]);
;   u32x2 dn[4][3], up[4][3];
;   auto issue = [&](int k, int slot) {
;     const int e = (k < 64) ? __builtin_amdgcn_readlane(e0, k) : __builtin_amdgcn_readlane(e1, k - 64);
;     const unsigned char* dr = p.down8 + (size_t)e * ROW6 + lane * 24;
;     const unsigned char* ur = p.up8 + (size_t)e * ROW6 + lane * 24;
; #pragma unroll
;     for (int i = 0; i < 3; ++i) { dn[slot][i] = *(const u32x2*)(dr + i * 8); up[slot][i] = *(const u32x2*)(ur + i * 8); }
;   };
;   issue(0, 0); issue(1, 1); issue(2, 2);
.LBB0_1567:
	s_or_b64 exec, exec, s[0:1]
	s_waitcnt lgkmcnt(0)
	s_barrier
	s_mov_b64 exec, -1
	v_lshrrev_b32_e32 v2, 6, v0
	v_and_b32_e32 v3, 63, v0
	s_nop 0
	v_readfirstlane_b32 s38, v2
	s_add_i32 s20, s84, s38
	s_mov_b32 s90, s38
	s_lshl_b32 s21, s92, 2
	s_cmpk_lt_u32 s20, 0x4000
	s_cbranch_scc0 .Lp12_end
	v_lshlrev_b32_e32 v1, 4, v3
	v_lshlrev_b32_e32 v242, 2, v3
	v_lshlrev_b32_e32 v243, 3, v3
	v_lshlrev_b32_e32 v244, 4, v3
	v_add_u32_e32 v245, 0x1000, v244
	v_lshrrev_b32_e32 v2, 3, v3
	v_and_b32_e32 v246, 7, v3
	v_lshlrev_b32_e32 v2, 20, v2
	v_lshl_or_b32 v246, v246, 3, v2
	v_add_u32_e32 v247, 0x800000, v246
	v_add_u32_e32 v248, 0x1000000, v246
	v_add_u32_e32 v249, 0x1800000, v246
	v_add_u32_e32 v250, 0x2000000, v246
	v_add_u32_e32 v251, 0x2800000, v246
	v_add_u32_e32 v252, 0x3000000, v246
	v_add_u32_e32 v253, 0x3800000, v246
	v_mov_b32_e32 v212, 0x3c800000
	v_mov_b32_e32 v213, 0x3ba10414
	v_mov_b32_e32 v214, 0xb9c68948
	v_mov_b32_e32 v215, 0x7f800000
	v_mov_b32_e32 v207, 0
	s_mov_b32 s9, 0x378e98ab
	s_mov_b32 s10, 0x3b7cd369
	s_mov_b32 s11, 0xbcc618b2
	s_mov_b32 s12, 0x3dda74e4
	s_mov_b32 s13, 0x3f228afd
	s_mov_b32 s14, 0x3e03c728
	s_mov_b32 s15, 0xbfb8aa3b
	s_mov_b32 s16, 0x42ce8ed0
	s_mov_b32 s17, 0xc2b17218
	s_brev_b32 s18, -2
	s_mov_b32 s43, 1
	s_mov_b32 s19, 0
	s_lshl_b32 s38, s20, 9
	s_add_u32 s58, s66, s38
	s_addc_u32 s59, s67, 0
	global_load_dword v216, v242, s[58:59]
	global_load_dword v217, v242, s[58:59] offset:256
	s_add_u32 s58, s68, s38
	s_addc_u32 s59, s69, 0
	global_load_dword v218, v242, s[58:59]
	global_load_dword v219, v242, s[58:59] offset:256
	s_lshl_b32 s38, s20, 6
	s_add_u32 s58, s80, s38
	s_addc_u32 s59, s81, 0
	global_load_dwordx2 v[220:221], v246, s[58:59]
	global_load_dwordx2 v[222:223], v247, s[58:59]
	global_load_dwordx2 v[224:225], v248, s[58:59]
	global_load_dwordx2 v[226:227], v249, s[58:59]
	global_load_dwordx2 v[228:229], v250, s[58:59]
	global_load_dwordx2 v[230:231], v251, s[58:59]
	global_load_dwordx2 v[232:233], v252, s[58:59]
	global_load_dwordx2 v[234:235], v253, s[58:59]
	s_waitcnt vmcnt(0) lgkmcnt(0)
	s_mov_b32 s36, 0
	s_mov_b32 s37, 0
	v_and_b32_e32 v236, 63, v0
	v_lshrrev_b32_e32 v241, 6, v0
	v_lshl_or_b32 v237, v216, 7, v236
	v_or_b32_e32 v238, 64, v236
	v_lshl_or_b32 v238, v217, 7, v238
	v_mov_b32_e32 v239, 0
	v_mov_b32_e32 v240, 0
	v_lshlrev_b32_e32 v241, 10, v241
	v_lshl_add_u32 v241, v236, 2, v241
	v_readlane_b32 s46, v237, 0
	v_readlane_b32 s47, v238, 0
	s_nop 1
	v_cmp_lt_u32_e64 s[48:49], s46, v237
	v_cmp_lt_u32_e64 s[50:51], s46, v238
	v_cmp_lt_u32_e64 s[52:53], s47, v237
	v_cmp_lt_u32_e64 s[54:55], s47, v238
	v_readlane_b32 s46, v237, 1
	v_readlane_b32 s47, v238, 1
	v_addc_co_u32_e64 v239, s[56:57], 0, v239, s[48:49]
	v_addc_co_u32_e64 v240, s[56:57], 0, v240, s[50:51]
	v_addc_co_u32_e64 v239, s[56:57], 0, v239, s[52:53]
	v_addc_co_u32_e64 v240, s[56:57], 0, v240, s[54:55]
	v_cmp_lt_u32_e64 s[48:49], s46, v237
	v_cmp_lt_u32_e64 s[50:51], s46, v238
	v_cmp_lt_u32_e64 s[52:53], s47, v237
	v_cmp_lt_u32_e64 s[54:55], s47, v238
	v_readlane_b32 s46, v237, 2
	v_readlane_b32 s47, v238, 2
	v_addc_co_u32_e64 v239, s[56:57], 0, v239, s[48:49]
	v_addc_co_u32_e64 v240, s[56:57], 0, v240, s[50:51]
	v_addc_co_u32_e64 v239, s[56:57], 0, v239, s[52:53]
	v_addc_co_u32_e64 v240, s[56:57], 0, v240, s[54:55]
	v_cmp_lt_u32_e64 s[48:49], s46, v237
	v_cmp_lt_u32_e64 s[50:51], s46, v238
	v_cmp_lt_u32_e64 s[52:53], s47, v237
	v_cmp_lt_u32_e64 s[54:55], s47, v238
	v_readlane_b32 s46, v237, 3
	v_readlane_b32 s47, v238, 3
	v_addc_co_u32_e64 v239, s[56:57], 0, v239, s[48:49]
	v_addc_co_u32_e64 v240, s[56:57], 0, v240, s[50:51]
	v_addc_co_u32_e64 v239, s[56:57], 0, v239, s[52:53]
	v_addc_co_u32_e64 v240, s[56:57], 0, v240, s[54:55]
	v_cmp_lt_u32_e64 s[48:49], s46, v237
	v_cmp_lt_u32_e64 s[50:51], s46, v238
	v_cmp_lt_u32_e64 s[52:53], s47, v237
	v_cmp_lt_u32_e64 s[54:55], s47, v238
	v_readlane_b32 s46, v237, 4
	v_readlane_b32 s47, v238, 4
	v_addc_co_u32_e64 v239, s[56:57], 0, v239, s[48:49]
	v_addc_co_u32_e64 v240, s[56:57], 0, v240, s[50:51]
	v_addc_co_u32_e64 v239, s[56:57], 0, v239, s[52:53]
	v_addc_co_u32_e64 v240, s[56:57], 0, v240, s[54:55]
	v_cmp_lt_u32_e64 s[48:49], s46, v237
	v_cmp_lt_u32_e64 s[50:51], s46, v238
	v_cmp_lt_u32_e64 s[52:53], s47, v237
	v_cmp_lt_u32_e64 s[54:55], s47, v238
	v_readlane_b32 s46, v237, 5
	v_readlane_b32 s47, v238, 5
	v_addc_co_u32_e64 v239, s[56:57], 0, v239, s[48:49]
	v_addc_co_u32_e64 v240, s[56:57], 0, v240, s[50:51]
	v_addc_co_u32_e64 v239, s[56:57], 0, v239, s[52:53]
	v_addc_co_u32_e64 v240, s[56:57], 0, v240, s[54:55]
	v_cmp_lt_u32_e64 s[48:49], s46, v237
	v_cmp_lt_u32_e64 s[50:51], s46, v238
	v_cmp_lt_u32_e64 s[52:53], s47, v237
	v_cmp_lt_u32_e64 s[54:55], s47, v238
	v_readlane_b32 s46, v237, 6
	v_readlane_b32 s47, v238, 6
	v_addc_co_u32_e64 v239, s[56:57], 0, v239, s[48:49]
	v_addc_co_u32_e64 v240, s[56:57], 0, v240, s[50:51]
	v_addc_co_u32_e64 v239, s[56:57], 0, v239, s[52:53]
	v_addc_co_u32_e64 v240, s[56:57], 0, v240, s[54:55]
	v_cmp_lt_u32_e64 s[48:49], s46, v237
	v_cmp_lt_u32_e64 s[50:51], s46, v238
	v_cmp_lt_u32_e64 s[52:53], s47, v237
	v_cmp_lt_u32_e64 s[54:55], s47, v238
	v_readlane_b32 s46, v237, 7
	v_readlane_b32 s47, v238, 7
	v_addc_co_u32_e64 v239, s[56:57], 0, v239, s[48:49]
	v_addc_co_u32_e64 v240, s[56:57], 0, v240, s[50:51]
	v_addc_co_u32_e64 v239, s[56:57], 0, v239, s[52:53]
	v_addc_co_u32_e64 v240, s[56:57], 0, v240, s[54:55]
	v_cmp_lt_u32_e64 s[48:49], s46, v237
	v_cmp_lt_u32_e64 s[50:51], s46, v238
	v_cmp_lt_u32_e64 s[52:53], s47, v237
	v_cmp_lt_u32_e64 s[54:55], s47, v238
	v_readlane_b32 s46, v237, 8
	v_readlane_b32 s47, v238, 8
; DEV void peer_gather_token(const Params& p, int tok) {
;     ...
;   const int e0 = p.eidx[(size_t)tok * 128 + lane], e1 = p.eidx[(size_t)tok * 128 + 64 + lane];
;   const int g0 = __builtin_bit_cast(int, p.gw[(size_t)tok * 128 + lane]), g1 = __builtin_bit_cast(int, p.gw[(size_t)tok * 128 + 64 + lane]);
;   u32x2 dn[4][3], up[4][3];
;   auto issue = [&](int k, int slot) {
;     const int e = (k < 64) ? __builtin_amdgcn_readlane(e0, k) : __builtin_amdgcn_readlane(e1, k - 64);
;     const unsigned char* dr = p.down8 + (size_t)e * ROW6 + lane * 24;
;     const unsigned char* ur = p.up8 + (size_t)e * ROW6 + lane * 24;
; #pragma unroll
;     for (int i = 0; i < 3; ++i) { dn[slot][i] = *(const u32x2*)(dr + i * 8); up[slot][i] = *(const u32x2*)(ur + i * 8); }
;   };
;   issue(0, 0); issue(1, 1); issue(2, 2);
	v_addc_co_u32_e64 v239, s[56:57], 0, v239, s[48:49]
	v_addc_co_u32_e64 v240, s[56:57], 0, v240, s[50:51]
	v_addc_co_u32_e64 v239, s[56:57], 0, v239, s[52:53]
	v_addc_co_u32_e64 v240, s[56:57], 0, v240, s[54:55]
	v_cmp_lt_u32_e64 s[48:49], s46, v237
	v_cmp_lt_u32_e64 s[50:51], s46, v238
	v_cmp_lt_u32_e64 s[52:53], s47, v237
	v_cmp_lt_u32_e64 s[54:55], s47, v238
	v_readlane_b32 s46, v237, 9
	v_readlane_b32 s47, v238, 9
	v_addc_co_u32_e64 v239, s[56:57], 0, v239, s[48:49]
	v_addc_co_u32_e64 v240, s[56:57], 0, v240, s[50:51]
	v_addc_co_u32_e64 v239, s[56:57], 0, v239, s[52:53]
	v_addc_co_u32_e64 v240, s[56:57], 0, v240, s[54:55]
	v_cmp_lt_u32_e64 s[48:49], s46, v237
	v_cmp_lt_u32_e64 s[50:51], s46, v238
	v_cmp_lt_u32_e64 s[52:53], s47, v237
	v_cmp_lt_u32_e64 s[54:55], s47, v238
	v_readlane_b32 s46, v237, 10
	v_readlane_b32 s47, v238, 10
	v_addc_co_u32_e64 v239, s[56:57], 0, v239, s[48:49]
	v_addc_co_u32_e64 v240, s[56:57], 0, v240, s[50:51]
	v_addc_co_u32_e64 v239, s[56:57], 0, v239, s[52:53]
	v_addc_co_u32_e64 v240, s[56:57], 0, v240, s[54:55]
	v_cmp_lt_u32_e64 s[48:49], s46, v237
	v_cmp_lt_u32_e64 s[50:51], s46, v238
	v_cmp_lt_u32_e64 s[52:53], s47, v237
	v_cmp_lt_u32_e64 s[54:55], s47, v238
	v_readlane_b32 s46, v237, 11
	v_readlane_b32 s47, v238, 11
	v_addc_co_u32_e64 v239, s[56:57], 0, v239, s[48:49]
	v_addc_co_u32_e64 v240, s[56:57], 0, v240, s[50:51]
	v_addc_co_u32_e64 v239, s[56:57], 0, v239, s[52:53]
	v_addc_co_u32_e64 v240, s[56:57], 0, v240, s[54:55]
	v_cmp_lt_u32_e64 s[48:49], s46, v237
	v_cmp_lt_u32_e64 s[50:51], s46, v238
	v_cmp_lt_u32_e64 s[52:53], s47, v237
	v_cmp_lt_u32_e64 s[54:55], s47, v238
	v_readlane_b32 s46, v237, 12
	v_readlane_b32 s47, v238, 12
	v_addc_co_u32_e64 v239, s[56:57], 0, v239, s[48:49]
	v_addc_co_u32_e64 v240, s[56:57], 0, v240, s[50:51]
	v_addc_co_u32_e64 v239, s[56:57], 0, v239, s[52:53]
	v_addc_co_u32_e64 v240, s[56:57], 0, v240, s[54:55]
	v_cmp_lt_u32_e64 s[48:49], s46, v237
	v_cmp_lt_u32_e64 s[50:51], s46, v238
	v_cmp_lt_u32_e64 s[52:53], s47, v237
	v_cmp_lt_u32_e64 s[54:55], s47, v238
	v_readlane_b32 s46, v237, 13
	v_readlane_b32 s47, v238, 13
	v_addc_co_u32_e64 v239, s[56:57], 0, v239, s[48:49]
	v_addc_co_u32_e64 v240, s[56:57], 0, v240, s[50:51]
	v_addc_co_u32_e64 v239, s[56:57], 0, v239, s[52:53]
	v_addc_co_u32_e64 v240, s[56:57], 0, v240, s[54:55]
	v_cmp_lt_u32_e64 s[48:49], s46, v237
	v_cmp_lt_u32_e64 s[50:51], s46, v238
	v_cmp_lt_u32_e64 s[52:53], s47, v237
	v_cmp_lt_u32_e64 s[54:55], s47, v238
	v_readlane_b32 s46, v237, 14
	v_readlane_b32 s47, v238, 14
	v_addc_co_u32_e64 v239, s[56:57], 0, v239, s[48:49]
	v_addc_co_u32_e64 v240, s[56:57], 0, v240, s[50:51]
	v_addc_co_u32_e64 v239, s[56:57], 0, v239, s[52:53]
	v_addc_co_u32_e64 v240, s[56:57], 0, v240, s[54:55]
	v_cmp_lt_u32_e64 s[48:49], s46, v237
	v_cmp_lt_u32_e64 s[50:51], s46, v238
	v_cmp_lt_u32_e64 s[52:53], s47, v237
	v_cmp_lt_u32_e64 s[54:55], s47, v238
	v_readlane_b32 s46, v237, 15
	v_readlane_b32 s47, v238, 15
	v_addc_co_u32_e64 v239, s[56:57], 0, v239, s[48:49]
	v_addc_co_u32_e64 v240, s[56:57], 0, v240, s[50:51]
	v_addc_co_u32_e64 v239, s[56:57], 0, v239, s[52:53]
	v_addc_co_u32_e64 v240, s[56:57], 0, v240, s[54:55]
	v_cmp_lt_u32_e64 s[48:49], s46, v237
	v_cmp_lt_u32_e64 s[50:51], s46, v238
	v_cmp_lt_u32_e64 s[52:53], s47, v237
	v_cmp_lt_u32_e64 s[54:55], s47, v238
	v_readlane_b32 s46, v237, 16
	v_readlane_b32 s47, v238, 16
	v_addc_co_u32_e64 v239, s[56:57], 0, v239, s[48:49]
	v_addc_co_u32_e64 v240, s[56:57], 0, v240, s[50:51]
	v_addc_co_u32_e64 v239, s[56:57], 0, v239, s[52:53]
	v_addc_co_u32_e64 v240, s[56:57], 0, v240, s[54:55]
	v_cmp_lt_u32_e64 s[48:49], s46, v237
	v_cmp_lt_u32_e64 s[50:51], s46, v238
	v_cmp_lt_u32_e64 s[52:53], s47, v237
	v_cmp_lt_u32_e64 s[54:55], s47, v238
	v_readlane_b32 s46, v237, 17
	v_readlane_b32 s47, v238, 17
	v_addc_co_u32_e64 v239, s[56:57], 0, v239, s[48:49]
	v_addc_co_u32_e64 v240, s[56:57], 0, v240, s[50:51]
	v_addc_co_u32_e64 v239, s[56:57], 0, v239, s[52:53]
	v_addc_co_u32_e64 v240, s[56:57], 0, v240, s[54:55]
	v_cmp_lt_u32_e64 s[48:49], s46, v237
	v_cmp_lt_u32_e64 s[50:51], s46, v238
	v_cmp_lt_u32_e64 s[52:53], s47, v237
	v_cmp_lt_u32_e64 s[54:55], s47, v238
	v_readlane_b32 s46, v237, 18
	v_readlane_b32 s47, v238, 18
	v_addc_co_u32_e64 v239, s[56:57], 0, v239, s[48:49]
	v_addc_co_u32_e64 v240, s[56:57], 0, v240, s[50:51]
	v_addc_co_u32_e64 v239, s[56:57], 0, v239, s[52:53]
	v_addc_co_u32_e64 v240, s[56:57], 0, v240, s[54:55]
	v_cmp_lt_u32_e64 s[48:49], s46, v237
	v_cmp_lt_u32_e64 s[50:51], s46, v238
	v_cmp_lt_u32_e64 s[52:53], s47, v237
	v_cmp_lt_u32_e64 s[54:55], s47, v238
	v_readlane_b32 s46, v237, 19
	v_readlane_b32 s47, v238, 19
	v_addc_co_u32_e64 v239, s[56:57], 0, v239, s[48:49]
	v_addc_co_u32_e64 v240, s[56:57], 0, v240, s[50:51]
	v_addc_co_u32_e64 v239, s[56:57], 0, v239, s[52:53]
	v_addc_co_u32_e64 v240, s[56:57], 0, v240, s[54:55]
	v_cmp_lt_u32_e64 s[48:49], s46, v237
	v_cmp_lt_u32_e64 s[50:51], s46, v238
	v_cmp_lt_u32_e64 s[52:53], s47, v237
	v_cmp_lt_u32_e64 s[54:55], s47, v238
	v_readlane_b32 s46, v237, 20
	v_readlane_b32 s47, v238, 20
	v_addc_co_u32_e64 v239, s[56:57], 0, v239, s[48:49]
	v_addc_co_u32_e64 v240, s[56:57], 0, v240, s[50:51]
	v_addc_co_u32_e64 v239, s[56:57], 0, v239, s[52:53]
	v_addc_co_u32_e64 v240, s[56:57], 0, v240, s[54:55]
	v_cmp_lt_u32_e64 s[48:49], s46, v237
	v_cmp_lt_u32_e64 s[50:51], s46, v238
	v_cmp_lt_u32_e64 s[52:53], s47, v237
	v_cmp_lt_u32_e64 s[54:55], s47, v238
	v_readlane_b32 s46, v237, 21
	v_readlane_b32 s47, v238, 21
	v_addc_co_u32_e64 v239, s[56:57], 0, v239, s[48:49]
	v_addc_co_u32_e64 v240, s[56:57], 0, v240, s[50:51]
; DEV void peer_gather_token(const Params& p, int tok) {
;     ...
;   const int e0 = p.eidx[(size_t)tok * 128 + lane], e1 = p.eidx[(size_t)tok * 128 + 64 + lane];
;   const int g0 = __builtin_bit_cast(int, p.gw[(size_t)tok * 128 + lane]), g1 = __builtin_bit_cast(int, p.gw[(size_t)tok * 128 + 64 + lane]);
;   u32x2 dn[4][3], up[4][3];
;   auto issue = [&](int k, int slot) {
;     const int e = (k < 64) ? __builtin_amdgcn_readlane(e0, k) : __builtin_amdgcn_readlane(e1, k - 64);
;     const unsigned char* dr = p.down8 + (size_t)e * ROW6 + lane * 24;
;     const unsigned char* ur = p.up8 + (size_t)e * ROW6 + lane * 24;
; #pragma unroll
;     for (int i = 0; i < 3; ++i) { dn[slot][i] = *(const u32x2*)(dr + i * 8); up[slot][i] = *(const u32x2*)(ur + i * 8); }
;   };
;   issue(0, 0); issue(1, 1); issue(2, 2);
	v_addc_co_u32_e64 v239, s[56:57], 0, v239, s[52:53]
	v_addc_co_u32_e64 v240, s[56:57], 0, v240, s[54:55]
	v_cmp_lt_u32_e64 s[48:49], s46, v237
	v_cmp_lt_u32_e64 s[50:51], s46, v238
	v_cmp_lt_u32_e64 s[52:53], s47, v237
	v_cmp_lt_u32_e64 s[54:55], s47, v238
	v_readlane_b32 s46, v237, 22
	v_readlane_b32 s47, v238, 22
	v_addc_co_u32_e64 v239, s[56:57], 0, v239, s[48:49]
	v_addc_co_u32_e64 v240, s[56:57], 0, v240, s[50:51]
	v_addc_co_u32_e64 v239, s[56:57], 0, v239, s[52:53]
	v_addc_co_u32_e64 v240, s[56:57], 0, v240, s[54:55]
	v_cmp_lt_u32_e64 s[48:49], s46, v237
	v_cmp_lt_u32_e64 s[50:51], s46, v238
	v_cmp_lt_u32_e64 s[52:53], s47, v237
	v_cmp_lt_u32_e64 s[54:55], s47, v238
	v_readlane_b32 s46, v237, 23
	v_readlane_b32 s47, v238, 23
	v_addc_co_u32_e64 v239, s[56:57], 0, v239, s[48:49]
	v_addc_co_u32_e64 v240, s[56:57], 0, v240, s[50:51]
	v_addc_co_u32_e64 v239, s[56:57], 0, v239, s[52:53]
	v_addc_co_u32_e64 v240, s[56:57], 0, v240, s[54:55]
	v_cmp_lt_u32_e64 s[48:49], s46, v237
	v_cmp_lt_u32_e64 s[50:51], s46, v238
	v_cmp_lt_u32_e64 s[52:53], s47, v237
	v_cmp_lt_u32_e64 s[54:55], s47, v238
	v_readlane_b32 s46, v237, 24
	v_readlane_b32 s47, v238, 24
	v_addc_co_u32_e64 v239, s[56:57], 0, v239, s[48:49]
	v_addc_co_u32_e64 v240, s[56:57], 0, v240, s[50:51]
	v_addc_co_u32_e64 v239, s[56:57], 0, v239, s[52:53]
	v_addc_co_u32_e64 v240, s[56:57], 0, v240, s[54:55]
	v_cmp_lt_u32_e64 s[48:49], s46, v237
	v_cmp_lt_u32_e64 s[50:51], s46, v238
	v_cmp_lt_u32_e64 s[52:53], s47, v237
	v_cmp_lt_u32_e64 s[54:55], s47, v238
	v_readlane_b32 s46, v237, 25
	v_readlane_b32 s47, v238, 25
	v_addc_co_u32_e64 v239, s[56:57], 0, v239, s[48:49]
	v_addc_co_u32_e64 v240, s[56:57], 0, v240, s[50:51]
	v_addc_co_u32_e64 v239, s[56:57], 0, v239, s[52:53]
	v_addc_co_u32_e64 v240, s[56:57], 0, v240, s[54:55]
	v_cmp_lt_u32_e64 s[48:49], s46, v237
	v_cmp_lt_u32_e64 s[50:51], s46, v238
	v_cmp_lt_u32_e64 s[52:53], s47, v237
	v_cmp_lt_u32_e64 s[54:55], s47, v238
	v_readlane_b32 s46, v237, 26
	v_readlane_b32 s47, v238, 26
	v_addc_co_u32_e64 v239, s[56:57], 0, v239, s[48:49]
	v_addc_co_u32_e64 v240, s[56:57], 0, v240, s[50:51]
	v_addc_co_u32_e64 v239, s[56:57], 0, v239, s[52:53]
	v_addc_co_u32_e64 v240, s[56:57], 0, v240, s[54:55]
	v_cmp_lt_u32_e64 s[48:49], s46, v237
	v_cmp_lt_u32_e64 s[50:51], s46, v238
	v_cmp_lt_u32_e64 s[52:53], s47, v237
	v_cmp_lt_u32_e64 s[54:55], s47, v238
	v_readlane_b32 s46, v237, 27
	v_readlane_b32 s47, v238, 27
	v_addc_co_u32_e64 v239, s[56:57], 0, v239, s[48:49]
	v_addc_co_u32_e64 v240, s[56:57], 0, v240, s[50:51]
	v_addc_co_u32_e64 v239, s[56:57], 0, v239, s[52:53]
	v_addc_co_u32_e64 v240, s[56:57], 0, v240, s[54:55]
	v_cmp_lt_u32_e64 s[48:49], s46, v237
	v_cmp_lt_u32_e64 s[50:51], s46, v238
	v_cmp_lt_u32_e64 s[52:53], s47, v237
	v_cmp_lt_u32_e64 s[54:55], s47, v238
	v_readlane_b32 s46, v237, 28
	v_readlane_b32 s47, v238, 28
	v_addc_co_u32_e64 v239, s[56:57], 0, v239, s[48:49]
	v_addc_co_u32_e64 v240, s[56:57], 0, v240, s[50:51]
	v_addc_co_u32_e64 v239, s[56:57], 0, v239, s[52:53]
	v_addc_co_u32_e64 v240, s[56:57], 0, v240, s[54:55]
	v_cmp_lt_u32_e64 s[48:49], s46, v237
	v_cmp_lt_u32_e64 s[50:51], s46, v238
	v_cmp_lt_u32_e64 s[52:53], s47, v237
	v_cmp_lt_u32_e64 s[54:55], s47, v238
	v_readlane_b32 s46, v237, 29
	v_readlane_b32 s47, v238, 29
	v_addc_co_u32_e64 v239, s[56:57], 0, v239, s[48:49]
	v_addc_co_u32_e64 v240, s[56:57], 0, v240, s[50:51]
	v_addc_co_u32_e64 v239, s[56:57], 0, v239, s[52:53]
	v_addc_co_u32_e64 v240, s[56:57], 0, v240, s[54:55]
	v_cmp_lt_u32_e64 s[48:49], s46, v237
	v_cmp_lt_u32_e64 s[50:51], s46, v238
	v_cmp_lt_u32_e64 s[52:53], s47, v237
	v_cmp_lt_u32_e64 s[54:55], s47, v238
	v_readlane_b32 s46, v237, 30
	v_readlane_b32 s47, v238, 30
	v_addc_co_u32_e64 v239, s[56:57], 0, v239, s[48:49]
	v_addc_co_u32_e64 v240, s[56:57], 0, v240, s[50:51]
	v_addc_co_u32_e64 v239, s[56:57], 0, v239, s[52:53]
	v_addc_co_u32_e64 v240, s[56:57], 0, v240, s[54:55]
	v_cmp_lt_u32_e64 s[48:49], s46, v237
	v_cmp_lt_u32_e64 s[50:51], s46, v238
	v_cmp_lt_u32_e64 s[52:53], s47, v237
	v_cmp_lt_u32_e64 s[54:55], s47, v238
	v_readlane_b32 s46, v237, 31
	v_readlane_b32 s47, v238, 31
	v_addc_co_u32_e64 v239, s[56:57], 0, v239, s[48:49]
	v_addc_co_u32_e64 v240, s[56:57], 0, v240, s[50:51]
	v_addc_co_u32_e64 v239, s[56:57], 0, v239, s[52:53]
	v_addc_co_u32_e64 v240, s[56:57], 0, v240, s[54:55]
	v_cmp_lt_u32_e64 s[48:49], s46, v237
	v_cmp_lt_u32_e64 s[50:51], s46, v238
	v_cmp_lt_u32_e64 s[52:53], s47, v237
	v_cmp_lt_u32_e64 s[54:55], s47, v238
	v_readlane_b32 s46, v237, 32
	v_readlane_b32 s47, v238, 32
	v_addc_co_u32_e64 v239, s[56:57], 0, v239, s[48:49]
	v_addc_co_u32_e64 v240, s[56:57], 0, v240, s[50:51]
	v_addc_co_u32_e64 v239, s[56:57], 0, v239, s[52:53]
	v_addc_co_u32_e64 v240, s[56:57], 0, v240, s[54:55]
	v_cmp_lt_u32_e64 s[48:49], s46, v237
	v_cmp_lt_u32_e64 s[50:51], s46, v238
	v_cmp_lt_u32_e64 s[52:53], s47, v237
	v_cmp_lt_u32_e64 s[54:55], s47, v238
	v_readlane_b32 s46, v237, 33
	v_readlane_b32 s47, v238, 33
	v_addc_co_u32_e64 v239, s[56:57], 0, v239, s[48:49]
	v_addc_co_u32_e64 v240, s[56:57], 0, v240, s[50:51]
	v_addc_co_u32_e64 v239, s[56:57], 0, v239, s[52:53]
	v_addc_co_u32_e64 v240, s[56:57], 0, v240, s[54:55]
	v_cmp_lt_u32_e64 s[48:49], s46, v237
	v_cmp_lt_u32_e64 s[50:51], s46, v238
	v_cmp_lt_u32_e64 s[52:53], s47, v237
	v_cmp_lt_u32_e64 s[54:55], s47, v238
	v_readlane_b32 s46, v237, 34
	v_readlane_b32 s47, v238, 34
	v_addc_co_u32_e64 v239, s[56:57], 0, v239, s[48:49]
	v_addc_co_u32_e64 v240, s[56:57], 0, v240, s[50:51]
	v_addc_co_u32_e64 v239, s[56:57], 0, v239, s[52:53]
	v_addc_co_u32_e64 v240, s[56:57], 0, v240, s[54:55]
	v_cmp_lt_u32_e64 s[48:49], s46, v237
; DEV void peer_gather_token(const Params& p, int tok) {
;     ...
;   const int e0 = p.eidx[(size_t)tok * 128 + lane], e1 = p.eidx[(size_t)tok * 128 + 64 + lane];
;   const int g0 = __builtin_bit_cast(int, p.gw[(size_t)tok * 128 + lane]), g1 = __builtin_bit_cast(int, p.gw[(size_t)tok * 128 + 64 + lane]);
;   u32x2 dn[4][3], up[4][3];
;   auto issue = [&](int k, int slot) {
;     const int e = (k < 64) ? __builtin_amdgcn_readlane(e0, k) : __builtin_amdgcn_readlane(e1, k - 64);
	v_cmp_lt_u32_e64 s[50:51], s46, v238
	v_cmp_lt_u32_e64 s[52:53], s47, v237
	v_cmp_lt_u32_e64 s[54:55], s47, v238
	v_readlane_b32 s46, v237, 35
	v_readlane_b32 s47, v238, 35
	v_addc_co_u32_e64 v239, s[56:57], 0, v239, s[48:49]
	v_addc_co_u32_e64 v240, s[56:57], 0, v240, s[50:51]
	v_addc_co_u32_e64 v239, s[56:57], 0, v239, s[52:53]
	v_addc_co_u32_e64 v240, s[56:57], 0, v240, s[54:55]
	v_cmp_lt_u32_e64 s[48:49], s46, v237
	v_cmp_lt_u32_e64 s[50:51], s46, v238
	v_cmp_lt_u32_e64 s[52:53], s47, v237
	v_cmp_lt_u32_e64 s[54:55], s47, v238
	v_readlane_b32 s46, v237, 36
	v_readlane_b32 s47, v238, 36
	v_addc_co_u32_e64 v239, s[56:57], 0, v239, s[48:49]
	v_addc_co_u32_e64 v240, s[56:57], 0, v240, s[50:51]
	v_addc_co_u32_e64 v239, s[56:57], 0, v239, s[52:53]
	v_addc_co_u32_e64 v240, s[56:57], 0, v240, s[54:55]
	v_cmp_lt_u32_e64 s[48:49], s46, v237
	v_cmp_lt_u32_e64 s[50:51], s46, v238
	v_cmp_lt_u32_e64 s[52:53], s47, v237
	v_cmp_lt_u32_e64 s[54:55], s47, v238
	v_readlane_b32 s46, v237, 37
	v_readlane_b32 s47, v238, 37
	v_addc_co_u32_e64 v239, s[56:57], 0, v239, s[48:49]
	v_addc_co_u32_e64 v240, s[56:57], 0, v240, s[50:51]
	v_addc_co_u32_e64 v239, s[56:57], 0, v239, s[52:53]
	v_addc_co_u32_e64 v240, s[56:57], 0, v240, s[54:55]
	v_cmp_lt_u32_e64 s[48:49], s46, v237
	v_cmp_lt_u32_e64 s[50:51], s46, v238
	v_cmp_lt_u32_e64 s[52:53], s47, v237
	v_cmp_lt_u32_e64 s[54:55], s47, v238
	v_readlane_b32 s46, v237, 38
	v_readlane_b32 s47, v238, 38
	v_addc_co_u32_e64 v239, s[56:57], 0, v239, s[48:49]
	v_addc_co_u32_e64 v240, s[56:57], 0, v240, s[50:51]
	v_addc_co_u32_e64 v239, s[56:57], 0, v239, s[52:53]
	v_addc_co_u32_e64 v240, s[56:57], 0, v240, s[54:55]
	v_cmp_lt_u32_e64 s[48:49], s46, v237
	v_cmp_lt_u32_e64 s[50:51], s46, v238
	v_cmp_lt_u32_e64 s[52:53], s47, v237
	v_cmp_lt_u32_e64 s[54:55], s47, v238
	v_readlane_b32 s46, v237, 39
	v_readlane_b32 s47, v238, 39
	v_addc_co_u32_e64 v239, s[56:57], 0, v239, s[48:49]
	v_addc_co_u32_e64 v240, s[56:57], 0, v240, s[50:51]
	v_addc_co_u32_e64 v239, s[56:57], 0, v239, s[52:53]
	v_addc_co_u32_e64 v240, s[56:57], 0, v240, s[54:55]
	v_cmp_lt_u32_e64 s[48:49], s46, v237
	v_cmp_lt_u32_e64 s[50:51], s46, v238
	v_cmp_lt_u32_e64 s[52:53], s47, v237
	v_cmp_lt_u32_e64 s[54:55], s47, v238
	v_readlane_b32 s46, v237, 40
	v_readlane_b32 s47, v238, 40
	v_addc_co_u32_e64 v239, s[56:57], 0, v239, s[48:49]
	v_addc_co_u32_e64 v240, s[56:57], 0, v240, s[50:51]
	v_addc_co_u32_e64 v239, s[56:57], 0, v239, s[52:53]
	v_addc_co_u32_e64 v240, s[56:57], 0, v240, s[54:55]
	v_cmp_lt_u32_e64 s[48:49], s46, v237
	v_cmp_lt_u32_e64 s[50:51], s46, v238
	v_cmp_lt_u32_e64 s[52:53], s47, v237
	v_cmp_lt_u32_e64 s[54:55], s47, v238
	v_readlane_b32 s46, v237, 41
	v_readlane_b32 s47, v238, 41
	v_addc_co_u32_e64 v239, s[56:57], 0, v239, s[48:49]
	v_addc_co_u32_e64 v240, s[56:57], 0, v240, s[50:51]
	v_addc_co_u32_e64 v239, s[56:57], 0, v239, s[52:53]
	v_addc_co_u32_e64 v240, s[56:57], 0, v240, s[54:55]
	v_cmp_lt_u32_e64 s[48:49], s46, v237
	v_cmp_lt_u32_e64 s[50:51], s46, v238
	v_cmp_lt_u32_e64 s[52:53], s47, v237
	v_cmp_lt_u32_e64 s[54:55], s47, v238
	v_readlane_b32 s46, v237, 42
	v_readlane_b32 s47, v238, 42
	v_addc_co_u32_e64 v239, s[56:57], 0, v239, s[48:49]
	v_addc_co_u32_e64 v240, s[56:57], 0, v240, s[50:51]
	v_addc_co_u32_e64 v239, s[56:57], 0, v239, s[52:53]
	v_addc_co_u32_e64 v240, s[56:57], 0, v240, s[54:55]
	v_cmp_lt_u32_e64 s[48:49], s46, v237
	v_cmp_lt_u32_e64 s[50:51], s46, v238
	v_cmp_lt_u32_e64 s[52:53], s47, v237
	v_cmp_lt_u32_e64 s[54:55], s47, v238
	v_readlane_b32 s46, v237, 43
	v_readlane_b32 s47, v238, 43
	v_addc_co_u32_e64 v239, s[56:57], 0, v239, s[48:49]
	v_addc_co_u32_e64 v240, s[56:57], 0, v240, s[50:51]
	v_addc_co_u32_e64 v239, s[56:57], 0, v239, s[52:53]
	v_addc_co_u32_e64 v240, s[56:57], 0, v240, s[54:55]
	v_cmp_lt_u32_e64 s[48:49], s46, v237
	v_cmp_lt_u32_e64 s[50:51], s46, v238
	v_cmp_lt_u32_e64 s[52:53], s47, v237
	v_cmp_lt_u32_e64 s[54:55], s47, v238
	v_readlane_b32 s46, v237, 44
	v_readlane_b32 s47, v238, 44
	v_addc_co_u32_e64 v239, s[56:57], 0, v239, s[48:49]
	v_addc_co_u32_e64 v240, s[56:57], 0, v240, s[50:51]
	v_addc_co_u32_e64 v239, s[56:57], 0, v239, s[52:53]
	v_addc_co_u32_e64 v240, s[56:57], 0, v240, s[54:55]
	v_cmp_lt_u32_e64 s[48:49], s46, v237
	v_cmp_lt_u32_e64 s[50:51], s46, v238
	v_cmp_lt_u32_e64 s[52:53], s47, v237
	v_cmp_lt_u32_e64 s[54:55], s47, v238
	v_readlane_b32 s46, v237, 45
	v_readlane_b32 s47, v238, 45
	v_addc_co_u32_e64 v239, s[56:57], 0, v239, s[48:49]
	v_addc_co_u32_e64 v240, s[56:57], 0, v240, s[50:51]
	v_addc_co_u32_e64 v239, s[56:57], 0, v239, s[52:53]
	v_addc_co_u32_e64 v240, s[56:57], 0, v240, s[54:55]
	v_cmp_lt_u32_e64 s[48:49], s46, v237
	v_cmp_lt_u32_e64 s[50:51], s46, v238
	v_cmp_lt_u32_e64 s[52:53], s47, v237
	v_cmp_lt_u32_e64 s[54:55], s47, v238
	v_readlane_b32 s46, v237, 46
	v_readlane_b32 s47, v238, 46
	v_addc_co_u32_e64 v239, s[56:57], 0, v239, s[48:49]
	v_addc_co_u32_e64 v240, s[56:57], 0, v240, s[50:51]
	v_addc_co_u32_e64 v239, s[56:57], 0, v239, s[52:53]
	v_addc_co_u32_e64 v240, s[56:57], 0, v240, s[54:55]
	v_cmp_lt_u32_e64 s[48:49], s46, v237
	v_cmp_lt_u32_e64 s[50:51], s46, v238
	v_cmp_lt_u32_e64 s[52:53], s47, v237
	v_cmp_lt_u32_e64 s[54:55], s47, v238
	v_readlane_b32 s46, v237, 47
	v_readlane_b32 s47, v238, 47
	v_addc_co_u32_e64 v239, s[56:57], 0, v239, s[48:49]
	v_addc_co_u32_e64 v240, s[56:57], 0, v240, s[50:51]
	v_addc_co_u32_e64 v239, s[56:57], 0, v239, s[52:53]
	v_addc_co_u32_e64 v240, s[56:57], 0, v240, s[54:55]
	v_cmp_lt_u32_e64 s[48:49], s46, v237
	v_cmp_lt_u32_e64 s[50:51], s46, v238
	v_cmp_lt_u32_e64 s[52:53], s47, v237
	v_cmp_lt_u32_e64 s[54:55], s47, v238
; DEV void peer_gather_token(const Params& p, int tok) {
;     ...
;   const int e0 = p.eidx[(size_t)tok * 128 + lane], e1 = p.eidx[(size_t)tok * 128 + 64 + lane];
;   const int g0 = __builtin_bit_cast(int, p.gw[(size_t)tok * 128 + lane]), g1 = __builtin_bit_cast(int, p.gw[(size_t)tok * 128 + 64 + lane]);
;   u32x2 dn[4][3], up[4][3];
;   auto issue = [&](int k, int slot) {
;     const int e = (k < 64) ? __builtin_amdgcn_readlane(e0, k) : __builtin_amdgcn_readlane(e1, k - 64);
	v_readlane_b32 s46, v237, 48
	v_readlane_b32 s47, v238, 48
	v_addc_co_u32_e64 v239, s[56:57], 0, v239, s[48:49]
	v_addc_co_u32_e64 v240, s[56:57], 0, v240, s[50:51]
	v_addc_co_u32_e64 v239, s[56:57], 0, v239, s[52:53]
	v_addc_co_u32_e64 v240, s[56:57], 0, v240, s[54:55]
	v_cmp_lt_u32_e64 s[48:49], s46, v237
	v_cmp_lt_u32_e64 s[50:51], s46, v238
	v_cmp_lt_u32_e64 s[52:53], s47, v237
	v_cmp_lt_u32_e64 s[54:55], s47, v238
	v_readlane_b32 s46, v237, 49
	v_readlane_b32 s47, v238, 49
	v_addc_co_u32_e64 v239, s[56:57], 0, v239, s[48:49]
	v_addc_co_u32_e64 v240, s[56:57], 0, v240, s[50:51]
	v_addc_co_u32_e64 v239, s[56:57], 0, v239, s[52:53]
	v_addc_co_u32_e64 v240, s[56:57], 0, v240, s[54:55]
	v_cmp_lt_u32_e64 s[48:49], s46, v237
	v_cmp_lt_u32_e64 s[50:51], s46, v238
	v_cmp_lt_u32_e64 s[52:53], s47, v237
	v_cmp_lt_u32_e64 s[54:55], s47, v238
	v_readlane_b32 s46, v237, 50
	v_readlane_b32 s47, v238, 50
	v_addc_co_u32_e64 v239, s[56:57], 0, v239, s[48:49]
	v_addc_co_u32_e64 v240, s[56:57], 0, v240, s[50:51]
	v_addc_co_u32_e64 v239, s[56:57], 0, v239, s[52:53]
	v_addc_co_u32_e64 v240, s[56:57], 0, v240, s[54:55]
	v_cmp_lt_u32_e64 s[48:49], s46, v237
	v_cmp_lt_u32_e64 s[50:51], s46, v238
	v_cmp_lt_u32_e64 s[52:53], s47, v237
	v_cmp_lt_u32_e64 s[54:55], s47, v238
	v_readlane_b32 s46, v237, 51
	v_readlane_b32 s47, v238, 51
	v_addc_co_u32_e64 v239, s[56:57], 0, v239, s[48:49]
	v_addc_co_u32_e64 v240, s[56:57], 0, v240, s[50:51]
	v_addc_co_u32_e64 v239, s[56:57], 0, v239, s[52:53]
	v_addc_co_u32_e64 v240, s[56:57], 0, v240, s[54:55]
	v_cmp_lt_u32_e64 s[48:49], s46, v237
	v_cmp_lt_u32_e64 s[50:51], s46, v238
	v_cmp_lt_u32_e64 s[52:53], s47, v237
	v_cmp_lt_u32_e64 s[54:55], s47, v238
	v_readlane_b32 s46, v237, 52
	v_readlane_b32 s47, v238, 52
	v_addc_co_u32_e64 v239, s[56:57], 0, v239, s[48:49]
	v_addc_co_u32_e64 v240, s[56:57], 0, v240, s[50:51]
	v_addc_co_u32_e64 v239, s[56:57], 0, v239, s[52:53]
	v_addc_co_u32_e64 v240, s[56:57], 0, v240, s[54:55]
	v_cmp_lt_u32_e64 s[48:49], s46, v237
	v_cmp_lt_u32_e64 s[50:51], s46, v238
	v_cmp_lt_u32_e64 s[52:53], s47, v237
	v_cmp_lt_u32_e64 s[54:55], s47, v238
	v_readlane_b32 s46, v237, 53
	v_readlane_b32 s47, v238, 53
	v_addc_co_u32_e64 v239, s[56:57], 0, v239, s[48:49]
	v_addc_co_u32_e64 v240, s[56:57], 0, v240, s[50:51]
	v_addc_co_u32_e64 v239, s[56:57], 0, v239, s[52:53]
	v_addc_co_u32_e64 v240, s[56:57], 0, v240, s[54:55]
	v_cmp_lt_u32_e64 s[48:49], s46, v237
	v_cmp_lt_u32_e64 s[50:51], s46, v238
	v_cmp_lt_u32_e64 s[52:53], s47, v237
	v_cmp_lt_u32_e64 s[54:55], s47, v238
	v_readlane_b32 s46, v237, 54
	v_readlane_b32 s47, v238, 54
	v_addc_co_u32_e64 v239, s[56:57], 0, v239, s[48:49]
	v_addc_co_u32_e64 v240, s[56:57], 0, v240, s[50:51]
	v_addc_co_u32_e64 v239, s[56:57], 0, v239, s[52:53]
	v_addc_co_u32_e64 v240, s[56:57], 0, v240, s[54:55]
	v_cmp_lt_u32_e64 s[48:49], s46, v237
	v_cmp_lt_u32_e64 s[50:51], s46, v238
	v_cmp_lt_u32_e64 s[52:53], s47, v237
	v_cmp_lt_u32_e64 s[54:55], s47, v238
	v_readlane_b32 s46, v237, 55
	v_readlane_b32 s47, v238, 55
	v_addc_co_u32_e64 v239, s[56:57], 0, v239, s[48:49]
	v_addc_co_u32_e64 v240, s[56:57], 0, v240, s[50:51]
	v_addc_co_u32_e64 v239, s[56:57], 0, v239, s[52:53]
	v_addc_co_u32_e64 v240, s[56:57], 0, v240, s[54:55]
	v_cmp_lt_u32_e64 s[48:49], s46, v237
	v_cmp_lt_u32_e64 s[50:51], s46, v238
	v_cmp_lt_u32_e64 s[52:53], s47, v237
	v_cmp_lt_u32_e64 s[54:55], s47, v238
	v_readlane_b32 s46, v237, 56
	v_readlane_b32 s47, v238, 56
	v_addc_co_u32_e64 v239, s[56:57], 0, v239, s[48:49]
	v_addc_co_u32_e64 v240, s[56:57], 0, v240, s[50:51]
	v_addc_co_u32_e64 v239, s[56:57], 0, v239, s[52:53]
	v_addc_co_u32_e64 v240, s[56:57], 0, v240, s[54:55]
	v_cmp_lt_u32_e64 s[48:49], s46, v237
	v_cmp_lt_u32_e64 s[50:51], s46, v238
	v_cmp_lt_u32_e64 s[52:53], s47, v237
; DEV void peer_gather_token(const Params& p, int tok) {
;     ...
;   const int e0 = p.eidx[(size_t)tok * 128 + lane], e1 = p.eidx[(size_t)tok * 128 + 64 + lane];
;   const int g0 = __builtin_bit_cast(int, p.gw[(size_t)tok * 128 + lane]), g1 = __builtin_bit_cast(int, p.gw[(size_t)tok * 128 + 64 + lane]);
;   u32x2 dn[4][3], up[4][3];
;   auto issue = [&](int k, int slot) {
;     const int e = (k < 64) ? __builtin_amdgcn_readlane(e0, k) : __builtin_amdgcn_readlane(e1, k - 64);
	v_cmp_lt_u32_e64 s[54:55], s47, v238
	v_readlane_b32 s46, v237, 57
	v_readlane_b32 s47, v238, 57
	v_addc_co_u32_e64 v239, s[56:57], 0, v239, s[48:49]
	v_addc_co_u32_e64 v240, s[56:57], 0, v240, s[50:51]
	v_addc_co_u32_e64 v239, s[56:57], 0, v239, s[52:53]
	v_addc_co_u32_e64 v240, s[56:57], 0, v240, s[54:55]
	v_cmp_lt_u32_e64 s[48:49], s46, v237
	v_cmp_lt_u32_e64 s[50:51], s46, v238
	v_cmp_lt_u32_e64 s[52:53], s47, v237
	v_cmp_lt_u32_e64 s[54:55], s47, v238
	v_readlane_b32 s46, v237, 58
	v_readlane_b32 s47, v238, 58
	v_addc_co_u32_e64 v239, s[56:57], 0, v239, s[48:49]
	v_addc_co_u32_e64 v240, s[56:57], 0, v240, s[50:51]
	v_addc_co_u32_e64 v239, s[56:57], 0, v239, s[52:53]
	v_addc_co_u32_e64 v240, s[56:57], 0, v240, s[54:55]
	v_cmp_lt_u32_e64 s[48:49], s46, v237
	v_cmp_lt_u32_e64 s[50:51], s46, v238
	v_cmp_lt_u32_e64 s[52:53], s47, v237
	v_cmp_lt_u32_e64 s[54:55], s47, v238
	v_readlane_b32 s46, v237, 59
	v_readlane_b32 s47, v238, 59
	v_addc_co_u32_e64 v239, s[56:57], 0, v239, s[48:49]
	v_addc_co_u32_e64 v240, s[56:57], 0, v240, s[50:51]
	v_addc_co_u32_e64 v239, s[56:57], 0, v239, s[52:53]
	v_addc_co_u32_e64 v240, s[56:57], 0, v240, s[54:55]
	v_cmp_lt_u32_e64 s[48:49], s46, v237
	v_cmp_lt_u32_e64 s[50:51], s46, v238
	v_cmp_lt_u32_e64 s[52:53], s47, v237
	v_cmp_lt_u32_e64 s[54:55], s47, v238
	v_readlane_b32 s46, v237, 60
	v_readlane_b32 s47, v238, 60
	v_addc_co_u32_e64 v239, s[56:57], 0, v239, s[48:49]
	v_addc_co_u32_e64 v240, s[56:57], 0, v240, s[50:51]
	v_addc_co_u32_e64 v239, s[56:57], 0, v239, s[52:53]
	v_addc_co_u32_e64 v240, s[56:57], 0, v240, s[54:55]
	v_cmp_lt_u32_e64 s[48:49], s46, v237
	v_cmp_lt_u32_e64 s[50:51], s46, v238
	v_cmp_lt_u32_e64 s[52:53], s47, v237
	v_cmp_lt_u32_e64 s[54:55], s47, v238
	v_readlane_b32 s46, v237, 61
	v_readlane_b32 s47, v238, 61
	v_addc_co_u32_e64 v239, s[56:57], 0, v239, s[48:49]
	v_addc_co_u32_e64 v240, s[56:57], 0, v240, s[50:51]
	v_addc_co_u32_e64 v239, s[56:57], 0, v239, s[52:53]
	v_addc_co_u32_e64 v240, s[56:57], 0, v240, s[54:55]
	v_cmp_lt_u32_e64 s[48:49], s46, v237
	v_cmp_lt_u32_e64 s[50:51], s46, v238
	v_cmp_lt_u32_e64 s[52:53], s47, v237
	v_cmp_lt_u32_e64 s[54:55], s47, v238
	v_readlane_b32 s46, v237, 62
	v_readlane_b32 s47, v238, 62
	v_addc_co_u32_e64 v239, s[56:57], 0, v239, s[48:49]
	v_addc_co_u32_e64 v240, s[56:57], 0, v240, s[50:51]
	v_addc_co_u32_e64 v239, s[56:57], 0, v239, s[52:53]
	v_addc_co_u32_e64 v240, s[56:57], 0, v240, s[54:55]
	v_cmp_lt_u32_e64 s[48:49], s46, v237
	v_cmp_lt_u32_e64 s[50:51], s46, v238
	v_cmp_lt_u32_e64 s[52:53], s47, v237
	v_cmp_lt_u32_e64 s[54:55], s47, v238
	v_readlane_b32 s46, v237, 63
	v_readlane_b32 s47, v238, 63
	v_addc_co_u32_e64 v239, s[56:57], 0, v239, s[48:49]
	v_addc_co_u32_e64 v240, s[56:57], 0, v240, s[50:51]
	v_addc_co_u32_e64 v239, s[56:57], 0, v239, s[52:53]
	v_addc_co_u32_e64 v240, s[56:57], 0, v240, s[54:55]
	v_cmp_lt_u32_e64 s[48:49], s46, v237
	v_cmp_lt_u32_e64 s[50:51], s46, v238
	v_cmp_lt_u32_e64 s[52:53], s47, v237
	v_cmp_lt_u32_e64 s[54:55], s47, v238
	s_nop 1
	v_addc_co_u32_e64 v239, s[56:57], 0, v239, s[48:49]
	v_addc_co_u32_e64 v240, s[56:57], 0, v240, s[50:51]
	v_addc_co_u32_e64 v239, s[56:57], 0, v239, s[52:53]
	v_addc_co_u32_e64 v240, s[56:57], 0, v240, s[54:55]
	v_xor_b32_e32 v239, s19, v239
	v_xor_b32_e32 v240, s19, v240
	s_xor_b32 s19, s19, 0x7f
	v_and_b32_e32 v237, 0xfffffc00, v241
	v_lshl_add_u32 v239, v239, 2, v237
	v_lshl_add_u32 v240, v240, 2, v237
	ds_write_b32 v239, v216
	ds_write_b32 v240, v217
	ds_write_b32 v239, v218 offset:512
	ds_write_b32 v240, v219 offset:512
	s_waitcnt lgkmcnt(0)
	ds_read_b32 v216, v241
	ds_read_b32 v217, v241 offset:256
	ds_read_b32 v218, v241 offset:512
	ds_read_b32 v219, v241 offset:768
	s_waitcnt lgkmcnt(0)
	s_branch .Lp12_switch

; DEV float gelu_exact(float v) { return 0.5f * v * (1.f + erff(v * 0.7071067811865476f)); }
; DEV void peer_gather_token(const Params& p, int tok) {
;     ...
;   const int e0 = p.eidx[(size_t)tok * 128 + lane], e1 = p.eidx[(size_t)tok * 128 + 64 + lane];
;   const int g0 = __builtin_bit_cast(int, p.gw[(size_t)tok * 128 + lane]), g1 = __builtin_bit_cast(int, p.gw[(size_t)tok * 128 + 64 + lane]);
;   u32x2 dn[4][3], up[4][3];
;   auto issue = [&](int k, int slot) {
;     const int e = (k < 64) ? __builtin_amdgcn_readlane(e0, k) : __builtin_amdgcn_readlane(e1, k - 64);
;     ...
;       const float gk = __builtin_bit_cast(float, (k < 64) ? __builtin_amdgcn_readlane(g0, k) : __builtin_amdgcn_readlane(g1, k - 64));
;       const float act = gelu_exact(d) * gk * (1.f / UP_SCALE);
;       const v6u uq = v6u{up[s][0][0], up[s][0][1], up[s][1][0], up[s][1][1], up[s][2][0], up[s][2][1]};
;       const v32f uv = __builtin_amdgcn_cvt_scalef32_pk32_f32_fp6(uq, 1.0f);
; #pragma unroll
;       for (int i = 0; i < 32; ++i) acc[i] += act * uv[i];
.Ljn_31:
	v_bfi_b32 v209, s18, v210, v205
	v_mul_f32_e32 v208, 0.5, v204
	v_add_f32_e32 v209, 1.0, v209
	v_mul_f32_e32 v208, v208, v209
	v_mul_f32_e32 v208, s26, v208
	v_mul_f32_e32 v206, 0x3e800000, v208
	v_pk_fma_f32 v[66:67], v[2:3], v[206:207], v[66:67] op_sel_hi:[1,0,1]
	v_pk_fma_f32 v[68:69], v[4:5], v[206:207], v[68:69] op_sel_hi:[1,0,1]
	v_pk_fma_f32 v[70:71], v[6:7], v[206:207], v[70:71] op_sel_hi:[1,0,1]
	v_pk_fma_f32 v[72:73], v[8:9], v[206:207], v[72:73] op_sel_hi:[1,0,1]
	v_pk_fma_f32 v[74:75], v[10:11], v[206:207], v[74:75] op_sel_hi:[1,0,1]
	v_pk_fma_f32 v[76:77], v[12:13], v[206:207], v[76:77] op_sel_hi:[1,0,1]
	v_pk_fma_f32 v[78:79], v[14:15], v[206:207], v[78:79] op_sel_hi:[1,0,1]
	v_pk_fma_f32 v[80:81], v[16:17], v[206:207], v[80:81] op_sel_hi:[1,0,1]
	v_pk_fma_f32 v[82:83], v[18:19], v[206:207], v[82:83] op_sel_hi:[1,0,1]
	v_pk_fma_f32 v[84:85], v[20:21], v[206:207], v[84:85] op_sel_hi:[1,0,1]
	v_pk_fma_f32 v[86:87], v[22:23], v[206:207], v[86:87] op_sel_hi:[1,0,1]
	v_pk_fma_f32 v[88:89], v[24:25], v[206:207], v[88:89] op_sel_hi:[1,0,1]
	v_pk_fma_f32 v[90:91], v[26:27], v[206:207], v[90:91] op_sel_hi:[1,0,1]
	v_pk_fma_f32 v[92:93], v[28:29], v[206:207], v[92:93] op_sel_hi:[1,0,1]
	v_pk_fma_f32 v[94:95], v[30:31], v[206:207], v[94:95] op_sel_hi:[1,0,1]
	v_pk_fma_f32 v[96:97], v[32:33], v[206:207], v[96:97] op_sel_hi:[1,0,1]
	s_add_i32 s24, s24, 8
	s_and_b32 s24, s24, 63
	s_waitcnt vmcnt(21)
	v_and_b32_e32 v236, 63, v0
	v_lshrrev_b32_e32 v241, 6, v0
	v_lshl_or_b32 v237, v216, 7, v236
	v_or_b32_e32 v238, 64, v236
	v_lshl_or_b32 v238, v217, 7, v238
	v_mov_b32_e32 v239, 0
	v_mov_b32_e32 v240, 0
	v_lshlrev_b32_e32 v241, 10, v241
	v_lshl_add_u32 v241, v236, 2, v241
	v_readlane_b32 s46, v237, 0
	v_readlane_b32 s47, v238, 0
	s_nop 1
	v_cmp_lt_u32_e64 s[48:49], s46, v237
	v_cmp_lt_u32_e64 s[50:51], s46, v238
	v_cmp_lt_u32_e64 s[52:53], s47, v237
	v_cmp_lt_u32_e64 s[54:55], s47, v238
	v_readlane_b32 s46, v237, 1
	v_readlane_b32 s47, v238, 1
	v_addc_co_u32_e64 v239, s[56:57], 0, v239, s[48:49]
	v_addc_co_u32_e64 v240, s[56:57], 0, v240, s[50:51]
	v_addc_co_u32_e64 v239, s[56:57], 0, v239, s[52:53]
	v_addc_co_u32_e64 v240, s[56:57], 0, v240, s[54:55]
	v_cmp_lt_u32_e64 s[48:49], s46, v237
	v_cmp_lt_u32_e64 s[50:51], s46, v238
	v_cmp_lt_u32_e64 s[52:53], s47, v237
	v_cmp_lt_u32_e64 s[54:55], s47, v238
	v_readlane_b32 s46, v237, 2
	v_readlane_b32 s47, v238, 2
	v_addc_co_u32_e64 v239, s[56:57], 0, v239, s[48:49]
	v_addc_co_u32_e64 v240, s[56:57], 0, v240, s[50:51]
	v_addc_co_u32_e64 v239, s[56:57], 0, v239, s[52:53]
	v_addc_co_u32_e64 v240, s[56:57], 0, v240, s[54:55]
	v_cmp_lt_u32_e64 s[48:49], s46, v237
	v_cmp_lt_u32_e64 s[50:51], s46, v238
	v_cmp_lt_u32_e64 s[52:53], s47, v237
	v_cmp_lt_u32_e64 s[54:55], s47, v238
	v_readlane_b32 s46, v237, 3
	v_readlane_b32 s47, v238, 3
	v_addc_co_u32_e64 v239, s[56:57], 0, v239, s[48:49]
	v_addc_co_u32_e64 v240, s[56:57], 0, v240, s[50:51]
	v_addc_co_u32_e64 v239, s[56:57], 0, v239, s[52:53]
	v_addc_co_u32_e64 v240, s[56:57], 0, v240, s[54:55]
	v_cmp_lt_u32_e64 s[48:49], s46, v237
	v_cmp_lt_u32_e64 s[50:51], s46, v238
	v_cmp_lt_u32_e64 s[52:53], s47, v237
	v_cmp_lt_u32_e64 s[54:55], s47, v238
	v_readlane_b32 s46, v237, 4
	v_readlane_b32 s47, v238, 4
	v_addc_co_u32_e64 v239, s[56:57], 0, v239, s[48:49]
	v_addc_co_u32_e64 v240, s[56:57], 0, v240, s[50:51]
	v_addc_co_u32_e64 v239, s[56:57], 0, v239, s[52:53]
	v_addc_co_u32_e64 v240, s[56:57], 0, v240, s[54:55]
	v_cmp_lt_u32_e64 s[48:49], s46, v237
	v_cmp_lt_u32_e64 s[50:51], s46, v238
	v_cmp_lt_u32_e64 s[52:53], s47, v237
	v_cmp_lt_u32_e64 s[54:55], s47, v238
	v_readlane_b32 s46, v237, 5
	v_readlane_b32 s47, v238, 5
	v_addc_co_u32_e64 v239, s[56:57], 0, v239, s[48:49]
	v_addc_co_u32_e64 v240, s[56:57], 0, v240, s[50:51]
	v_addc_co_u32_e64 v239, s[56:57], 0, v239, s[52:53]
	v_addc_co_u32_e64 v240, s[56:57], 0, v240, s[54:55]
	v_cmp_lt_u32_e64 s[48:49], s46, v237
	v_cmp_lt_u32_e64 s[50:51], s46, v238
	v_cmp_lt_u32_e64 s[52:53], s47, v237
	v_cmp_lt_u32_e64 s[54:55], s47, v238
	v_readlane_b32 s46, v237, 6
	v_readlane_b32 s47, v238, 6
	v_addc_co_u32_e64 v239, s[56:57], 0, v239, s[48:49]
	v_addc_co_u32_e64 v240, s[56:57], 0, v240, s[50:51]
	v_addc_co_u32_e64 v239, s[56:57], 0, v239, s[52:53]
	v_addc_co_u32_e64 v240, s[56:57], 0, v240, s[54:55]
	v_cmp_lt_u32_e64 s[48:49], s46, v237
	v_cmp_lt_u32_e64 s[50:51], s46, v238
	v_cmp_lt_u32_e64 s[52:53], s47, v237
	v_cmp_lt_u32_e64 s[54:55], s47, v238
	v_readlane_b32 s46, v237, 7
	v_readlane_b32 s47, v238, 7
	v_addc_co_u32_e64 v239, s[56:57], 0, v239, s[48:49]
	v_addc_co_u32_e64 v240, s[56:57], 0, v240, s[50:51]
	v_addc_co_u32_e64 v239, s[56:57], 0, v239, s[52:53]
	v_addc_co_u32_e64 v240, s[56:57], 0, v240, s[54:55]
	v_cmp_lt_u32_e64 s[48:49], s46, v237
	v_cmp_lt_u32_e64 s[50:51], s46, v238
	v_cmp_lt_u32_e64 s[52:53], s47, v237
	v_cmp_lt_u32_e64 s[54:55], s47, v238
	v_readlane_b32 s46, v237, 8
	v_readlane_b32 s47, v238, 8
	v_addc_co_u32_e64 v239, s[56:57], 0, v239, s[48:49]
	v_addc_co_u32_e64 v240, s[56:57], 0, v240, s[50:51]
	v_addc_co_u32_e64 v239, s[56:57], 0, v239, s[52:53]
	v_addc_co_u32_e64 v240, s[56:57], 0, v240, s[54:55]
	v_cmp_lt_u32_e64 s[48:49], s46, v237
	v_cmp_lt_u32_e64 s[50:51], s46, v238
	v_cmp_lt_u32_e64 s[52:53], s47, v237
	v_cmp_lt_u32_e64 s[54:55], s47, v238
	v_readlane_b32 s46, v237, 9
	v_readlane_b32 s47, v238, 9
	v_addc_co_u32_e64 v239, s[56:57], 0, v239, s[48:49]
	v_addc_co_u32_e64 v240, s[56:57], 0, v240, s[50:51]
	v_addc_co_u32_e64 v239, s[56:57], 0, v239, s[52:53]
	v_addc_co_u32_e64 v240, s[56:57], 0, v240, s[54:55]
	v_cmp_lt_u32_e64 s[48:49], s46, v237
	v_cmp_lt_u32_e64 s[50:51], s46, v238
; DEV void peer_gather_token(const Params& p, int tok) {
;     ...
;   const int e0 = p.eidx[(size_t)tok * 128 + lane], e1 = p.eidx[(size_t)tok * 128 + 64 + lane];
;   const int g0 = __builtin_bit_cast(int, p.gw[(size_t)tok * 128 + lane]), g1 = __builtin_bit_cast(int, p.gw[(size_t)tok * 128 + 64 + lane]);
;   u32x2 dn[4][3], up[4][3];
;   auto issue = [&](int k, int slot) {
;     const int e = (k < 64) ? __builtin_amdgcn_readlane(e0, k) : __builtin_amdgcn_readlane(e1, k - 64);
	v_cmp_lt_u32_e64 s[52:53], s47, v237
	v_cmp_lt_u32_e64 s[54:55], s47, v238
	v_readlane_b32 s46, v237, 10
	v_readlane_b32 s47, v238, 10
	v_addc_co_u32_e64 v239, s[56:57], 0, v239, s[48:49]
	v_addc_co_u32_e64 v240, s[56:57], 0, v240, s[50:51]
	v_addc_co_u32_e64 v239, s[56:57], 0, v239, s[52:53]
	v_addc_co_u32_e64 v240, s[56:57], 0, v240, s[54:55]
	v_cmp_lt_u32_e64 s[48:49], s46, v237
	v_cmp_lt_u32_e64 s[50:51], s46, v238
	v_cmp_lt_u32_e64 s[52:53], s47, v237
	v_cmp_lt_u32_e64 s[54:55], s47, v238
	v_readlane_b32 s46, v237, 11
	v_readlane_b32 s47, v238, 11
	v_addc_co_u32_e64 v239, s[56:57], 0, v239, s[48:49]
	v_addc_co_u32_e64 v240, s[56:57], 0, v240, s[50:51]
	v_addc_co_u32_e64 v239, s[56:57], 0, v239, s[52:53]
	v_addc_co_u32_e64 v240, s[56:57], 0, v240, s[54:55]
	v_cmp_lt_u32_e64 s[48:49], s46, v237
	v_cmp_lt_u32_e64 s[50:51], s46, v238
	v_cmp_lt_u32_e64 s[52:53], s47, v237
	v_cmp_lt_u32_e64 s[54:55], s47, v238
	v_readlane_b32 s46, v237, 12
	v_readlane_b32 s47, v238, 12
	v_addc_co_u32_e64 v239, s[56:57], 0, v239, s[48:49]
	v_addc_co_u32_e64 v240, s[56:57], 0, v240, s[50:51]
	v_addc_co_u32_e64 v239, s[56:57], 0, v239, s[52:53]
	v_addc_co_u32_e64 v240, s[56:57], 0, v240, s[54:55]
	v_cmp_lt_u32_e64 s[48:49], s46, v237
	v_cmp_lt_u32_e64 s[50:51], s46, v238
	v_cmp_lt_u32_e64 s[52:53], s47, v237
	v_cmp_lt_u32_e64 s[54:55], s47, v238
	v_readlane_b32 s46, v237, 13
	v_readlane_b32 s47, v238, 13
	v_addc_co_u32_e64 v239, s[56:57], 0, v239, s[48:49]
	v_addc_co_u32_e64 v240, s[56:57], 0, v240, s[50:51]
	v_addc_co_u32_e64 v239, s[56:57], 0, v239, s[52:53]
	v_addc_co_u32_e64 v240, s[56:57], 0, v240, s[54:55]
	v_cmp_lt_u32_e64 s[48:49], s46, v237
	v_cmp_lt_u32_e64 s[50:51], s46, v238
	v_cmp_lt_u32_e64 s[52:53], s47, v237
	v_cmp_lt_u32_e64 s[54:55], s47, v238
	v_readlane_b32 s46, v237, 14
	v_readlane_b32 s47, v238, 14
	v_addc_co_u32_e64 v239, s[56:57], 0, v239, s[48:49]
	v_addc_co_u32_e64 v240, s[56:57], 0, v240, s[50:51]
	v_addc_co_u32_e64 v239, s[56:57], 0, v239, s[52:53]
	v_addc_co_u32_e64 v240, s[56:57], 0, v240, s[54:55]
	v_cmp_lt_u32_e64 s[48:49], s46, v237
	v_cmp_lt_u32_e64 s[50:51], s46, v238
	v_cmp_lt_u32_e64 s[52:53], s47, v237
	v_cmp_lt_u32_e64 s[54:55], s47, v238
	v_readlane_b32 s46, v237, 15
	v_readlane_b32 s47, v238, 15
	v_addc_co_u32_e64 v239, s[56:57], 0, v239, s[48:49]
	v_addc_co_u32_e64 v240, s[56:57], 0, v240, s[50:51]
	v_addc_co_u32_e64 v239, s[56:57], 0, v239, s[52:53]
	v_addc_co_u32_e64 v240, s[56:57], 0, v240, s[54:55]
	v_cmp_lt_u32_e64 s[48:49], s46, v237
	v_cmp_lt_u32_e64 s[50:51], s46, v238
	v_cmp_lt_u32_e64 s[52:53], s47, v237
	v_cmp_lt_u32_e64 s[54:55], s47, v238
	v_readlane_b32 s46, v237, 16
	v_readlane_b32 s47, v238, 16
	v_addc_co_u32_e64 v239, s[56:57], 0, v239, s[48:49]
	v_addc_co_u32_e64 v240, s[56:57], 0, v240, s[50:51]
	v_addc_co_u32_e64 v239, s[56:57], 0, v239, s[52:53]
	v_addc_co_u32_e64 v240, s[56:57], 0, v240, s[54:55]
	v_cmp_lt_u32_e64 s[48:49], s46, v237
	v_cmp_lt_u32_e64 s[50:51], s46, v238
	v_cmp_lt_u32_e64 s[52:53], s47, v237
	v_cmp_lt_u32_e64 s[54:55], s47, v238
	v_readlane_b32 s46, v237, 17
	v_readlane_b32 s47, v238, 17
	v_addc_co_u32_e64 v239, s[56:57], 0, v239, s[48:49]
	v_addc_co_u32_e64 v240, s[56:57], 0, v240, s[50:51]
	v_addc_co_u32_e64 v239, s[56:57], 0, v239, s[52:53]
	v_addc_co_u32_e64 v240, s[56:57], 0, v240, s[54:55]
	v_cmp_lt_u32_e64 s[48:49], s46, v237
	v_cmp_lt_u32_e64 s[50:51], s46, v238
	v_cmp_lt_u32_e64 s[52:53], s47, v237
	v_cmp_lt_u32_e64 s[54:55], s47, v238
	v_readlane_b32 s46, v237, 18
	v_readlane_b32 s47, v238, 18
	v_addc_co_u32_e64 v239, s[56:57], 0, v239, s[48:49]
	v_addc_co_u32_e64 v240, s[56:57], 0, v240, s[50:51]
	v_addc_co_u32_e64 v239, s[56:57], 0, v239, s[52:53]
	v_addc_co_u32_e64 v240, s[56:57], 0, v240, s[54:55]
	v_cmp_lt_u32_e64 s[48:49], s46, v237
	v_cmp_lt_u32_e64 s[50:51], s46, v238
	v_cmp_lt_u32_e64 s[52:53], s47, v237
	v_cmp_lt_u32_e64 s[54:55], s47, v238
	v_readlane_b32 s46, v237, 19
	v_readlane_b32 s47, v238, 19
	v_addc_co_u32_e64 v239, s[56:57], 0, v239, s[48:49]
	v_addc_co_u32_e64 v240, s[56:57], 0, v240, s[50:51]
	v_addc_co_u32_e64 v239, s[56:57], 0, v239, s[52:53]
	v_addc_co_u32_e64 v240, s[56:57], 0, v240, s[54:55]
	v_cmp_lt_u32_e64 s[48:49], s46, v237
	v_cmp_lt_u32_e64 s[50:51], s46, v238
	v_cmp_lt_u32_e64 s[52:53], s47, v237
	v_cmp_lt_u32_e64 s[54:55], s47, v238
	v_readlane_b32 s46, v237, 20
	v_readlane_b32 s47, v238, 20
	v_addc_co_u32_e64 v239, s[56:57], 0, v239, s[48:49]
	v_addc_co_u32_e64 v240, s[56:57], 0, v240, s[50:51]
	v_addc_co_u32_e64 v239, s[56:57], 0, v239, s[52:53]
	v_addc_co_u32_e64 v240, s[56:57], 0, v240, s[54:55]
	v_cmp_lt_u32_e64 s[48:49], s46, v237
	v_cmp_lt_u32_e64 s[50:51], s46, v238
	v_cmp_lt_u32_e64 s[52:53], s47, v237
	v_cmp_lt_u32_e64 s[54:55], s47, v238
	v_readlane_b32 s46, v237, 21
	v_readlane_b32 s47, v238, 21
	v_addc_co_u32_e64 v239, s[56:57], 0, v239, s[48:49]
	v_addc_co_u32_e64 v240, s[56:57], 0, v240, s[50:51]
	v_addc_co_u32_e64 v239, s[56:57], 0, v239, s[52:53]
	v_addc_co_u32_e64 v240, s[56:57], 0, v240, s[54:55]
	v_cmp_lt_u32_e64 s[48:49], s46, v237
	v_cmp_lt_u32_e64 s[50:51], s46, v238
	v_cmp_lt_u32_e64 s[52:53], s47, v237
	v_cmp_lt_u32_e64 s[54:55], s47, v238
	v_readlane_b32 s46, v237, 22
	v_readlane_b32 s47, v238, 22
	v_addc_co_u32_e64 v239, s[56:57], 0, v239, s[48:49]
	v_addc_co_u32_e64 v240, s[56:57], 0, v240, s[50:51]
	v_addc_co_u32_e64 v239, s[56:57], 0, v239, s[52:53]
	v_addc_co_u32_e64 v240, s[56:57], 0, v240, s[54:55]
	v_cmp_lt_u32_e64 s[48:49], s46, v237
	v_cmp_lt_u32_e64 s[50:51], s46, v238
	v_cmp_lt_u32_e64 s[52:53], s47, v237
	v_cmp_lt_u32_e64 s[54:55], s47, v238
	v_readlane_b32 s46, v237, 23
	v_readlane_b32 s47, v238, 23
; DEV void peer_gather_token(const Params& p, int tok) {
;     ...
;   const int e0 = p.eidx[(size_t)tok * 128 + lane], e1 = p.eidx[(size_t)tok * 128 + 64 + lane];
;   const int g0 = __builtin_bit_cast(int, p.gw[(size_t)tok * 128 + lane]), g1 = __builtin_bit_cast(int, p.gw[(size_t)tok * 128 + 64 + lane]);
;   u32x2 dn[4][3], up[4][3];
;   auto issue = [&](int k, int slot) {
;     const int e = (k < 64) ? __builtin_amdgcn_readlane(e0, k) : __builtin_amdgcn_readlane(e1, k - 64);
	v_addc_co_u32_e64 v239, s[56:57], 0, v239, s[48:49]
	v_addc_co_u32_e64 v240, s[56:57], 0, v240, s[50:51]
	v_addc_co_u32_e64 v239, s[56:57], 0, v239, s[52:53]
	v_addc_co_u32_e64 v240, s[56:57], 0, v240, s[54:55]
	v_cmp_lt_u32_e64 s[48:49], s46, v237
	v_cmp_lt_u32_e64 s[50:51], s46, v238
	v_cmp_lt_u32_e64 s[52:53], s47, v237
	v_cmp_lt_u32_e64 s[54:55], s47, v238
	v_readlane_b32 s46, v237, 24
	v_readlane_b32 s47, v238, 24
	v_addc_co_u32_e64 v239, s[56:57], 0, v239, s[48:49]
	v_addc_co_u32_e64 v240, s[56:57], 0, v240, s[50:51]
	v_addc_co_u32_e64 v239, s[56:57], 0, v239, s[52:53]
	v_addc_co_u32_e64 v240, s[56:57], 0, v240, s[54:55]
	v_cmp_lt_u32_e64 s[48:49], s46, v237
	v_cmp_lt_u32_e64 s[50:51], s46, v238
	v_cmp_lt_u32_e64 s[52:53], s47, v237
	v_cmp_lt_u32_e64 s[54:55], s47, v238
	v_readlane_b32 s46, v237, 25
	v_readlane_b32 s47, v238, 25
	v_addc_co_u32_e64 v239, s[56:57], 0, v239, s[48:49]
	v_addc_co_u32_e64 v240, s[56:57], 0, v240, s[50:51]
	v_addc_co_u32_e64 v239, s[56:57], 0, v239, s[52:53]
	v_addc_co_u32_e64 v240, s[56:57], 0, v240, s[54:55]
	v_cmp_lt_u32_e64 s[48:49], s46, v237
	v_cmp_lt_u32_e64 s[50:51], s46, v238
	v_cmp_lt_u32_e64 s[52:53], s47, v237
	v_cmp_lt_u32_e64 s[54:55], s47, v238
	v_readlane_b32 s46, v237, 26
	v_readlane_b32 s47, v238, 26
	v_addc_co_u32_e64 v239, s[56:57], 0, v239, s[48:49]
	v_addc_co_u32_e64 v240, s[56:57], 0, v240, s[50:51]
	v_addc_co_u32_e64 v239, s[56:57], 0, v239, s[52:53]
	v_addc_co_u32_e64 v240, s[56:57], 0, v240, s[54:55]
	v_cmp_lt_u32_e64 s[48:49], s46, v237
	v_cmp_lt_u32_e64 s[50:51], s46, v238
	v_cmp_lt_u32_e64 s[52:53], s47, v237
	v_cmp_lt_u32_e64 s[54:55], s47, v238
	v_readlane_b32 s46, v237, 27
	v_readlane_b32 s47, v238, 27
	v_addc_co_u32_e64 v239, s[56:57], 0, v239, s[48:49]
	v_addc_co_u32_e64 v240, s[56:57], 0, v240, s[50:51]
	v_addc_co_u32_e64 v239, s[56:57], 0, v239, s[52:53]
	v_addc_co_u32_e64 v240, s[56:57], 0, v240, s[54:55]
	v_cmp_lt_u32_e64 s[48:49], s46, v237
	v_cmp_lt_u32_e64 s[50:51], s46, v238
	v_cmp_lt_u32_e64 s[52:53], s47, v237
	v_cmp_lt_u32_e64 s[54:55], s47, v238
	v_readlane_b32 s46, v237, 28
	v_readlane_b32 s47, v238, 28
	v_addc_co_u32_e64 v239, s[56:57], 0, v239, s[48:49]
	v_addc_co_u32_e64 v240, s[56:57], 0, v240, s[50:51]
	v_addc_co_u32_e64 v239, s[56:57], 0, v239, s[52:53]
	v_addc_co_u32_e64 v240, s[56:57], 0, v240, s[54:55]
	v_cmp_lt_u32_e64 s[48:49], s46, v237
	v_cmp_lt_u32_e64 s[50:51], s46, v238
	v_cmp_lt_u32_e64 s[52:53], s47, v237
	v_cmp_lt_u32_e64 s[54:55], s47, v238
	v_readlane_b32 s46, v237, 29
	v_readlane_b32 s47, v238, 29
	v_addc_co_u32_e64 v239, s[56:57], 0, v239, s[48:49]
	v_addc_co_u32_e64 v240, s[56:57], 0, v240, s[50:51]
	v_addc_co_u32_e64 v239, s[56:57], 0, v239, s[52:53]
	v_addc_co_u32_e64 v240, s[56:57], 0, v240, s[54:55]
	v_cmp_lt_u32_e64 s[48:49], s46, v237
	v_cmp_lt_u32_e64 s[50:51], s46, v238
	v_cmp_lt_u32_e64 s[52:53], s47, v237
	v_cmp_lt_u32_e64 s[54:55], s47, v238
	v_readlane_b32 s46, v237, 30
	v_readlane_b32 s47, v238, 30
	v_addc_co_u32_e64 v239, s[56:57], 0, v239, s[48:49]
	v_addc_co_u32_e64 v240, s[56:57], 0, v240, s[50:51]
	v_addc_co_u32_e64 v239, s[56:57], 0, v239, s[52:53]
	v_addc_co_u32_e64 v240, s[56:57], 0, v240, s[54:55]
	v_cmp_lt_u32_e64 s[48:49], s46, v237
	v_cmp_lt_u32_e64 s[50:51], s46, v238
	v_cmp_lt_u32_e64 s[52:53], s47, v237
	v_cmp_lt_u32_e64 s[54:55], s47, v238
	v_readlane_b32 s46, v237, 31
	v_readlane_b32 s47, v238, 31
	v_addc_co_u32_e64 v239, s[56:57], 0, v239, s[48:49]
	v_addc_co_u32_e64 v240, s[56:57], 0, v240, s[50:51]
	v_addc_co_u32_e64 v239, s[56:57], 0, v239, s[52:53]
	v_addc_co_u32_e64 v240, s[56:57], 0, v240, s[54:55]
	v_cmp_lt_u32_e64 s[48:49], s46, v237
	v_cmp_lt_u32_e64 s[50:51], s46, v238
	v_cmp_lt_u32_e64 s[52:53], s47, v237
	v_cmp_lt_u32_e64 s[54:55], s47, v238
	v_readlane_b32 s46, v237, 32
	v_readlane_b32 s47, v238, 32
	v_addc_co_u32_e64 v239, s[56:57], 0, v239, s[48:49]
	v_addc_co_u32_e64 v240, s[56:57], 0, v240, s[50:51]
	v_addc_co_u32_e64 v239, s[56:57], 0, v239, s[52:53]
	v_addc_co_u32_e64 v240, s[56:57], 0, v240, s[54:55]
	v_cmp_lt_u32_e64 s[48:49], s46, v237
	v_cmp_lt_u32_e64 s[50:51], s46, v238
	v_cmp_lt_u32_e64 s[52:53], s47, v237
	v_cmp_lt_u32_e64 s[54:55], s47, v238
	v_readlane_b32 s46, v237, 33
	v_readlane_b32 s47, v238, 33
	v_addc_co_u32_e64 v239, s[56:57], 0, v239, s[48:49]
	v_addc_co_u32_e64 v240, s[56:57], 0, v240, s[50:51]
	v_addc_co_u32_e64 v239, s[56:57], 0, v239, s[52:53]
	v_addc_co_u32_e64 v240, s[56:57], 0, v240, s[54:55]
	v_cmp_lt_u32_e64 s[48:49], s46, v237
	v_cmp_lt_u32_e64 s[50:51], s46, v238
	v_cmp_lt_u32_e64 s[52:53], s47, v237
	v_cmp_lt_u32_e64 s[54:55], s47, v238
	v_readlane_b32 s46, v237, 34
	v_readlane_b32 s47, v238, 34
	v_addc_co_u32_e64 v239, s[56:57], 0, v239, s[48:49]
	v_addc_co_u32_e64 v240, s[56:57], 0, v240, s[50:51]
	v_addc_co_u32_e64 v239, s[56:57], 0, v239, s[52:53]
	v_addc_co_u32_e64 v240, s[56:57], 0, v240, s[54:55]
	v_cmp_lt_u32_e64 s[48:49], s46, v237
	v_cmp_lt_u32_e64 s[50:51], s46, v238
	v_cmp_lt_u32_e64 s[52:53], s47, v237
	v_cmp_lt_u32_e64 s[54:55], s47, v238
	v_readlane_b32 s46, v237, 35
	v_readlane_b32 s47, v238, 35
	v_addc_co_u32_e64 v239, s[56:57], 0, v239, s[48:49]
	v_addc_co_u32_e64 v240, s[56:57], 0, v240, s[50:51]
	v_addc_co_u32_e64 v239, s[56:57], 0, v239, s[52:53]
	v_addc_co_u32_e64 v240, s[56:57], 0, v240, s[54:55]
	v_cmp_lt_u32_e64 s[48:49], s46, v237
	v_cmp_lt_u32_e64 s[50:51], s46, v238
	v_cmp_lt_u32_e64 s[52:53], s47, v237
	v_cmp_lt_u32_e64 s[54:55], s47, v238
	v_readlane_b32 s46, v237, 36
	v_readlane_b32 s47, v238, 36
	v_addc_co_u32_e64 v239, s[56:57], 0, v239, s[48:49]
	v_addc_co_u32_e64 v240, s[56:57], 0, v240, s[50:51]
; DEV void peer_gather_token(const Params& p, int tok) {
;     ...
;   const int e0 = p.eidx[(size_t)tok * 128 + lane], e1 = p.eidx[(size_t)tok * 128 + 64 + lane];
;   const int g0 = __builtin_bit_cast(int, p.gw[(size_t)tok * 128 + lane]), g1 = __builtin_bit_cast(int, p.gw[(size_t)tok * 128 + 64 + lane]);
;   u32x2 dn[4][3], up[4][3];
;   auto issue = [&](int k, int slot) {
;     const int e = (k < 64) ? __builtin_amdgcn_readlane(e0, k) : __builtin_amdgcn_readlane(e1, k - 64);
	v_addc_co_u32_e64 v239, s[56:57], 0, v239, s[52:53]
	v_addc_co_u32_e64 v240, s[56:57], 0, v240, s[54:55]
	v_cmp_lt_u32_e64 s[48:49], s46, v237
	v_cmp_lt_u32_e64 s[50:51], s46, v238
	v_cmp_lt_u32_e64 s[52:53], s47, v237
	v_cmp_lt_u32_e64 s[54:55], s47, v238
	v_readlane_b32 s46, v237, 37
	v_readlane_b32 s47, v238, 37
	v_addc_co_u32_e64 v239, s[56:57], 0, v239, s[48:49]
	v_addc_co_u32_e64 v240, s[56:57], 0, v240, s[50:51]
	v_addc_co_u32_e64 v239, s[56:57], 0, v239, s[52:53]
	v_addc_co_u32_e64 v240, s[56:57], 0, v240, s[54:55]
	v_cmp_lt_u32_e64 s[48:49], s46, v237
	v_cmp_lt_u32_e64 s[50:51], s46, v238
	v_cmp_lt_u32_e64 s[52:53], s47, v237
	v_cmp_lt_u32_e64 s[54:55], s47, v238
	v_readlane_b32 s46, v237, 38
	v_readlane_b32 s47, v238, 38
	v_addc_co_u32_e64 v239, s[56:57], 0, v239, s[48:49]
	v_addc_co_u32_e64 v240, s[56:57], 0, v240, s[50:51]
	v_addc_co_u32_e64 v239, s[56:57], 0, v239, s[52:53]
	v_addc_co_u32_e64 v240, s[56:57], 0, v240, s[54:55]
	v_cmp_lt_u32_e64 s[48:49], s46, v237
	v_cmp_lt_u32_e64 s[50:51], s46, v238
	v_cmp_lt_u32_e64 s[52:53], s47, v237
	v_cmp_lt_u32_e64 s[54:55], s47, v238
	v_readlane_b32 s46, v237, 39
	v_readlane_b32 s47, v238, 39
	v_addc_co_u32_e64 v239, s[56:57], 0, v239, s[48:49]
	v_addc_co_u32_e64 v240, s[56:57], 0, v240, s[50:51]
	v_addc_co_u32_e64 v239, s[56:57], 0, v239, s[52:53]
	v_addc_co_u32_e64 v240, s[56:57], 0, v240, s[54:55]
	v_cmp_lt_u32_e64 s[48:49], s46, v237
	v_cmp_lt_u32_e64 s[50:51], s46, v238
	v_cmp_lt_u32_e64 s[52:53], s47, v237
	v_cmp_lt_u32_e64 s[54:55], s47, v238
	v_readlane_b32 s46, v237, 40
	v_readlane_b32 s47, v238, 40
	v_addc_co_u32_e64 v239, s[56:57], 0, v239, s[48:49]
	v_addc_co_u32_e64 v240, s[56:57], 0, v240, s[50:51]
	v_addc_co_u32_e64 v239, s[56:57], 0, v239, s[52:53]
	v_addc_co_u32_e64 v240, s[56:57], 0, v240, s[54:55]
	v_cmp_lt_u32_e64 s[48:49], s46, v237
	v_cmp_lt_u32_e64 s[50:51], s46, v238
	v_cmp_lt_u32_e64 s[52:53], s47, v237
	v_cmp_lt_u32_e64 s[54:55], s47, v238
	v_readlane_b32 s46, v237, 41
	v_readlane_b32 s47, v238, 41
	v_addc_co_u32_e64 v239, s[56:57], 0, v239, s[48:49]
	v_addc_co_u32_e64 v240, s[56:57], 0, v240, s[50:51]
	v_addc_co_u32_e64 v239, s[56:57], 0, v239, s[52:53]
	v_addc_co_u32_e64 v240, s[56:57], 0, v240, s[54:55]
	v_cmp_lt_u32_e64 s[48:49], s46, v237
	v_cmp_lt_u32_e64 s[50:51], s46, v238
	v_cmp_lt_u32_e64 s[52:53], s47, v237
	v_cmp_lt_u32_e64 s[54:55], s47, v238
	v_readlane_b32 s46, v237, 42
	v_readlane_b32 s47, v238, 42
	v_addc_co_u32_e64 v239, s[56:57], 0, v239, s[48:49]
	v_addc_co_u32_e64 v240, s[56:57], 0, v240, s[50:51]
	v_addc_co_u32_e64 v239, s[56:57], 0, v239, s[52:53]
	v_addc_co_u32_e64 v240, s[56:57], 0, v240, s[54:55]
	v_cmp_lt_u32_e64 s[48:49], s46, v237
	v_cmp_lt_u32_e64 s[50:51], s46, v238
	v_cmp_lt_u32_e64 s[52:53], s47, v237
	v_cmp_lt_u32_e64 s[54:55], s47, v238
	v_readlane_b32 s46, v237, 43
	v_readlane_b32 s47, v238, 43
	v_addc_co_u32_e64 v239, s[56:57], 0, v239, s[48:49]
	v_addc_co_u32_e64 v240, s[56:57], 0, v240, s[50:51]
	v_addc_co_u32_e64 v239, s[56:57], 0, v239, s[52:53]
	v_addc_co_u32_e64 v240, s[56:57], 0, v240, s[54:55]
	v_cmp_lt_u32_e64 s[48:49], s46, v237
	v_cmp_lt_u32_e64 s[50:51], s46, v238
	v_cmp_lt_u32_e64 s[52:53], s47, v237
	v_cmp_lt_u32_e64 s[54:55], s47, v238
	v_readlane_b32 s46, v237, 44
	v_readlane_b32 s47, v238, 44
	v_addc_co_u32_e64 v239, s[56:57], 0, v239, s[48:49]
	v_addc_co_u32_e64 v240, s[56:57], 0, v240, s[50:51]
	v_addc_co_u32_e64 v239, s[56:57], 0, v239, s[52:53]
	v_addc_co_u32_e64 v240, s[56:57], 0, v240, s[54:55]
	v_cmp_lt_u32_e64 s[48:49], s46, v237
	v_cmp_lt_u32_e64 s[50:51], s46, v238
	v_cmp_lt_u32_e64 s[52:53], s47, v237
	v_cmp_lt_u32_e64 s[54:55], s47, v238
	v_readlane_b32 s46, v237, 45
	v_readlane_b32 s47, v238, 45
	v_addc_co_u32_e64 v239, s[56:57], 0, v239, s[48:49]
	v_addc_co_u32_e64 v240, s[56:57], 0, v240, s[50:51]
	v_addc_co_u32_e64 v239, s[56:57], 0, v239, s[52:53]
	v_addc_co_u32_e64 v240, s[56:57], 0, v240, s[54:55]
	v_cmp_lt_u32_e64 s[48:49], s46, v237
	v_cmp_lt_u32_e64 s[50:51], s46, v238
	v_cmp_lt_u32_e64 s[52:53], s47, v237
	v_cmp_lt_u32_e64 s[54:55], s47, v238
	v_readlane_b32 s46, v237, 46
	v_readlane_b32 s47, v238, 46
	v_addc_co_u32_e64 v239, s[56:57], 0, v239, s[48:49]
	v_addc_co_u32_e64 v240, s[56:57], 0, v240, s[50:51]
	v_addc_co_u32_e64 v239, s[56:57], 0, v239, s[52:53]
	v_addc_co_u32_e64 v240, s[56:57], 0, v240, s[54:55]
	v_cmp_lt_u32_e64 s[48:49], s46, v237
	v_cmp_lt_u32_e64 s[50:51], s46, v238
	v_cmp_lt_u32_e64 s[52:53], s47, v237
	v_cmp_lt_u32_e64 s[54:55], s47, v238
	v_readlane_b32 s46, v237, 47
	v_readlane_b32 s47, v238, 47
	v_addc_co_u32_e64 v239, s[56:57], 0, v239, s[48:49]
	v_addc_co_u32_e64 v240, s[56:57], 0, v240, s[50:51]
	v_addc_co_u32_e64 v239, s[56:57], 0, v239, s[52:53]
	v_addc_co_u32_e64 v240, s[56:57], 0, v240, s[54:55]
	v_cmp_lt_u32_e64 s[48:49], s46, v237
	v_cmp_lt_u32_e64 s[50:51], s46, v238
	v_cmp_lt_u32_e64 s[52:53], s47, v237
	v_cmp_lt_u32_e64 s[54:55], s47, v238
	v_readlane_b32 s46, v237, 48
	v_readlane_b32 s47, v238, 48
	v_addc_co_u32_e64 v239, s[56:57], 0, v239, s[48:49]
	v_addc_co_u32_e64 v240, s[56:57], 0, v240, s[50:51]
	v_addc_co_u32_e64 v239, s[56:57], 0, v239, s[52:53]
	v_addc_co_u32_e64 v240, s[56:57], 0, v240, s[54:55]
	v_cmp_lt_u32_e64 s[48:49], s46, v237
	v_cmp_lt_u32_e64 s[50:51], s46, v238
	v_cmp_lt_u32_e64 s[52:53], s47, v237
	v_cmp_lt_u32_e64 s[54:55], s47, v238
	v_readlane_b32 s46, v237, 49
	v_readlane_b32 s47, v238, 49
	v_addc_co_u32_e64 v239, s[56:57], 0, v239, s[48:49]
	v_addc_co_u32_e64 v240, s[56:57], 0, v240, s[50:51]
	v_addc_co_u32_e64 v239, s[56:57], 0, v239, s[52:53]
	v_addc_co_u32_e64 v240, s[56:57], 0, v240, s[54:55]
	v_cmp_lt_u32_e64 s[48:49], s46, v237
; DEV void peer_gather_token(const Params& p, int tok) {
;     ...
;   const int e0 = p.eidx[(size_t)tok * 128 + lane], e1 = p.eidx[(size_t)tok * 128 + 64 + lane];
;   const int g0 = __builtin_bit_cast(int, p.gw[(size_t)tok * 128 + lane]), g1 = __builtin_bit_cast(int, p.gw[(size_t)tok * 128 + 64 + lane]);
;   u32x2 dn[4][3], up[4][3];
;   auto issue = [&](int k, int slot) {
;     const int e = (k < 64) ? __builtin_amdgcn_readlane(e0, k) : __builtin_amdgcn_readlane(e1, k - 64);
	v_cmp_lt_u32_e64 s[50:51], s46, v238
	v_cmp_lt_u32_e64 s[52:53], s47, v237
	v_cmp_lt_u32_e64 s[54:55], s47, v238
	v_readlane_b32 s46, v237, 50
	v_readlane_b32 s47, v238, 50
	v_addc_co_u32_e64 v239, s[56:57], 0, v239, s[48:49]
	v_addc_co_u32_e64 v240, s[56:57], 0, v240, s[50:51]
	v_addc_co_u32_e64 v239, s[56:57], 0, v239, s[52:53]
	v_addc_co_u32_e64 v240, s[56:57], 0, v240, s[54:55]
	v_cmp_lt_u32_e64 s[48:49], s46, v237
	v_cmp_lt_u32_e64 s[50:51], s46, v238
	v_cmp_lt_u32_e64 s[52:53], s47, v237
	v_cmp_lt_u32_e64 s[54:55], s47, v238
	v_readlane_b32 s46, v237, 51
	v_readlane_b32 s47, v238, 51
	v_addc_co_u32_e64 v239, s[56:57], 0, v239, s[48:49]
	v_addc_co_u32_e64 v240, s[56:57], 0, v240, s[50:51]
	v_addc_co_u32_e64 v239, s[56:57], 0, v239, s[52:53]
	v_addc_co_u32_e64 v240, s[56:57], 0, v240, s[54:55]
	v_cmp_lt_u32_e64 s[48:49], s46, v237
	v_cmp_lt_u32_e64 s[50:51], s46, v238
	v_cmp_lt_u32_e64 s[52:53], s47, v237
	v_cmp_lt_u32_e64 s[54:55], s47, v238
	v_readlane_b32 s46, v237, 52
	v_readlane_b32 s47, v238, 52
	v_addc_co_u32_e64 v239, s[56:57], 0, v239, s[48:49]
	v_addc_co_u32_e64 v240, s[56:57], 0, v240, s[50:51]
	v_addc_co_u32_e64 v239, s[56:57], 0, v239, s[52:53]
	v_addc_co_u32_e64 v240, s[56:57], 0, v240, s[54:55]
	v_cmp_lt_u32_e64 s[48:49], s46, v237
	v_cmp_lt_u32_e64 s[50:51], s46, v238
	v_cmp_lt_u32_e64 s[52:53], s47, v237
	v_cmp_lt_u32_e64 s[54:55], s47, v238
	v_readlane_b32 s46, v237, 53
	v_readlane_b32 s47, v238, 53
	v_addc_co_u32_e64 v239, s[56:57], 0, v239, s[48:49]
	v_addc_co_u32_e64 v240, s[56:57], 0, v240, s[50:51]
	v_addc_co_u32_e64 v239, s[56:57], 0, v239, s[52:53]
	v_addc_co_u32_e64 v240, s[56:57], 0, v240, s[54:55]
	v_cmp_lt_u32_e64 s[48:49], s46, v237
	v_cmp_lt_u32_e64 s[50:51], s46, v238
	v_cmp_lt_u32_e64 s[52:53], s47, v237
	v_cmp_lt_u32_e64 s[54:55], s47, v238
	v_readlane_b32 s46, v237, 54
	v_readlane_b32 s47, v238, 54
	v_addc_co_u32_e64 v239, s[56:57], 0, v239, s[48:49]
	v_addc_co_u32_e64 v240, s[56:57], 0, v240, s[50:51]
	v_addc_co_u32_e64 v239, s[56:57], 0, v239, s[52:53]
	v_addc_co_u32_e64 v240, s[56:57], 0, v240, s[54:55]
	v_cmp_lt_u32_e64 s[48:49], s46, v237
	v_cmp_lt_u32_e64 s[50:51], s46, v238
	v_cmp_lt_u32_e64 s[52:53], s47, v237
	v_cmp_lt_u32_e64 s[54:55], s47, v238
	v_readlane_b32 s46, v237, 55
	v_readlane_b32 s47, v238, 55
	v_addc_co_u32_e64 v239, s[56:57], 0, v239, s[48:49]
	v_addc_co_u32_e64 v240, s[56:57], 0, v240, s[50:51]
	v_addc_co_u32_e64 v239, s[56:57], 0, v239, s[52:53]
	v_addc_co_u32_e64 v240, s[56:57], 0, v240, s[54:55]
	v_cmp_lt_u32_e64 s[48:49], s46, v237
	v_cmp_lt_u32_e64 s[50:51], s46, v238
	v_cmp_lt_u32_e64 s[52:53], s47, v237
	v_cmp_lt_u32_e64 s[54:55], s47, v238
	v_readlane_b32 s46, v237, 56
	v_readlane_b32 s47, v238, 56
	v_addc_co_u32_e64 v239, s[56:57], 0, v239, s[48:49]
	v_addc_co_u32_e64 v240, s[56:57], 0, v240, s[50:51]
	v_addc_co_u32_e64 v239, s[56:57], 0, v239, s[52:53]
	v_addc_co_u32_e64 v240, s[56:57], 0, v240, s[54:55]
	v_cmp_lt_u32_e64 s[48:49], s46, v237
	v_cmp_lt_u32_e64 s[50:51], s46, v238
	v_cmp_lt_u32_e64 s[52:53], s47, v237
	v_cmp_lt_u32_e64 s[54:55], s47, v238
	v_readlane_b32 s46, v237, 57
	v_readlane_b32 s47, v238, 57
	v_addc_co_u32_e64 v239, s[56:57], 0, v239, s[48:49]
	v_addc_co_u32_e64 v240, s[56:57], 0, v240, s[50:51]
	v_addc_co_u32_e64 v239, s[56:57], 0, v239, s[52:53]
	v_addc_co_u32_e64 v240, s[56:57], 0, v240, s[54:55]
	v_cmp_lt_u32_e64 s[48:49], s46, v237
	v_cmp_lt_u32_e64 s[50:51], s46, v238
	v_cmp_lt_u32_e64 s[52:53], s47, v237
	v_cmp_lt_u32_e64 s[54:55], s47, v238
	v_readlane_b32 s46, v237, 58
	v_readlane_b32 s47, v238, 58
	v_addc_co_u32_e64 v239, s[56:57], 0, v239, s[48:49]
	v_addc_co_u32_e64 v240, s[56:57], 0, v240, s[50:51]
	v_addc_co_u32_e64 v239, s[56:57], 0, v239, s[52:53]
	v_addc_co_u32_e64 v240, s[56:57], 0, v240, s[54:55]
	v_cmp_lt_u32_e64 s[48:49], s46, v237
	v_cmp_lt_u32_e64 s[50:51], s46, v238
	v_cmp_lt_u32_e64 s[52:53], s47, v237
	v_cmp_lt_u32_e64 s[54:55], s47, v238
	v_readlane_b32 s46, v237, 59
	v_readlane_b32 s47, v238, 59
	v_addc_co_u32_e64 v239, s[56:57], 0, v239, s[48:49]
	v_addc_co_u32_e64 v240, s[56:57], 0, v240, s[50:51]
	v_addc_co_u32_e64 v239, s[56:57], 0, v239, s[52:53]
	v_addc_co_u32_e64 v240, s[56:57], 0, v240, s[54:55]
	v_cmp_lt_u32_e64 s[48:49], s46, v237
	v_cmp_lt_u32_e64 s[50:51], s46, v238
	v_cmp_lt_u32_e64 s[52:53], s47, v237
	v_cmp_lt_u32_e64 s[54:55], s47, v238
	v_readlane_b32 s46, v237, 60
	v_readlane_b32 s47, v238, 60
	v_addc_co_u32_e64 v239, s[56:57], 0, v239, s[48:49]
	v_addc_co_u32_e64 v240, s[56:57], 0, v240, s[50:51]
	v_addc_co_u32_e64 v239, s[56:57], 0, v239, s[52:53]
	v_addc_co_u32_e64 v240, s[56:57], 0, v240, s[54:55]
	v_cmp_lt_u32_e64 s[48:49], s46, v237
	v_cmp_lt_u32_e64 s[50:51], s46, v238
	v_cmp_lt_u32_e64 s[52:53], s47, v237
	v_cmp_lt_u32_e64 s[54:55], s47, v238
	v_readlane_b32 s46, v237, 61
	v_readlane_b32 s47, v238, 61
	v_addc_co_u32_e64 v239, s[56:57], 0, v239, s[48:49]
	v_addc_co_u32_e64 v240, s[56:57], 0, v240, s[50:51]
	v_addc_co_u32_e64 v239, s[56:57], 0, v239, s[52:53]
	v_addc_co_u32_e64 v240, s[56:57], 0, v240, s[54:55]
	v_cmp_lt_u32_e64 s[48:49], s46, v237
	v_cmp_lt_u32_e64 s[50:51], s46, v238
	v_cmp_lt_u32_e64 s[52:53], s47, v237
	v_cmp_lt_u32_e64 s[54:55], s47, v238
	v_readlane_b32 s46, v237, 62
	v_readlane_b32 s47, v238, 62
	v_addc_co_u32_e64 v239, s[56:57], 0, v239, s[48:49]
	v_addc_co_u32_e64 v240, s[56:57], 0, v240, s[50:51]
	v_addc_co_u32_e64 v239, s[56:57], 0, v239, s[52:53]
	v_addc_co_u32_e64 v240, s[56:57], 0, v240, s[54:55]
	v_cmp_lt_u32_e64 s[48:49], s46, v237
	v_cmp_lt_u32_e64 s[50:51], s46, v238
	v_cmp_lt_u32_e64 s[52:53], s47, v237
	v_cmp_lt_u32_e64 s[54:55], s47, v238
	v_readlane_b32 s46, v237, 63
	v_readlane_b32 s47, v238, 63
	v_addc_co_u32_e64 v239, s[56:57], 0, v239, s[48:49]
	v_addc_co_u32_e64 v240, s[56:57], 0, v240, s[50:51]
	v_addc_co_u32_e64 v239, s[56:57], 0, v239, s[52:53]
	v_addc_co_u32_e64 v240, s[56:57], 0, v240, s[54:55]
	v_cmp_lt_u32_e64 s[48:49], s46, v237
	v_cmp_lt_u32_e64 s[50:51], s46, v238
	v_cmp_lt_u32_e64 s[52:53], s47, v237
	v_cmp_lt_u32_e64 s[54:55], s47, v238
	s_nop 1
	v_addc_co_u32_e64 v239, s[56:57], 0, v239, s[48:49]
	v_addc_co_u32_e64 v240, s[56:57], 0, v240, s[50:51]
	v_addc_co_u32_e64 v239, s[56:57], 0, v239, s[52:53]
	v_addc_co_u32_e64 v240, s[56:57], 0, v240, s[54:55]
	v_xor_b32_e32 v239, s19, v239
	v_xor_b32_e32 v240, s19, v240
	s_xor_b32 s19, s19, 0x7f
	v_and_b32_e32 v237, 0xfffffc00, v241
	v_lshl_add_u32 v239, v239, 2, v237
	v_lshl_add_u32 v240, v240, 2, v237
	ds_write_b32 v239, v216
	ds_write_b32 v240, v217
	ds_write_b32 v239, v218 offset:512
	ds_write_b32 v240, v219 offset:512
	s_waitcnt lgkmcnt(0)
; DEV void peer_gather_token(const Params& p, int tok) {
;     ...
;     for (int s = 0; s < 4; ++s) {
;       const int k = k4 + s;
;       if (k + 3 < 128) issue(k + 3, (s + 3) & 3);
;       const v6u dq = v6u{dn[s][0][0], dn[s][0][1], dn[s][1][0], dn[s][1][1], dn[s][2][0], dn[s][2][1]};
;       const v32f dv = __builtin_amdgcn_cvt_scalef32_pk32_f32_fp6(dq, 1.0f);
;       float d0 = 0.f, d1 = 0.f, d2 = 0.f, d3 = 0.f;
; #pragma unroll
;       for (int i = 0; i < 8; ++i) { d0 += dv[4 * i] * hx[4 * i]; d1 += dv[4 * i + 1] * hx[4 * i + 1]; d2 += dv[4 * i + 2] * hx[4 * i + 2]; d3 += dv[4 * i + 3] * hx[4 * i + 3]; }
;       const float d = wave_sum_fast((d0 + d1) + (d2 + d3)) * (1.f / DOWN_SCALE);
;       const float gk = __builtin_bit_cast(float, (k < 64) ? __builtin_amdgcn_readlane(g0, k) : __builtin_amdgcn_readlane(g1, k - 64));
	ds_read_b32 v216, v241
	ds_read_b32 v217, v241 offset:256
	ds_read_b32 v218, v241 offset:512
	ds_read_b32 v219, v241 offset:768
	s_waitcnt lgkmcnt(0)
	v_cvt_scalef32_pk32_f32_fp6 v[2:33], v[98:103], 1.0
	v_mul_f32_e32 v200, v2, v34
	v_mul_f32_e32 v201, v3, v35
	v_mul_f32_e32 v202, v4, v36
	v_mul_f32_e32 v203, v5, v37
	v_fmac_f32_e32 v200, v6, v38
	v_fmac_f32_e32 v201, v7, v39
	v_fmac_f32_e32 v202, v8, v40
	v_fmac_f32_e32 v203, v9, v41
	v_fmac_f32_e32 v200, v10, v42
	v_fmac_f32_e32 v201, v11, v43
	v_fmac_f32_e32 v202, v12, v44
	v_fmac_f32_e32 v203, v13, v45
	v_fmac_f32_e32 v200, v14, v46
	v_fmac_f32_e32 v201, v15, v47
	v_fmac_f32_e32 v202, v16, v48
	v_fmac_f32_e32 v203, v17, v49
	v_fmac_f32_e32 v200, v18, v50
	v_fmac_f32_e32 v201, v19, v51
	v_fmac_f32_e32 v202, v20, v52
	v_fmac_f32_e32 v203, v21, v53
	v_fmac_f32_e32 v200, v22, v54
	v_fmac_f32_e32 v201, v23, v55
	v_fmac_f32_e32 v202, v24, v56
	v_fmac_f32_e32 v203, v25, v57
	v_fmac_f32_e32 v200, v26, v58
	v_fmac_f32_e32 v201, v27, v59
	v_fmac_f32_e32 v202, v28, v60
	v_fmac_f32_e32 v203, v29, v61
	v_fmac_f32_e32 v200, v30, v62
	v_fmac_f32_e32 v201, v31, v63
	v_fmac_f32_e32 v202, v32, v64
	v_fmac_f32_e32 v203, v33, v65
	v_add_f32_e32 v200, v201, v200
	v_add_f32_e32 v202, v203, v202
	v_cvt_scalef32_pk32_f32_fp6 v[2:33], v[104:109], 1.0
	v_add_f32_e32 v200, v202, v200
	s_add_i32 s38, s24, 0
	v_readlane_b32 s26, v199, s38
	s_mov_b32 s39, 0
	v_readlane_b32 s25, v216, s39
	v_add_f32_dpp v200, v200, v200 quad_perm:[1,0,3,2] row_mask:0xf bank_mask:0xf bound_ctrl:1
	s_nop 1
	v_add_f32_dpp v200, v200, v200 quad_perm:[2,3,0,1] row_mask:0xf bank_mask:0xf bound_ctrl:1
	s_nop 1
	v_add_f32_dpp v200, v200, v200 row_half_mirror row_mask:0xf bank_mask:0xf bound_ctrl:1
	s_nop 1
	v_add_f32_dpp v200, v200, v200 row_mirror row_mask:0xf bank_mask:0xf bound_ctrl:1
	s_nop 1
	v_add_f32_dpp v200, v200, v200 row_bcast:15 row_mask:0xa bank_mask:0xf
	s_nop 1
	v_add_f32_dpp v200, v200, v200 row_bcast:31 row_mask:0xc bank_mask:0xf
	s_nop 0
	v_readlane_b32 s27, v200, 63
	s_mul_i32 s40, s25, 0xc00
	s_add_u32 s28, s62, s40
	s_addc_u32 s29, s63, 0
	global_load_dwordx4 v[98:101], v1, s[28:29]
	global_load_dwordx4 v[102:105], v1, s[28:29] offset:2048
	global_load_dwordx4 v[106:109], v1, s[28:29] offset:1024
	v_mul_f32_e32 v204, s27, v212
	v_mul_f32_e32 v205, 0x3f3504f3, v204
	v_cmp_lt_f32_e64 s[32:33], |v205|, 1.0
	s_and_b64 vcc, exec, s[32:33]
	s_cbranch_vccnz .Lsm_33
	v_fma_f32 v208, |v205|, s9, v214
	v_fma_f32 v208, |v205|, v208, s10
	v_fma_f32 v208, |v205|, v208, s11
	v_fma_f32 v208, |v205|, v208, s12
	v_fma_f32 v208, |v205|, v208, s13
	v_fma_f32 v208, |v205|, v208, s14
	v_fma_f32 v208, |v205|, v208, |v205|
	v_mul_f32_e32 v209, 0xbfb8aa3b, v208
	v_fma_f32 v210, v208, s15, -v209
	v_rndne_f32_e32 v211, v209
	v_fmac_f32_e32 v210, 0xb2a5705f, v208
	v_sub_f32_e32 v209, v209, v211
	v_add_f32_e32 v209, v209, v210
	v_cvt_i32_f32_e32 v210, v211
	v_exp_f32_e32 v209, v209
	v_cmp_nlt_f32_e32 vcc, s16, v208
	v_ldexp_f32 v209, v209, v210
	s_nop 0
	v_cndmask_b32_e32 v209, 0, v209, vcc
	v_cmp_ngt_f32_e32 vcc, s17, v208
	s_nop 1
	v_cndmask_b32_e32 v208, v215, v209, vcc
	v_sub_f32_e32 v210, 1.0, v208
	s_branch .Ljn_33
